# combo4: combo3 + next-tile pointer select block and kstep base copies moved from the P1/P3 read slots into the P2 read slot
# baseline (speedup 1.0000x reference)
; #define PG8_STAGE(bufoff, gbase, voff) do { _Pragma("unroll") for (int _i = 0; _i < 2; ++_i) \
;     __builtin_amdgcn_global_load_lds((const unsigned*)((const char*)(gbase) + (voff)[_i]), (LAS unsigned*)(lds + (bufoff) + ldsw + _i * 8192), 16, 0, 0); } while (0)
; #define PG8_LDA(dst, b, h) do { _Pragma("unroll") for (int m = 0; m < 4; ++m) _Pragma("unroll") for (int k = 0; k < 2; ++k) dst[m][k] = *(const LAS bf16x8*)(lds + PG8_SA(b, h) + aoff + m * 2048 + k * 1024); } while (0)
; #define PG8_LDB(dst, b, h) do { _Pragma("unroll") for (int n = 0; n < 2; ++n) _Pragma("unroll") for (int k = 0; k < 2; ++k) dst[n][k] = *(const LAS bf16x8*)(lds + PG8_SB(b, h) + boff + n * 2048 + k * 1024); } while (0)
; #define PG8_MMA(ai, bj, At, Bt) do { __builtin_amdgcn_s_setprio(1); _Pragma("unroll") for (int m = 0; m < 4; ++m) _Pragma("unroll") for (int n = 0; n < 2; ++n) _Pragma("unroll") for (int k = 0; k < 2; ++k) \
;     acc[ai][bj][m][n] = __builtin_amdgcn_mfma_f32_16x16x32_bf16(Bt[n][k], At[m][k], acc[ai][bj][m][n], 0, 0, 0); __builtin_amdgcn_s_setprio(0); } while (0)
; #define PG8_WAIT_V(n) asm volatile("s_waitcnt vmcnt(" #n ")" ::: "memory")
; template <class Epi, class Sched = StaticOrder>
; DI void gemm_phase(LAS unsigned char* lds, const Gemm g, const Sched& S, const Epi& E) {
;     ...
;     for (int t = 0; t < nt; t += 2) {
;       const bool last = (t == nt - 2);
;       const char* a1 = cA + (size_t)(t + 1) * kstep;
;       const char* a2 = last ? nA : cA + (size_t)(t + 2) * kstep; const char* b2 = last ? nB : cB + (size_t)(t + 2) * kstep;
;       const char* a3 = a2 + kstep; const char* b3 = b2 + kstep;
;       PG8_LDB(B0, 0, 0); PG8_SCHED; PG8_LDA(At, 0, 0); PG8_STAGE(PG8_SA(1, 1), a1 + hstep, voffA);
;       PG8_WAIT_L(8); PG8_BAR; PG8_WAIT_L(0); PG8_MMA(0, 0, At, B0); PG8_BAR; PG8_SCHED;
;       PG8_LDB(B1, 0, 1); PG8_STAGE(PG8_SB(0, 0), b2, voffB);
;       PG8_BAR; PG8_WAIT_L(0); PG8_MMA(0, 1, At, B1); PG8_BAR;
;       PG8_LDA(At, 0, 1); PG8_STAGE(PG8_SA(0, 0), a2, voffA);
;       PG8_BAR; PG8_WAIT_L(0); PG8_MMA(1, 0, At, B0); PG8_BAR; PG8_SCHED;
;       PG8_STAGE(PG8_SB(0, 1), b2 + hstep, voffB);
;       PG8_WAIT_V(6); PG8_BAR; PG8_MMA(1, 1, At, B1); PG8_BAR;
;       PG8_LDB(B0, 1, 0); PG8_SCHED; PG8_LDA(At, 1, 0); PG8_STAGE(PG8_SA(0, 1), a2 + hstep, voffA);
;       PG8_WAIT_L(8); PG8_BAR; PG8_WAIT_L(0); PG8_MMA(0, 0, At, B0); PG8_BAR; PG8_SCHED;
.LBB0_346:
	s_add_i32 m0, s48, 0xc000
	ds_read_b128 v[162:165], v174
	ds_read_b128 v[166:169], v174 offset:1024
	ds_read_b128 v[178:181], v174 offset:2048
	ds_read_b128 v[182:185], v174 offset:3072
	ds_read_b128 v[186:189], v174 offset:4096
	ds_read_b128 v[190:193], v174 offset:5120
	ds_read_b128 v[194:197], v174 offset:6144
	ds_read_b128 v[198:201], v174 offset:7168
	global_load_lds_dwordx4 v146, s[6:7]
	s_add_i32 m0, s48, 0xe000
	s_nop 0
	global_load_lds_dwordx4 v148, s[6:7]
	s_waitcnt lgkmcnt(0)
	s_setprio 1
	s_barrier
	v_mfma_f32_16x16x32_bf16 v[124:127], v[128:131], v[162:165], v[124:127]
	v_mfma_f32_16x16x32_bf16 v[120:123], v[154:157], v[162:165], v[120:123]
	v_mfma_f32_16x16x32_bf16 v[108:111], v[128:131], v[178:181], v[108:111]
	v_mfma_f32_16x16x32_bf16 v[104:107], v[154:157], v[178:181], v[104:107]
	v_mfma_f32_16x16x32_bf16 v[100:103], v[128:131], v[186:189], v[100:103]
	v_mfma_f32_16x16x32_bf16 v[92:95], v[154:157], v[186:189], v[92:95]
	v_mfma_f32_16x16x32_bf16 v[84:87], v[128:131], v[194:197], v[84:87]
	v_mfma_f32_16x16x32_bf16 v[76:79], v[154:157], v[194:197], v[76:79]
	v_mfma_f32_16x16x32_bf16 v[124:127], v[132:135], v[166:169], v[124:127]
	v_mfma_f32_16x16x32_bf16 v[120:123], v[158:161], v[166:169], v[120:123]
	v_mfma_f32_16x16x32_bf16 v[108:111], v[132:135], v[182:185], v[108:111]
	v_mfma_f32_16x16x32_bf16 v[104:107], v[158:161], v[182:185], v[104:107]
	v_mfma_f32_16x16x32_bf16 v[100:103], v[132:135], v[190:193], v[100:103]
	v_mfma_f32_16x16x32_bf16 v[92:95], v[158:161], v[190:193], v[92:95]
	v_mfma_f32_16x16x32_bf16 v[84:87], v[132:135], v[198:201], v[84:87]
	v_mfma_f32_16x16x32_bf16 v[76:79], v[158:161], v[198:201], v[76:79]
	s_barrier
	s_setprio 0
	ds_read_b128 v[202:205], v175
	ds_read_b128 v[206:209], v175 offset:1024
	ds_read_b128 v[212:215], v175 offset:2048
	ds_read_b128 v[216:219], v175 offset:3072
	s_add_u32 s8, s6, 0xfff80080
	s_addc_u32 s9, s7, -1
	s_cmp_eq_u32 s52, 28
	s_cselect_b32 s11, s31, s9
	s_cselect_b32 s10, s42, s8
	s_cselect_b32 s9, s29, s45
	s_cselect_b32 s8, s43, s44
	s_add_i32 s53, s65, s41
	s_add_u32 s98, s8, 0x80
	s_addc_u32 s99, s9, 0
	s_add_u32 s100, s10, 0x80
	s_addc_u32 s101, s11, 0
	s_mov_b32 m0, s53
	s_nop 0
	global_load_lds_dwordx4 v140, s[8:9]
	s_add_i32 m0, s53, 0x2000
	s_nop 0
	global_load_lds_dwordx4 v136, s[8:9]
	s_waitcnt lgkmcnt(0)
	s_setprio 1
	s_barrier
	v_mfma_f32_16x16x32_bf16 v[116:119], v[202:205], v[162:165], v[116:119]
	v_mfma_f32_16x16x32_bf16 v[112:115], v[212:215], v[162:165], v[112:115]
	v_mfma_f32_16x16x32_bf16 v[96:99], v[202:205], v[178:181], v[96:99]
	v_mfma_f32_16x16x32_bf16 v[88:91], v[212:215], v[178:181], v[88:91]
	v_mfma_f32_16x16x32_bf16 v[80:83], v[202:205], v[186:189], v[80:83]
	v_mfma_f32_16x16x32_bf16 v[72:75], v[212:215], v[186:189], v[72:75]
	v_mfma_f32_16x16x32_bf16 v[68:71], v[202:205], v[194:197], v[68:71]
	v_mfma_f32_16x16x32_bf16 v[64:67], v[212:215], v[194:197], v[64:67]
	v_mfma_f32_16x16x32_bf16 v[116:119], v[206:209], v[166:169], v[116:119]
	v_mfma_f32_16x16x32_bf16 v[112:115], v[216:219], v[166:169], v[112:115]
	v_mfma_f32_16x16x32_bf16 v[96:99], v[206:209], v[182:185], v[96:99]
	v_mfma_f32_16x16x32_bf16 v[88:91], v[216:219], v[182:185], v[88:91]
	v_mfma_f32_16x16x32_bf16 v[80:83], v[206:209], v[190:193], v[80:83]
	v_mfma_f32_16x16x32_bf16 v[72:75], v[216:219], v[190:193], v[72:75]
	v_mfma_f32_16x16x32_bf16 v[68:71], v[206:209], v[198:201], v[68:71]
	v_mfma_f32_16x16x32_bf16 v[64:67], v[216:219], v[198:201], v[64:67]
	s_barrier
	s_setprio 0
	s_mov_b32 m0, s48
	ds_read_b128 v[162:165], v174 offset:16384
	ds_read_b128 v[166:169], v174 offset:17408
	ds_read_b128 v[178:181], v174 offset:18432
	ds_read_b128 v[182:185], v174 offset:19456
	ds_read_b128 v[186:189], v174 offset:20480
	ds_read_b128 v[190:193], v174 offset:21504
	ds_read_b128 v[194:197], v174 offset:22528
	ds_read_b128 v[198:201], v174 offset:23552
	global_load_lds_dwordx4 v142, s[10:11]
	s_mov_b32 m0, s49
	s_nop 0
	global_load_lds_dwordx4 v138, s[10:11]
	s_waitcnt vmcnt(10)
	s_waitcnt lgkmcnt(0)
	s_setprio 1
	s_barrier
	v_mfma_f32_16x16x32_bf16 v[60:63], v[128:131], v[162:165], v[60:63]
	v_mfma_f32_16x16x32_bf16 v[56:59], v[154:157], v[162:165], v[56:59]
	v_mfma_f32_16x16x32_bf16 v[52:55], v[128:131], v[178:181], v[52:55]
	v_mfma_f32_16x16x32_bf16 v[44:47], v[154:157], v[178:181], v[44:47]
	v_mfma_f32_16x16x32_bf16 v[36:39], v[128:131], v[186:189], v[36:39]
	v_mfma_f32_16x16x32_bf16 v[28:31], v[154:157], v[186:189], v[28:31]
	v_mfma_f32_16x16x32_bf16 v[20:23], v[128:131], v[194:197], v[20:23]
	v_mfma_f32_16x16x32_bf16 v[12:15], v[154:157], v[194:197], v[12:15]
	v_mfma_f32_16x16x32_bf16 v[60:63], v[132:135], v[166:169], v[60:63]
	v_mfma_f32_16x16x32_bf16 v[56:59], v[158:161], v[166:169], v[56:59]
	v_mfma_f32_16x16x32_bf16 v[52:55], v[132:135], v[182:185], v[52:55]
	v_mfma_f32_16x16x32_bf16 v[44:47], v[158:161], v[182:185], v[44:47]
	v_mfma_f32_16x16x32_bf16 v[36:39], v[132:135], v[190:193], v[36:39]
	v_mfma_f32_16x16x32_bf16 v[28:31], v[158:161], v[190:193], v[28:31]
	v_mfma_f32_16x16x32_bf16 v[20:23], v[132:135], v[198:201], v[20:23]
	v_mfma_f32_16x16x32_bf16 v[12:15], v[158:161], v[198:201], v[12:15]
	s_barrier
	s_setprio 0
	s_add_u32 s54, s8, 0x80000
	s_addc_u32 s55, s9, 0
	s_add_i32 s53, s72, s41
	s_mov_b32 m0, s53
	s_nop 0
	global_load_lds_dwordx4 v140, s[54:55]
	s_add_i32 m0, s53, 0x2000
	s_nop 0
	global_load_lds_dwordx4 v136, s[54:55]
	s_add_i32 s53, 0, 0x18000
	v_add_u32_e32 v158, s53, v171
	ds_read_b128 v[128:131], v158
	ds_read_b128 v[132:135], v158 offset:1024
	ds_read_b128 v[154:157], v158 offset:2048
	ds_read_b128 v[158:161], v158 offset:3072
	s_waitcnt vmcnt(6)
	s_setprio 1
	s_barrier
; #define PG8_STAGE(bufoff, gbase, voff) do { _Pragma("unroll") for (int _i = 0; _i < 2; ++_i) \
;     __builtin_amdgcn_global_load_lds((const unsigned*)((const char*)(gbase) + (voff)[_i]), (LAS unsigned*)(lds + (bufoff) + ldsw + _i * 8192), 16, 0, 0); } while (0)
; #define PG8_LDA(dst, b, h) do { _Pragma("unroll") for (int m = 0; m < 4; ++m) _Pragma("unroll") for (int k = 0; k < 2; ++k) dst[m][k] = *(const LAS bf16x8*)(lds + PG8_SA(b, h) + aoff + m * 2048 + k * 1024); } while (0)
; #define PG8_LDB(dst, b, h) do { _Pragma("unroll") for (int n = 0; n < 2; ++n) _Pragma("unroll") for (int k = 0; k < 2; ++k) dst[n][k] = *(const LAS bf16x8*)(lds + PG8_SB(b, h) + boff + n * 2048 + k * 1024); } while (0)
; #define PG8_MMA(ai, bj, At, Bt) do { __builtin_amdgcn_s_setprio(1); _Pragma("unroll") for (int m = 0; m < 4; ++m) _Pragma("unroll") for (int n = 0; n < 2; ++n) _Pragma("unroll") for (int k = 0; k < 2; ++k) \
;     acc[ai][bj][m][n] = __builtin_amdgcn_mfma_f32_16x16x32_bf16(Bt[n][k], At[m][k], acc[ai][bj][m][n], 0, 0, 0); __builtin_amdgcn_s_setprio(0); } while (0)
; #define PG8_WAIT_V(n) asm volatile("s_waitcnt vmcnt(" #n ")" ::: "memory")
; #define PG8_WAIT_L(n) asm volatile("s_waitcnt lgkmcnt(" #n ")" ::: "memory")
; #define PG8_BAR __builtin_amdgcn_s_barrier()
; #define PG8_SCHED __builtin_amdgcn_sched_barrier(0)
; template <class Epi, class Sched = StaticOrder>
; DI void gemm_phase(LAS unsigned char* lds, const Gemm g, const Sched& S, const Epi& E) {
;     ...
;       PG8_BAR; PG8_WAIT_L(0); PG8_MMA(1, 0, At, B0); PG8_BAR; PG8_SCHED;
;       PG8_STAGE(PG8_SB(0, 1), b2 + hstep, voffB);
;       PG8_WAIT_V(6); PG8_BAR; PG8_MMA(1, 1, At, B1); PG8_BAR;
;       PG8_LDB(B0, 1, 0); PG8_SCHED; PG8_LDA(At, 1, 0); PG8_STAGE(PG8_SA(0, 1), a2 + hstep, voffA);
;       PG8_WAIT_L(8); PG8_BAR; PG8_WAIT_L(0); PG8_MMA(0, 0, At, B0); PG8_BAR; PG8_SCHED;
;       PG8_LDB(B1, 1, 1); PG8_STAGE(PG8_SB(1, 0), b3, voffB);
;       PG8_BAR; PG8_WAIT_L(0); PG8_MMA(0, 1, At, B1); PG8_BAR;
;       PG8_LDA(At, 1, 1); PG8_STAGE(PG8_SA(1, 0), a3, voffA);
;       PG8_BAR; PG8_WAIT_L(0); PG8_MMA(1, 0, At, B0); PG8_BAR; PG8_SCHED;
	v_mfma_f32_16x16x32_bf16 v[48:51], v[202:205], v[162:165], v[48:51]
	v_mfma_f32_16x16x32_bf16 v[40:43], v[212:215], v[162:165], v[40:43]
	v_mfma_f32_16x16x32_bf16 v[32:35], v[202:205], v[178:181], v[32:35]
	v_mfma_f32_16x16x32_bf16 v[24:27], v[212:215], v[178:181], v[24:27]
	v_mfma_f32_16x16x32_bf16 v[16:19], v[202:205], v[186:189], v[16:19]
	v_mfma_f32_16x16x32_bf16 v[8:11], v[212:215], v[186:189], v[8:11]
	v_mfma_f32_16x16x32_bf16 v[4:7], v[202:205], v[194:197], v[4:7]
	v_mfma_f32_16x16x32_bf16 v[0:3], v[212:215], v[194:197], v[0:3]
	v_mfma_f32_16x16x32_bf16 v[48:51], v[206:209], v[166:169], v[48:51]
	v_mfma_f32_16x16x32_bf16 v[40:43], v[216:219], v[166:169], v[40:43]
	v_mfma_f32_16x16x32_bf16 v[32:35], v[206:209], v[182:185], v[32:35]
	v_mfma_f32_16x16x32_bf16 v[24:27], v[216:219], v[182:185], v[24:27]
	v_mfma_f32_16x16x32_bf16 v[16:19], v[206:209], v[190:193], v[16:19]
	v_mfma_f32_16x16x32_bf16 v[8:11], v[216:219], v[190:193], v[8:11]
	v_mfma_f32_16x16x32_bf16 v[4:7], v[206:209], v[198:201], v[4:7]
	v_mfma_f32_16x16x32_bf16 v[0:3], v[216:219], v[198:201], v[0:3]
	s_barrier
	s_setprio 0
	s_add_u32 s10, s10, 0x80000
	s_addc_u32 s11, s11, 0
	s_mov_b32 m0, s50
	ds_read_b128 v[162:165], v174 offset:32768
	ds_read_b128 v[166:169], v174 offset:33792
	ds_read_b128 v[178:181], v174 offset:34816
	ds_read_b128 v[182:185], v174 offset:35840
	ds_read_b128 v[186:189], v174 offset:36864
	ds_read_b128 v[190:193], v174 offset:37888
	ds_read_b128 v[194:197], v174 offset:38912
	ds_read_b128 v[198:201], v174 offset:39936
	global_load_lds_dwordx4 v142, s[10:11]
	s_mov_b32 m0, s51
	s_nop 0
	global_load_lds_dwordx4 v138, s[10:11]
	s_waitcnt lgkmcnt(0)
	s_setprio 1
	s_barrier
	v_mfma_f32_16x16x32_bf16 v[124:127], v[128:131], v[162:165], v[124:127]
	v_mfma_f32_16x16x32_bf16 v[120:123], v[154:157], v[162:165], v[120:123]
	v_mfma_f32_16x16x32_bf16 v[108:111], v[128:131], v[178:181], v[108:111]
	v_mfma_f32_16x16x32_bf16 v[104:107], v[154:157], v[178:181], v[104:107]
	v_mfma_f32_16x16x32_bf16 v[100:103], v[128:131], v[186:189], v[100:103]
	v_mfma_f32_16x16x32_bf16 v[92:95], v[154:157], v[186:189], v[92:95]
	v_mfma_f32_16x16x32_bf16 v[84:87], v[128:131], v[194:197], v[84:87]
	v_mfma_f32_16x16x32_bf16 v[76:79], v[154:157], v[194:197], v[76:79]
	v_mfma_f32_16x16x32_bf16 v[124:127], v[132:135], v[166:169], v[124:127]
	v_mfma_f32_16x16x32_bf16 v[120:123], v[158:161], v[166:169], v[120:123]
	v_mfma_f32_16x16x32_bf16 v[108:111], v[132:135], v[182:185], v[108:111]
	v_mfma_f32_16x16x32_bf16 v[104:107], v[158:161], v[182:185], v[104:107]
	v_mfma_f32_16x16x32_bf16 v[100:103], v[132:135], v[190:193], v[100:103]
	v_mfma_f32_16x16x32_bf16 v[92:95], v[158:161], v[190:193], v[92:95]
	v_mfma_f32_16x16x32_bf16 v[84:87], v[132:135], v[198:201], v[84:87]
	v_mfma_f32_16x16x32_bf16 v[76:79], v[158:161], v[198:201], v[76:79]
	s_barrier
	s_setprio 0
	s_add_i32 s10, 0, 0x1c000
	s_add_i32 s11, s53, s41
	v_add_u32_e32 v177, s10, v171
	s_mov_b32 m0, s11
	ds_read_b128 v[202:205], v177
	ds_read_b128 v[206:209], v177 offset:1024
	ds_read_b128 v[212:215], v177 offset:2048
	ds_read_b128 v[216:219], v177 offset:3072
	global_load_lds_dwordx4 v140, s[98:99]
	s_add_i32 m0, s11, 0x2000
	s_nop 0
	global_load_lds_dwordx4 v136, s[98:99]
	s_waitcnt lgkmcnt(0)
	s_setprio 1
	s_barrier
	v_mfma_f32_16x16x32_bf16 v[116:119], v[202:205], v[162:165], v[116:119]
	v_mfma_f32_16x16x32_bf16 v[112:115], v[212:215], v[162:165], v[112:115]
	v_mfma_f32_16x16x32_bf16 v[96:99], v[202:205], v[178:181], v[96:99]
	v_mfma_f32_16x16x32_bf16 v[88:91], v[212:215], v[178:181], v[88:91]
	v_mfma_f32_16x16x32_bf16 v[80:83], v[202:205], v[186:189], v[80:83]
	v_mfma_f32_16x16x32_bf16 v[72:75], v[212:215], v[186:189], v[72:75]
	v_mfma_f32_16x16x32_bf16 v[68:71], v[202:205], v[194:197], v[68:71]
	v_mfma_f32_16x16x32_bf16 v[64:67], v[212:215], v[194:197], v[64:67]
	v_mfma_f32_16x16x32_bf16 v[116:119], v[206:209], v[166:169], v[116:119]
	v_mfma_f32_16x16x32_bf16 v[112:115], v[216:219], v[166:169], v[112:115]
	v_mfma_f32_16x16x32_bf16 v[96:99], v[206:209], v[182:185], v[96:99]
	v_mfma_f32_16x16x32_bf16 v[88:91], v[216:219], v[182:185], v[88:91]
	v_mfma_f32_16x16x32_bf16 v[80:83], v[206:209], v[190:193], v[80:83]
	v_mfma_f32_16x16x32_bf16 v[72:75], v[216:219], v[190:193], v[72:75]
	v_mfma_f32_16x16x32_bf16 v[68:71], v[206:209], v[198:201], v[68:71]
	v_mfma_f32_16x16x32_bf16 v[64:67], v[216:219], v[198:201], v[64:67]
	s_barrier
	s_setprio 0
	s_mov_b32 m0, s56
	ds_read_b128 v[162:165], v174 offset:49152
	ds_read_b128 v[166:169], v174 offset:50176
	ds_read_b128 v[178:181], v174 offset:51200
	ds_read_b128 v[182:185], v174 offset:52224
	ds_read_b128 v[186:189], v174 offset:53248
	ds_read_b128 v[190:193], v174 offset:54272
	ds_read_b128 v[194:197], v174 offset:55296
	ds_read_b128 v[198:201], v174 offset:56320
	global_load_lds_dwordx4 v142, s[100:101]
	s_mov_b32 m0, s57
	s_nop 0
	global_load_lds_dwordx4 v138, s[100:101]
	s_waitcnt vmcnt(10)
	s_waitcnt lgkmcnt(0)
	s_setprio 1
	s_barrier
	v_mfma_f32_16x16x32_bf16 v[60:63], v[128:131], v[162:165], v[60:63]
	v_mfma_f32_16x16x32_bf16 v[56:59], v[154:157], v[162:165], v[56:59]
	v_mfma_f32_16x16x32_bf16 v[52:55], v[128:131], v[178:181], v[52:55]
	v_mfma_f32_16x16x32_bf16 v[44:47], v[154:157], v[178:181], v[44:47]
	v_mfma_f32_16x16x32_bf16 v[36:39], v[128:131], v[186:189], v[36:39]
	v_mfma_f32_16x16x32_bf16 v[28:31], v[154:157], v[186:189], v[28:31]
	v_mfma_f32_16x16x32_bf16 v[20:23], v[128:131], v[194:197], v[20:23]
	v_mfma_f32_16x16x32_bf16 v[12:15], v[154:157], v[194:197], v[12:15]
	v_mfma_f32_16x16x32_bf16 v[60:63], v[132:135], v[166:169], v[60:63]
	v_mfma_f32_16x16x32_bf16 v[56:59], v[158:161], v[166:169], v[56:59]
	v_mfma_f32_16x16x32_bf16 v[52:55], v[132:135], v[182:185], v[52:55]
	v_mfma_f32_16x16x32_bf16 v[44:47], v[158:161], v[182:185], v[44:47]
	v_mfma_f32_16x16x32_bf16 v[36:39], v[132:135], v[190:193], v[36:39]
	v_mfma_f32_16x16x32_bf16 v[28:31], v[158:161], v[190:193], v[28:31]
	v_mfma_f32_16x16x32_bf16 v[20:23], v[132:135], v[198:201], v[20:23]
	v_mfma_f32_16x16x32_bf16 v[12:15], v[158:161], v[198:201], v[12:15]
	s_barrier
; #define PG8_STAGE(bufoff, gbase, voff) do { _Pragma("unroll") for (int _i = 0; _i < 2; ++_i) \
;     __builtin_amdgcn_global_load_lds((const unsigned*)((const char*)(gbase) + (voff)[_i]), (LAS unsigned*)(lds + (bufoff) + ldsw + _i * 8192), 16, 0, 0); } while (0)
; #define PG8_MMA(ai, bj, At, Bt) do { __builtin_amdgcn_s_setprio(1); _Pragma("unroll") for (int m = 0; m < 4; ++m) _Pragma("unroll") for (int n = 0; n < 2; ++n) _Pragma("unroll") for (int k = 0; k < 2; ++k) \
;     acc[ai][bj][m][n] = __builtin_amdgcn_mfma_f32_16x16x32_bf16(Bt[n][k], At[m][k], acc[ai][bj][m][n], 0, 0, 0); __builtin_amdgcn_s_setprio(0); } while (0)
; #define PG8_WAIT_V(n) asm volatile("s_waitcnt vmcnt(" #n ")" ::: "memory")
; #define PG8_WAIT_L(n) asm volatile("s_waitcnt lgkmcnt(" #n ")" ::: "memory")
; #define PG8_BAR __builtin_amdgcn_s_barrier()
; #define PG8_SCHED __builtin_amdgcn_sched_barrier(0)
; DI float row_rstd(const float* ssq, int row, int fq) {
;   const f32x4 a = *(const f32x4*)(ssq + (size_t)row * 32 + fq * 8), b = *(const f32x4*)(ssq + (size_t)row * 32 + fq * 8 + 4);
;   float sm = ((a[0] + a[1]) + (a[2] + a[3])) + ((b[0] + b[1]) + (b[2] + b[3]));
;   sm += __shfl_xor(sm, 16); sm += __shfl_xor(sm, 32);
;   return rsqrtf(sm * (1.0f / 2048.f) + 1e-6f);
; }
; template <class Epi, class Sched = StaticOrder>
; DI void gemm_phase(LAS unsigned char* lds, const Gemm g, const Sched& S, const Epi& E) {
;     ...
;       PG8_BAR; PG8_WAIT_L(0); PG8_MMA(1, 0, At, B0); PG8_BAR; PG8_SCHED;
;       PG8_STAGE(PG8_SB(1, 1), b3 + hstep, voffB);
;       PG8_WAIT_V(6); PG8_BAR; PG8_MMA(1, 1, At, B1); PG8_BAR;
;     }
	s_setprio 0
	s_add_u32 s8, s8, 0x80080
	s_addc_u32 s9, s9, 0
	s_add_i32 s10, s10, s41
	s_mov_b32 m0, s10
	s_nop 0
	global_load_lds_dwordx4 v140, s[8:9]
	s_add_i32 m0, s10, 0x2000
	s_nop 0
	global_load_lds_dwordx4 v136, s[8:9]
	ds_read_b128 v[128:131], v173
	ds_read_b128 v[132:135], v173 offset:1024
	ds_read_b128 v[154:157], v173 offset:2048
	ds_read_b128 v[158:161], v173 offset:3072
	s_waitcnt vmcnt(6)
	s_setprio 1
	s_barrier
	v_mfma_f32_16x16x32_bf16 v[48:51], v[202:205], v[162:165], v[48:51]
	v_mfma_f32_16x16x32_bf16 v[40:43], v[212:215], v[162:165], v[40:43]
	v_mfma_f32_16x16x32_bf16 v[32:35], v[202:205], v[178:181], v[32:35]
	v_mfma_f32_16x16x32_bf16 v[24:27], v[212:215], v[178:181], v[24:27]
	v_mfma_f32_16x16x32_bf16 v[16:19], v[202:205], v[186:189], v[16:19]
	v_mfma_f32_16x16x32_bf16 v[8:11], v[212:215], v[186:189], v[8:11]
	v_mfma_f32_16x16x32_bf16 v[4:7], v[202:205], v[194:197], v[4:7]
	v_mfma_f32_16x16x32_bf16 v[0:3], v[212:215], v[194:197], v[0:3]
	v_mfma_f32_16x16x32_bf16 v[48:51], v[206:209], v[166:169], v[48:51]
	v_mfma_f32_16x16x32_bf16 v[40:43], v[216:219], v[166:169], v[40:43]
	v_mfma_f32_16x16x32_bf16 v[32:35], v[206:209], v[182:185], v[32:35]
	v_mfma_f32_16x16x32_bf16 v[24:27], v[216:219], v[182:185], v[24:27]
	v_mfma_f32_16x16x32_bf16 v[16:19], v[206:209], v[190:193], v[16:19]
	v_mfma_f32_16x16x32_bf16 v[8:11], v[216:219], v[190:193], v[8:11]
	v_mfma_f32_16x16x32_bf16 v[4:7], v[206:209], v[198:201], v[4:7]
	v_mfma_f32_16x16x32_bf16 v[0:3], v[216:219], v[198:201], v[0:3]
	s_add_i32 s52, s52, 2
	s_add_u32 s6, s6, 0x100
	s_addc_u32 s7, s7, 0
	s_add_u32 s44, s44, 0x100
	s_addc_u32 s45, s45, 0
	s_cmp_gt_u32 s52, 29
	s_barrier
	s_setprio 0
	s_cbranch_scc0 .LBB0_346
	s_waitcnt lgkmcnt(0)
	v_lshl_add_u32 v168, s4, 8, v170
	v_ashrrev_i32_e32 v169, 31, v168
	v_or_b32_e32 v154, 16, v168
	v_lshlrev_b64 v[128:129], 7, v[168:169]
	v_ashrrev_i32_e32 v155, 31, v154
	v_lshl_add_u64 v[128:129], v[144:145], 0, v[128:129]
	v_lshlrev_b64 v[156:157], 7, v[154:155]
	global_load_dwordx4 v[132:135], v[128:129], off
	s_nop 0
	global_load_dwordx4 v[128:131], v[128:129], off offset:16
	v_lshl_add_u64 v[156:157], v[144:145], 0, v[156:157]
	global_load_dwordx4 v[178:181], v[156:157], off
	global_load_dwordx4 v[182:185], v[156:157], off offset:16
	v_or_b32_e32 v160, 32, v168
	v_ashrrev_i32_e32 v161, 31, v160
	v_lshlrev_b64 v[156:157], 7, v[160:161]
	v_lshl_add_u64 v[156:157], v[144:145], 0, v[156:157]
	global_load_dwordx4 v[186:189], v[156:157], off
	global_load_dwordx4 v[190:193], v[156:157], off offset:16
	v_or_b32_e32 v156, 48, v168
	v_ashrrev_i32_e32 v157, 31, v156
	v_lshlrev_b64 v[158:159], 7, v[156:157]
	v_lshl_add_u64 v[158:159], v[144:145], 0, v[158:159]
	global_load_dwordx4 v[194:197], v[158:159], off
	global_load_dwordx4 v[198:201], v[158:159], off offset:16
	v_add_u32_e32 v164, 0x80, v168
	v_ashrrev_i32_e32 v165, 31, v164
	v_lshlrev_b64 v[158:159], 7, v[164:165]
	v_lshl_add_u64 v[158:159], v[144:145], 0, v[158:159]
	global_load_dwordx4 v[202:205], v[158:159], off
	global_load_dwordx4 v[206:209], v[158:159], off offset:16
	v_add_u32_e32 v158, 0x90, v168
	v_ashrrev_i32_e32 v159, 31, v158
	v_lshlrev_b64 v[162:163], 7, v[158:159]
	v_lshl_add_u64 v[162:163], v[144:145], 0, v[162:163]
	global_load_dwordx4 v[212:215], v[162:163], off
	global_load_dwordx4 v[216:219], v[162:163], off offset:16
	v_add_u32_e32 v166, 0xa0, v168
	v_ashrrev_i32_e32 v167, 31, v166
	v_lshlrev_b64 v[162:163], 7, v[166:167]
	v_lshl_add_u64 v[162:163], v[144:145], 0, v[162:163]
	global_load_dwordx4 v[220:223], v[162:163], off
	global_load_dwordx4 v[224:227], v[162:163], off offset:16
	v_add_u32_e32 v162, 0xb0, v168
	v_ashrrev_i32_e32 v163, 31, v162
	v_lshlrev_b64 v[228:229], 7, v[162:163]
	v_lshl_add_u64 v[232:233], v[144:145], 0, v[228:229]
	global_load_dwordx4 v[228:231], v[232:233], off
	s_nop 0
	global_load_dwordx4 v[232:235], v[232:233], off offset:16
	s_waitcnt vmcnt(0)
	v_mov_b32_e32 v236, v132
	v_mov_b32_e32 v237, v128
	v_mov_b32_e32 v128, v133
	v_mov_b32_e32 v132, v134
	v_mov_b32_e32 v133, v130
	v_mov_b32_e32 v130, v135
	v_pk_add_f32 v[130:131], v[132:133], v[130:131]
	v_mov_b32_e32 v132, v178
	v_mov_b32_e32 v133, v182
	v_mov_b32_e32 v182, v179
	v_mov_b32_e32 v134, v180
	v_mov_b32_e32 v135, v184
	v_mov_b32_e32 v184, v181
	v_pk_add_f32 v[128:129], v[236:237], v[128:129]
	v_pk_add_f32 v[132:133], v[132:133], v[182:183]
	v_pk_add_f32 v[134:135], v[134:135], v[184:185]
	v_pk_add_f32 v[128:129], v[128:129], v[130:131]
	v_pk_add_f32 v[130:131], v[132:133], v[134:135]
	v_mov_b32_e32 v133, v128
	v_mov_b32_e32 v132, v130
	v_and_b32_e32 v130, 64, v176
	v_add_u32_e32 v155, 64, v130
	v_xor_b32_e32 v130, 16, v176
	v_cmp_lt_i32_e32 vcc, v130, v155
	v_mov_b32_e32 v128, v131
	v_pk_add_f32 v[128:129], v[132:133], v[128:129]
	v_cndmask_b32_e32 v130, v176, v130, vcc
	v_lshlrev_b32_e32 v157, 2, v130
	ds_bpermute_b32 v131, v157, v129
	ds_bpermute_b32 v130, v157, v128
	v_mov_b32_e32 v178, v186
	v_mov_b32_e32 v179, v190
	v_mov_b32_e32 v190, v187
	v_mov_b32_e32 v186, v194
	s_waitcnt lgkmcnt(0)
	v_pk_add_f32 v[128:129], v[128:129], v[130:131]
	v_xor_b32_e32 v130, 32, v176
	v_cmp_lt_i32_e32 vcc, v130, v155
	v_mov_b32_e32 v187, v198
	v_mov_b32_e32 v198, v195
	v_cndmask_b32_e32 v130, v176, v130, vcc
	v_lshlrev_b32_e32 v155, 2, v130
	ds_bpermute_b32 v131, v155, v129
	ds_bpermute_b32 v130, v155, v128
	v_pk_add_f32 v[182:183], v[186:187], v[198:199]
	v_mov_b32_e32 v180, v188
	v_mov_b32_e32 v181, v192
	v_mov_b32_e32 v192, v189
	s_waitcnt lgkmcnt(0)
; DI unsigned pack2(float lo, float hi) { f32x2 v = {lo, hi}; bf16v2 r = __builtin_convertvector(v, bf16v2); return __builtin_bit_cast(unsigned, r); }
; DI float row_rstd(const float* ssq, int row, int fq) {
;   const f32x4 a = *(const f32x4*)(ssq + (size_t)row * 32 + fq * 8), b = *(const f32x4*)(ssq + (size_t)row * 32 + fq * 8 + 4);
;   float sm = ((a[0] + a[1]) + (a[2] + a[3])) + ((b[0] + b[1]) + (b[2] + b[3]));
;   sm += __shfl_xor(sm, 16); sm += __shfl_xor(sm, 32);
;   return rsqrtf(sm * (1.0f / 2048.f) + 1e-6f);
; }
;   DI void operator()(const f32x4 (&acc)[2][2][4][2], const Unit& u, int wr, int wc, int fr, int fq) const {
;     const int row0 = u.pm * BM + wr * 64 + fr, col0 = u.pn * BM + wc * 32 + 8 * fq;
;     float rsv[2][4];
; #pragma unroll
;     for (int ai = 0; ai < 2; ++ai)
; #pragma unroll
;       for (int m = 0; m < 4; ++m) rsv[ai][m] = row_rstd(ssq, row0 + ai * HALF + m * 16, fq);
; #pragma unroll
;     for (int ai = 0; ai < 2; ++ai)
; #pragma unroll
;       for (int m = 0; m < 4; ++m) {
;         const int row = row0 + ai * HALF + m * 16;
;         const float rs = rsv[ai][m];
;         bf16_t* rowp = O + (size_t)row * ldc + col0;
; #pragma unroll
;         for (int bj = 0; bj < 2; ++bj) {
;           const f32x4 v0 = acc[ai][bj][m][0] * rs, v1 = acc[ai][bj][m][1] * rs;
;           u32x4 w; w.x = pack2(v0[0], v0[1]); w.y = pack2(v0[2], v0[3]); w.z = pack2(v1[0], v1[1]); w.w = pack2(v1[2], v1[3]);
;           *(u32x4*)(rowp + bj * HALF) = w;
;         }
;       }
	v_pk_add_f32 v[128:129], v[128:129], v[130:131]
	v_mov_b64_e32 v[130:131], s[26:27]
	v_pk_fma_f32 v[128:129], v[128:129], s[24:25], v[130:131] op_sel_hi:[1,0,0]
	v_mov_b32_e32 v188, v196
	v_mul_f32_e32 v159, 0x4b800000, v129
	v_cmp_gt_f32_e32 vcc, s73, v129
	v_mov_b32_e32 v189, v200
	v_mov_b32_e32 v200, v197
	v_cndmask_b32_e32 v129, v129, v159, vcc
	v_rsq_f32_e32 v129, v129
	v_pk_add_f32 v[178:179], v[178:179], v[190:191]
	v_pk_add_f32 v[180:181], v[180:181], v[192:193]
	v_pk_add_f32 v[184:185], v[188:189], v[200:201]
	v_mul_f32_e32 v159, 0x45800000, v129
	v_cndmask_b32_e32 v198, v129, v159, vcc
	v_pk_mul_f32 v[126:127], v[126:127], v[198:199] op_sel_hi:[1,0]
	v_pk_mul_f32 v[124:125], v[124:125], v[198:199] op_sel_hi:[1,0]
	v_pk_mul_f32 v[122:123], v[122:123], v[198:199] op_sel_hi:[1,0]
	v_pk_mul_f32 v[120:121], v[120:121], v[198:199] op_sel_hi:[1,0]
	v_cvt_pk_bf16_f32 v124, v124, v125
	v_cvt_pk_bf16_f32 v125, v126, v127
	v_cvt_pk_bf16_f32 v127, v122, v123
	v_lshl_or_b32 v122, s5, 8, v172
	v_cvt_pk_bf16_f32 v126, v120, v121
	v_ashrrev_i32_e32 v123, 31, v122
	v_mov_b64_e32 v[120:121], s[2:3]
	v_mad_i64_i32 v[168:169], s[4:5], v168, s76, v[120:121]
	v_lshlrev_b64 v[122:123], 1, v[122:123]
	v_lshl_add_u64 v[168:169], v[168:169], 0, v[122:123]
	global_store_dwordx4 v[168:169], v[124:127], off
	v_mov_b32_e32 v194, v202
	v_mov_b32_e32 v195, v206
	v_pk_add_f32 v[124:125], v[178:179], v[180:181]
	v_pk_add_f32 v[126:127], v[182:183], v[184:185]
	v_mov_b32_e32 v179, v124
	v_mov_b32_e32 v178, v126
	v_mov_b32_e32 v124, v127
	v_pk_add_f32 v[124:125], v[178:179], v[124:125]
	ds_bpermute_b32 v127, v157, v125
	ds_bpermute_b32 v126, v157, v124
	v_mov_b32_e32 v206, v203
	v_mov_b32_e32 v196, v204
	v_mov_b32_e32 v197, v208
	v_mov_b32_e32 v208, v205
	v_mov_b32_e32 v202, v212
	v_mov_b32_e32 v203, v216
	v_mov_b32_e32 v216, v213
	v_mov_b32_e32 v204, v214
	v_mov_b32_e32 v205, v218
	v_mov_b32_e32 v218, v215
	v_pk_add_f32 v[186:187], v[194:195], v[206:207]
	v_pk_add_f32 v[188:189], v[196:197], v[208:209]
	v_pk_add_f32 v[190:191], v[202:203], v[216:217]
	v_pk_add_f32 v[192:193], v[204:205], v[218:219]
	v_pk_mul_f32 v[178:179], v[114:115], v[198:199] op_sel_hi:[1,0]
	s_waitcnt lgkmcnt(0)
	v_pk_add_f32 v[114:115], v[124:125], v[126:127]
	v_pk_add_f32 v[126:127], v[186:187], v[188:189]
	v_pk_add_f32 v[180:181], v[190:191], v[192:193]
	v_mov_b32_e32 v183, v126
	v_mov_b32_e32 v182, v180
	v_mov_b32_e32 v126, v181
	v_pk_add_f32 v[126:127], v[182:183], v[126:127]
	ds_bpermute_b32 v125, v155, v115
	ds_bpermute_b32 v124, v155, v114
	ds_bpermute_b32 v181, v157, v127
	ds_bpermute_b32 v180, v157, v126
	v_mul_f32_e32 v129, 0x4b800000, v128
	v_cmp_gt_f32_e32 vcc, s73, v128
	s_waitcnt lgkmcnt(2)
	v_pk_add_f32 v[114:115], v[114:115], v[124:125]
	v_mov_b32_e32 v194, v220
	s_waitcnt lgkmcnt(0)
	v_pk_add_f32 v[124:125], v[126:127], v[180:181]
	ds_bpermute_b32 v127, v155, v125
	ds_bpermute_b32 v126, v155, v124
	v_pk_fma_f32 v[114:115], v[114:115], s[24:25], v[130:131] op_sel_hi:[1,0,0]
	v_cndmask_b32_e32 v159, v128, v129, vcc
	v_mul_f32_e32 v128, 0x4b800000, v115
	v_cmp_gt_f32_e64 s[4:5], s73, v115
	v_cmp_gt_f32_e64 s[6:7], s73, v114
	v_mov_b32_e32 v195, v224
	v_cndmask_b32_e64 v161, v115, v128, s[4:5]
	v_mul_f32_e32 v115, 0x4b800000, v114
	v_mov_b32_e32 v224, v221
	v_mov_b32_e32 v196, v222
	v_mov_b32_e32 v197, v226
	v_mov_b32_e32 v226, v223
	v_cndmask_b32_e64 v163, v114, v115, s[6:7]
	s_waitcnt lgkmcnt(0)
	v_pk_add_f32 v[114:115], v[124:125], v[126:127]
	v_pk_add_f32 v[132:133], v[194:195], v[224:225]
	v_pk_add_f32 v[134:135], v[196:197], v[226:227]
	v_mov_b32_e32 v194, v228
	v_mov_b32_e32 v195, v232
	v_mov_b32_e32 v232, v229
	v_mov_b32_e32 v196, v230
	v_mov_b32_e32 v197, v234
	v_mov_b32_e32 v234, v231
	v_pk_fma_f32 v[114:115], v[114:115], s[24:25], v[130:131] op_sel_hi:[1,0,0]
	v_pk_add_f32 v[194:195], v[194:195], v[232:233]
	v_pk_add_f32 v[196:197], v[196:197], v[234:235]
	v_mul_f32_e32 v124, 0x4b800000, v115
	v_cmp_gt_f32_e64 s[8:9], s73, v115
	v_pk_add_f32 v[126:127], v[194:195], v[196:197]
	v_cmp_gt_f32_e64 s[10:11], s73, v114
	v_cndmask_b32_e64 v165, v115, v124, s[8:9]
	v_pk_add_f32 v[124:125], v[132:133], v[134:135]
	v_mov_b32_e32 v128, v126
	v_mov_b32_e32 v129, v124
	v_mov_b32_e32 v124, v127
	v_pk_add_f32 v[124:125], v[128:129], v[124:125]
	ds_bpermute_b32 v127, v157, v125
	ds_bpermute_b32 v126, v157, v124
	v_rsq_f32_e32 v128, v159
	v_mul_f32_e32 v115, 0x4b800000, v114
	v_cndmask_b32_e64 v129, v114, v115, s[10:11]
	v_pk_mul_f32 v[116:117], v[116:117], v[198:199] op_sel_hi:[1,0]
	s_waitcnt lgkmcnt(0)
	v_pk_add_f32 v[114:115], v[124:125], v[126:127]
	ds_bpermute_b32 v125, v155, v115
	ds_bpermute_b32 v124, v155, v114
	v_mul_f32_e32 v126, 0x45800000, v128
	v_rsq_f32_e32 v127, v161
	v_cndmask_b32_e32 v126, v128, v126, vcc
	v_rsq_f32_e32 v128, v163
	s_waitcnt lgkmcnt(0)
; DI unsigned pack2(float lo, float hi) { f32x2 v = {lo, hi}; bf16v2 r = __builtin_convertvector(v, bf16v2); return __builtin_bit_cast(unsigned, r); }
;   DI void operator()(const f32x4 (&acc)[2][2][4][2], const Unit& u, int wr, int wc, int fr, int fq) const {
;     ...
;     for (int ai = 0; ai < 2; ++ai)
; #pragma unroll
;       for (int m = 0; m < 4; ++m) {
;         const int row = row0 + ai * HALF + m * 16;
;         const float rs = rsv[ai][m];
;         bf16_t* rowp = O + (size_t)row * ldc + col0;
; #pragma unroll
;         for (int bj = 0; bj < 2; ++bj) {
;           const f32x4 v0 = acc[ai][bj][m][0] * rs, v1 = acc[ai][bj][m][1] * rs;
;           u32x4 w; w.x = pack2(v0[0], v0[1]); w.y = pack2(v0[2], v0[3]); w.z = pack2(v1[0], v1[1]); w.w = pack2(v1[2], v1[3]);
;           *(u32x4*)(rowp + bj * HALF) = w;
;         }
;       }
	v_pk_add_f32 v[114:115], v[114:115], v[124:125]
	v_mul_f32_e32 v124, 0x45800000, v127
	v_cndmask_b32_e64 v124, v127, v124, s[4:5]
	v_mul_f32_e32 v127, 0x45800000, v128
	v_pk_fma_f32 v[114:115], v[114:115], s[24:25], v[130:131] op_sel_hi:[1,0,0]
	v_rsq_f32_e32 v125, v165
	v_cndmask_b32_e64 v128, v128, v127, s[6:7]
	v_rsq_f32_e32 v127, v129
	v_mul_f32_e32 v129, 0x4b800000, v115
	v_cmp_gt_f32_e32 vcc, s73, v115
	v_cmp_gt_f32_e64 s[4:5], s73, v114
	v_pk_mul_f32 v[118:119], v[118:119], v[198:199] op_sel_hi:[1,0]
	v_cndmask_b32_e32 v129, v115, v129, vcc
	v_mul_f32_e32 v115, 0x4b800000, v114
	v_cndmask_b32_e64 v131, v114, v115, s[4:5]
	v_cvt_pk_bf16_f32 v114, v116, v117
	v_rsq_f32_e32 v117, v129
	v_cvt_pk_bf16_f32 v115, v118, v119
	v_rsq_f32_e32 v119, v131
	v_mul_f32_e32 v116, 0x45800000, v125
	v_pk_mul_f32 v[112:113], v[112:113], v[198:199] op_sel_hi:[1,0]
	v_cndmask_b32_e64 v118, v125, v116, s[8:9]
	v_mul_f32_e32 v116, 0x45800000, v127
	v_cndmask_b32_e64 v130, v127, v116, s[10:11]
	v_cvt_pk_bf16_f32 v116, v112, v113
	v_mul_f32_e32 v112, 0x45800000, v117
	v_cndmask_b32_e32 v132, v117, v112, vcc
	v_mul_f32_e32 v112, 0x45800000, v119
	v_cvt_pk_bf16_f32 v117, v178, v179
	v_cndmask_b32_e64 v112, v119, v112, s[4:5]
	global_store_dwordx4 v[168:169], v[114:117], off offset:256
	v_pk_mul_f32 v[110:111], v[110:111], v[126:127] op_sel_hi:[1,0]
	v_pk_mul_f32 v[108:109], v[108:109], v[126:127] op_sel_hi:[1,0]
	v_mad_i64_i32 v[114:115], s[4:5], v154, s76, v[120:121]
	v_pk_mul_f32 v[116:117], v[106:107], v[126:127] op_sel_hi:[1,0]
	v_pk_mul_f32 v[106:107], v[104:105], v[126:127] op_sel_hi:[1,0]
	v_lshl_add_u64 v[114:115], v[114:115], 0, v[122:123]
	v_cvt_pk_bf16_f32 v104, v108, v109
	v_cvt_pk_bf16_f32 v105, v110, v111
	v_cvt_pk_bf16_f32 v106, v106, v107
	v_cvt_pk_bf16_f32 v107, v116, v117
	global_store_dwordx4 v[114:115], v[104:107], off
	v_pk_mul_f32 v[98:99], v[98:99], v[126:127] op_sel_hi:[1,0]
	v_pk_mul_f32 v[96:97], v[96:97], v[126:127] op_sel_hi:[1,0]
	v_pk_mul_f32 v[104:105], v[90:91], v[126:127] op_sel_hi:[1,0]
	v_pk_mul_f32 v[90:91], v[88:89], v[126:127] op_sel_hi:[1,0]
	v_cvt_pk_bf16_f32 v88, v96, v97
	v_cvt_pk_bf16_f32 v89, v98, v99
	v_cvt_pk_bf16_f32 v90, v90, v91
	v_cvt_pk_bf16_f32 v91, v104, v105
	global_store_dwordx4 v[114:115], v[88:91], off offset:256
	v_pk_mul_f32 v[94:95], v[94:95], v[124:125] op_sel_hi:[1,0]
	v_pk_mul_f32 v[92:93], v[92:93], v[124:125] op_sel_hi:[1,0]
	v_mad_i64_i32 v[88:89], s[4:5], v160, s76, v[120:121]
	v_lshl_add_u64 v[96:97], v[88:89], 0, v[122:123]
	v_pk_mul_f32 v[90:91], v[102:103], v[124:125] op_sel_hi:[1,0]
	v_pk_mul_f32 v[88:89], v[100:101], v[124:125] op_sel_hi:[1,0]
	v_pk_mul_f32 v[82:83], v[82:83], v[124:125] op_sel_hi:[1,0]
	v_cvt_pk_bf16_f32 v88, v88, v89
	v_cvt_pk_bf16_f32 v89, v90, v91
	v_cvt_pk_bf16_f32 v90, v92, v93
	v_cvt_pk_bf16_f32 v91, v94, v95
	global_store_dwordx4 v[96:97], v[88:91], off
	v_pk_mul_f32 v[80:81], v[80:81], v[124:125] op_sel_hi:[1,0]
	v_pk_mul_f32 v[78:79], v[78:79], v[128:129] op_sel_hi:[1,0]
	v_pk_mul_f32 v[88:89], v[74:75], v[124:125] op_sel_hi:[1,0]
	v_pk_mul_f32 v[74:75], v[72:73], v[124:125] op_sel_hi:[1,0]
	v_cvt_pk_bf16_f32 v72, v80, v81
	v_cvt_pk_bf16_f32 v73, v82, v83
	v_cvt_pk_bf16_f32 v74, v74, v75
	v_cvt_pk_bf16_f32 v75, v88, v89
	global_store_dwordx4 v[96:97], v[72:75], off offset:256
	v_pk_mul_f32 v[76:77], v[76:77], v[128:129] op_sel_hi:[1,0]
	v_pk_mul_f32 v[70:71], v[70:71], v[128:129] op_sel_hi:[1,0]
	v_mad_i64_i32 v[72:73], s[4:5], v156, s76, v[120:121]
	v_lshl_add_u64 v[80:81], v[72:73], 0, v[122:123]
	v_pk_mul_f32 v[74:75], v[86:87], v[128:129] op_sel_hi:[1,0]
	v_pk_mul_f32 v[72:73], v[84:85], v[128:129] op_sel_hi:[1,0]
	v_pk_mul_f32 v[68:69], v[68:69], v[128:129] op_sel_hi:[1,0]
	v_cvt_pk_bf16_f32 v72, v72, v73
	v_cvt_pk_bf16_f32 v73, v74, v75
	v_cvt_pk_bf16_f32 v74, v76, v77
	v_cvt_pk_bf16_f32 v75, v78, v79
	global_store_dwordx4 v[80:81], v[72:75], off
	v_pk_mul_f32 v[62:63], v[62:63], v[118:119] op_sel_hi:[1,0]
	v_pk_mul_f32 v[60:61], v[60:61], v[118:119] op_sel_hi:[1,0]
	v_pk_mul_f32 v[72:73], v[66:67], v[128:129] op_sel_hi:[1,0]
	v_pk_mul_f32 v[66:67], v[64:65], v[128:129] op_sel_hi:[1,0]
; DI unsigned pack2(float lo, float hi) { f32x2 v = {lo, hi}; bf16v2 r = __builtin_convertvector(v, bf16v2); return __builtin_bit_cast(unsigned, r); }
; #define PG8_WAIT_V(n) asm volatile("s_waitcnt vmcnt(" #n ")" ::: "memory")
; #define PG8_BAR __builtin_amdgcn_s_barrier()
;   DI void operator()(const f32x4 (&acc)[2][2][4][2], const Unit& u, int wr, int wc, int fr, int fq) const {
;     ...
;     for (int ai = 0; ai < 2; ++ai)
; #pragma unroll
;       for (int m = 0; m < 4; ++m) {
;         const int row = row0 + ai * HALF + m * 16;
;         const float rs = rsv[ai][m];
;         bf16_t* rowp = O + (size_t)row * ldc + col0;
; #pragma unroll
;         for (int bj = 0; bj < 2; ++bj) {
;           const f32x4 v0 = acc[ai][bj][m][0] * rs, v1 = acc[ai][bj][m][1] * rs;
;           u32x4 w; w.x = pack2(v0[0], v0[1]); w.y = pack2(v0[2], v0[3]); w.z = pack2(v1[0], v1[1]); w.w = pack2(v1[2], v1[3]);
;           *(u32x4*)(rowp + bj * HALF) = w;
;         }
;       }
; template <class Epi, class Sched = StaticOrder>
; DI void gemm_phase(LAS unsigned char* lds, const Gemm g, const Sched& S, const Epi& E) {
;     ...
;     E(acc, cur, wr, wc, fr, fq);
;     if (!has_next) break;
; #pragma unroll
;     for (int a = 0; a < 2; ++a)
; #pragma unroll
;       for (int b = 0; b < 2; ++b)
; #pragma unroll
;         for (int m = 0; m < 4; ++m)
; #pragma unroll
;           for (int n = 0; n < 2; ++n) acc[a][b][m][n] = (f32x4){0.f, 0.f, 0.f, 0.f};
;     cur = nxt; cA = nA; cB = nB; ++ui;
;   }
;   PG8_WAIT_V(0);
;   if (wr == 0) PG8_BAR;
;   PG8_BAR;
	v_cvt_pk_bf16_f32 v64, v68, v69
	v_cvt_pk_bf16_f32 v65, v70, v71
	v_cvt_pk_bf16_f32 v66, v66, v67
	v_cvt_pk_bf16_f32 v67, v72, v73
	global_store_dwordx4 v[80:81], v[64:67], off offset:256
	v_pk_mul_f32 v[50:51], v[50:51], v[118:119] op_sel_hi:[1,0]
	v_pk_mul_f32 v[48:49], v[48:49], v[118:119] op_sel_hi:[1,0]
	v_mad_i64_i32 v[64:65], s[4:5], v164, s76, v[120:121]
	v_pk_mul_f32 v[66:67], v[58:59], v[118:119] op_sel_hi:[1,0]
	v_pk_mul_f32 v[58:59], v[56:57], v[118:119] op_sel_hi:[1,0]
	v_lshl_add_u64 v[64:65], v[64:65], 0, v[122:123]
	v_cvt_pk_bf16_f32 v56, v60, v61
	v_cvt_pk_bf16_f32 v57, v62, v63
	v_cvt_pk_bf16_f32 v58, v58, v59
	v_cvt_pk_bf16_f32 v59, v66, v67
	global_store_dwordx4 v[64:65], v[56:59], off
	v_pk_mul_f32 v[46:47], v[46:47], v[130:131] op_sel_hi:[1,0]
	v_pk_mul_f32 v[44:45], v[44:45], v[130:131] op_sel_hi:[1,0]
	v_pk_mul_f32 v[56:57], v[42:43], v[118:119] op_sel_hi:[1,0]
	v_pk_mul_f32 v[42:43], v[40:41], v[118:119] op_sel_hi:[1,0]
	v_cvt_pk_bf16_f32 v40, v48, v49
	v_cvt_pk_bf16_f32 v41, v50, v51
	v_cvt_pk_bf16_f32 v42, v42, v43
	v_cvt_pk_bf16_f32 v43, v56, v57
	global_store_dwordx4 v[64:65], v[40:43], off offset:256
	v_pk_mul_f32 v[34:35], v[34:35], v[130:131] op_sel_hi:[1,0]
	v_pk_mul_f32 v[32:33], v[32:33], v[130:131] op_sel_hi:[1,0]
	v_mad_i64_i32 v[40:41], s[4:5], v158, s76, v[120:121]
	v_lshl_add_u64 v[48:49], v[40:41], 0, v[122:123]
	v_pk_mul_f32 v[42:43], v[54:55], v[130:131] op_sel_hi:[1,0]
	v_pk_mul_f32 v[40:41], v[52:53], v[130:131] op_sel_hi:[1,0]
	v_pk_mul_f32 v[30:31], v[30:31], v[132:133] op_sel_hi:[1,0]
	v_cvt_pk_bf16_f32 v40, v40, v41
	v_cvt_pk_bf16_f32 v41, v42, v43
	v_cvt_pk_bf16_f32 v42, v44, v45
	v_cvt_pk_bf16_f32 v43, v46, v47
	global_store_dwordx4 v[48:49], v[40:43], off
	v_pk_mul_f32 v[28:29], v[28:29], v[132:133] op_sel_hi:[1,0]
	v_pk_mul_f32 v[18:19], v[18:19], v[132:133] op_sel_hi:[1,0]
	v_pk_mul_f32 v[40:41], v[26:27], v[130:131] op_sel_hi:[1,0]
	v_pk_mul_f32 v[26:27], v[24:25], v[130:131] op_sel_hi:[1,0]
	v_cvt_pk_bf16_f32 v24, v32, v33
	v_cvt_pk_bf16_f32 v25, v34, v35
	v_cvt_pk_bf16_f32 v26, v26, v27
	v_cvt_pk_bf16_f32 v27, v40, v41
	global_store_dwordx4 v[48:49], v[24:27], off offset:256
	v_pk_mul_f32 v[16:17], v[16:17], v[132:133] op_sel_hi:[1,0]
	v_pk_mul_f32 v[14:15], v[14:15], v[112:113] op_sel_hi:[1,0]
	v_mad_i64_i32 v[24:25], s[4:5], v166, s76, v[120:121]
	v_lshl_add_u64 v[32:33], v[24:25], 0, v[122:123]
	v_pk_mul_f32 v[26:27], v[38:39], v[132:133] op_sel_hi:[1,0]
	v_pk_mul_f32 v[24:25], v[36:37], v[132:133] op_sel_hi:[1,0]
	v_pk_mul_f32 v[12:13], v[12:13], v[112:113] op_sel_hi:[1,0]
	v_cvt_pk_bf16_f32 v24, v24, v25
	v_cvt_pk_bf16_f32 v25, v26, v27
	v_cvt_pk_bf16_f32 v26, v28, v29
	v_cvt_pk_bf16_f32 v27, v30, v31
	global_store_dwordx4 v[32:33], v[24:27], off
	v_pk_mul_f32 v[6:7], v[6:7], v[112:113] op_sel_hi:[1,0]
	v_pk_mul_f32 v[4:5], v[4:5], v[112:113] op_sel_hi:[1,0]
	v_pk_mul_f32 v[24:25], v[10:11], v[132:133] op_sel_hi:[1,0]
	v_pk_mul_f32 v[10:11], v[8:9], v[132:133] op_sel_hi:[1,0]
	v_cvt_pk_bf16_f32 v8, v16, v17
	v_cvt_pk_bf16_f32 v9, v18, v19
	v_cvt_pk_bf16_f32 v10, v10, v11
	v_cvt_pk_bf16_f32 v11, v24, v25
	global_store_dwordx4 v[32:33], v[8:11], off offset:256
	s_and_b64 vcc, exec, s[0:1]
	s_mov_b64 s[8:9], s[36:37]
	v_mad_i64_i32 v[8:9], s[4:5], v162, s76, v[120:121]
	v_lshl_add_u64 v[16:17], v[8:9], 0, v[122:123]
	v_pk_mul_f32 v[10:11], v[22:23], v[112:113] op_sel_hi:[1,0]
	v_pk_mul_f32 v[8:9], v[20:21], v[112:113] op_sel_hi:[1,0]
	s_mov_b32 s5, s28
	v_cvt_pk_bf16_f32 v8, v8, v9
	v_cvt_pk_bf16_f32 v9, v10, v11
	v_cvt_pk_bf16_f32 v10, v12, v13
	v_cvt_pk_bf16_f32 v11, v14, v15
	global_store_dwordx4 v[16:17], v[8:11], off
	s_mov_b32 s4, s30
	s_mov_b64 s[6:7], s[34:35]
	v_pk_mul_f32 v[8:9], v[2:3], v[112:113] op_sel_hi:[1,0]
	v_pk_mul_f32 v[2:3], v[0:1], v[112:113] op_sel_hi:[1,0]
	v_cvt_pk_bf16_f32 v0, v4, v5
	v_cvt_pk_bf16_f32 v1, v6, v7
	v_cvt_pk_bf16_f32 v2, v2, v3
	v_cvt_pk_bf16_f32 v3, v8, v9
	global_store_dwordx4 v[16:17], v[0:3], off offset:256
	s_cbranch_vccz .LBB0_343
	s_waitcnt vmcnt(0)
	s_cmpk_gt_u32 s27, 0xff
	s_cbranch_scc1 .LBB0_350
	s_barrier

; #define PG8_STAGE(bufoff, gbase, voff) do { _Pragma("unroll") for (int _i = 0; _i < 2; ++_i) \
;     __builtin_amdgcn_global_load_lds((const unsigned*)((const char*)(gbase) + (voff)[_i]), (LAS unsigned*)(lds + (bufoff) + ldsw + _i * 8192), 16, 0, 0); } while (0)
; #define PG8_LDA(dst, b, h) do { _Pragma("unroll") for (int m = 0; m < 4; ++m) _Pragma("unroll") for (int k = 0; k < 2; ++k) dst[m][k] = *(const LAS bf16x8*)(lds + PG8_SA(b, h) + aoff + m * 2048 + k * 1024); } while (0)
; #define PG8_LDB(dst, b, h) do { _Pragma("unroll") for (int n = 0; n < 2; ++n) _Pragma("unroll") for (int k = 0; k < 2; ++k) dst[n][k] = *(const LAS bf16x8*)(lds + PG8_SB(b, h) + boff + n * 2048 + k * 1024); } while (0)
; #define PG8_MMA(ai, bj, At, Bt) do { __builtin_amdgcn_s_setprio(1); _Pragma("unroll") for (int m = 0; m < 4; ++m) _Pragma("unroll") for (int n = 0; n < 2; ++n) _Pragma("unroll") for (int k = 0; k < 2; ++k) \
;     acc[ai][bj][m][n] = __builtin_amdgcn_mfma_f32_16x16x32_bf16(Bt[n][k], At[m][k], acc[ai][bj][m][n], 0, 0, 0); __builtin_amdgcn_s_setprio(0); } while (0)
; #define PG8_WAIT_V(n) asm volatile("s_waitcnt vmcnt(" #n ")" ::: "memory")
; template <class Epi, class Sched = StaticOrder>
; DI void gemm_phase(LAS unsigned char* lds, const Gemm g, const Sched& S, const Epi& E) {
;     ...
;     for (int t = 0; t < nt; t += 2) {
;       const bool last = (t == nt - 2);
;       const char* a1 = cA + (size_t)(t + 1) * kstep;
;       const char* a2 = last ? nA : cA + (size_t)(t + 2) * kstep; const char* b2 = last ? nB : cB + (size_t)(t + 2) * kstep;
;       const char* a3 = a2 + kstep; const char* b3 = b2 + kstep;
;       PG8_LDB(B0, 0, 0); PG8_SCHED; PG8_LDA(At, 0, 0); PG8_STAGE(PG8_SA(1, 1), a1 + hstep, voffA);
;       PG8_WAIT_L(8); PG8_BAR; PG8_WAIT_L(0); PG8_MMA(0, 0, At, B0); PG8_BAR; PG8_SCHED;
;       PG8_LDB(B1, 0, 1); PG8_STAGE(PG8_SB(0, 0), b2, voffB);
;       PG8_BAR; PG8_WAIT_L(0); PG8_MMA(0, 1, At, B1); PG8_BAR;
;       PG8_LDA(At, 0, 1); PG8_STAGE(PG8_SA(0, 0), a2, voffA);
;       PG8_BAR; PG8_WAIT_L(0); PG8_MMA(1, 0, At, B0); PG8_BAR; PG8_SCHED;
;       PG8_STAGE(PG8_SB(0, 1), b2 + hstep, voffB);
;       PG8_WAIT_V(6); PG8_BAR; PG8_MMA(1, 1, At, B1); PG8_BAR;
;       PG8_LDB(B0, 1, 0); PG8_SCHED; PG8_LDA(At, 1, 0); PG8_STAGE(PG8_SA(0, 1), a2 + hstep, voffA);
;       PG8_WAIT_L(8); PG8_BAR; PG8_WAIT_L(0); PG8_MMA(0, 0, At, B0); PG8_BAR; PG8_SCHED;
.LBB0_728:
	s_add_i32 m0, s37, 0xc000
	ds_read_b128 v[144:147], v208
	ds_read_b128 v[148:151], v208 offset:1024
	ds_read_b128 v[152:155], v208 offset:2048
	ds_read_b128 v[156:159], v208 offset:3072
	ds_read_b128 v[160:163], v208 offset:4096
	ds_read_b128 v[164:167], v208 offset:5120
	ds_read_b128 v[168:171], v208 offset:6144
	ds_read_b128 v[172:175], v208 offset:7168
	global_load_lds_dwordx4 v184, s[22:23]
	s_add_i32 m0, s37, 0xe000
	s_nop 0
	global_load_lds_dwordx4 v186, s[22:23]
	s_waitcnt lgkmcnt(0)
	s_setprio 1
	s_barrier
	v_mfma_f32_16x16x32_bf16 v[124:127], v[128:131], v[144:147], v[124:127]
	v_mfma_f32_16x16x32_bf16 v[120:123], v[136:139], v[144:147], v[120:123]
	v_mfma_f32_16x16x32_bf16 v[108:111], v[128:131], v[152:155], v[108:111]
	v_mfma_f32_16x16x32_bf16 v[104:107], v[136:139], v[152:155], v[104:107]
	v_mfma_f32_16x16x32_bf16 v[92:95], v[128:131], v[160:163], v[92:95]
	v_mfma_f32_16x16x32_bf16 v[88:91], v[136:139], v[160:163], v[88:91]
	v_mfma_f32_16x16x32_bf16 v[76:79], v[128:131], v[168:171], v[76:79]
	v_mfma_f32_16x16x32_bf16 v[72:75], v[136:139], v[168:171], v[72:75]
	v_mfma_f32_16x16x32_bf16 v[124:127], v[132:135], v[148:151], v[124:127]
	v_mfma_f32_16x16x32_bf16 v[120:123], v[140:143], v[148:151], v[120:123]
	v_mfma_f32_16x16x32_bf16 v[108:111], v[132:135], v[156:159], v[108:111]
	v_mfma_f32_16x16x32_bf16 v[104:107], v[140:143], v[156:159], v[104:107]
	v_mfma_f32_16x16x32_bf16 v[92:95], v[132:135], v[164:167], v[92:95]
	v_mfma_f32_16x16x32_bf16 v[88:91], v[140:143], v[164:167], v[88:91]
	v_mfma_f32_16x16x32_bf16 v[76:79], v[132:135], v[172:175], v[76:79]
	v_mfma_f32_16x16x32_bf16 v[72:75], v[140:143], v[172:175], v[72:75]
	s_barrier
	s_setprio 0
	ds_read_b128 v[192:195], v209
	ds_read_b128 v[196:199], v209 offset:1024
	ds_read_b128 v[200:203], v209 offset:2048
	ds_read_b128 v[212:215], v209 offset:3072
	s_add_u32 s24, s22, 0xfff80080
	s_addc_u32 s25, s23, -1
	s_cmp_eq_u32 s53, 28
	s_cselect_b32 s27, s17, s25
	s_cselect_b32 s26, s43, s24
	s_cselect_b32 s25, s15, s52
	s_cselect_b32 s24, s44, s45
	s_add_i32 s54, s50, s35
	s_add_u32 s98, s24, 0x80
	s_addc_u32 s99, s25, 0
	s_add_u32 s100, s26, 0x80
	s_addc_u32 s101, s27, 0
	s_mov_b32 m0, s54
	s_nop 0
	global_load_lds_dwordx4 v180, s[24:25]
	s_add_i32 m0, s54, 0x2000
	s_nop 0
	global_load_lds_dwordx4 v176, s[24:25]
	s_waitcnt lgkmcnt(0)
	s_setprio 1
	s_barrier
	v_mfma_f32_16x16x32_bf16 v[116:119], v[192:195], v[144:147], v[116:119]
	v_mfma_f32_16x16x32_bf16 v[112:115], v[200:203], v[144:147], v[112:115]
	v_mfma_f32_16x16x32_bf16 v[100:103], v[192:195], v[152:155], v[100:103]
	v_mfma_f32_16x16x32_bf16 v[96:99], v[200:203], v[152:155], v[96:99]
	v_mfma_f32_16x16x32_bf16 v[84:87], v[192:195], v[160:163], v[84:87]
	v_mfma_f32_16x16x32_bf16 v[80:83], v[200:203], v[160:163], v[80:83]
	v_mfma_f32_16x16x32_bf16 v[68:71], v[192:195], v[168:171], v[68:71]
	v_mfma_f32_16x16x32_bf16 v[64:67], v[200:203], v[168:171], v[64:67]
	v_mfma_f32_16x16x32_bf16 v[116:119], v[196:199], v[148:151], v[116:119]
	v_mfma_f32_16x16x32_bf16 v[112:115], v[212:215], v[148:151], v[112:115]
	v_mfma_f32_16x16x32_bf16 v[100:103], v[196:199], v[156:159], v[100:103]
	v_mfma_f32_16x16x32_bf16 v[96:99], v[212:215], v[156:159], v[96:99]
	v_mfma_f32_16x16x32_bf16 v[84:87], v[196:199], v[164:167], v[84:87]
	v_mfma_f32_16x16x32_bf16 v[80:83], v[212:215], v[164:167], v[80:83]
	v_mfma_f32_16x16x32_bf16 v[68:71], v[196:199], v[172:175], v[68:71]
	v_mfma_f32_16x16x32_bf16 v[64:67], v[212:215], v[172:175], v[64:67]
	s_barrier
	s_setprio 0
	s_mov_b32 m0, s37
	ds_read_b128 v[144:147], v208 offset:16384
	ds_read_b128 v[148:151], v208 offset:17408
	ds_read_b128 v[152:155], v208 offset:18432
	ds_read_b128 v[156:159], v208 offset:19456
	ds_read_b128 v[160:163], v208 offset:20480
	ds_read_b128 v[164:167], v208 offset:21504
	ds_read_b128 v[168:171], v208 offset:22528
	ds_read_b128 v[172:175], v208 offset:23552
	global_load_lds_dwordx4 v182, s[26:27]
	s_mov_b32 m0, s38
	s_nop 0
	global_load_lds_dwordx4 v178, s[26:27]
	s_waitcnt vmcnt(10)
	s_waitcnt lgkmcnt(0)
	s_setprio 1
	s_barrier
	v_mfma_f32_16x16x32_bf16 v[60:63], v[128:131], v[144:147], v[60:63]
	v_mfma_f32_16x16x32_bf16 v[56:59], v[136:139], v[144:147], v[56:59]
	v_mfma_f32_16x16x32_bf16 v[44:47], v[128:131], v[152:155], v[44:47]
	v_mfma_f32_16x16x32_bf16 v[40:43], v[136:139], v[152:155], v[40:43]
	v_mfma_f32_16x16x32_bf16 v[28:31], v[128:131], v[160:163], v[28:31]
	v_mfma_f32_16x16x32_bf16 v[24:27], v[136:139], v[160:163], v[24:27]
	v_mfma_f32_16x16x32_bf16 v[12:15], v[128:131], v[168:171], v[12:15]
	v_mfma_f32_16x16x32_bf16 v[8:11], v[136:139], v[168:171], v[8:11]
	v_mfma_f32_16x16x32_bf16 v[60:63], v[132:135], v[148:151], v[60:63]
	v_mfma_f32_16x16x32_bf16 v[56:59], v[140:143], v[148:151], v[56:59]
	v_mfma_f32_16x16x32_bf16 v[44:47], v[132:135], v[156:159], v[44:47]
	v_mfma_f32_16x16x32_bf16 v[40:43], v[140:143], v[156:159], v[40:43]
	v_mfma_f32_16x16x32_bf16 v[28:31], v[132:135], v[164:167], v[28:31]
	v_mfma_f32_16x16x32_bf16 v[24:27], v[140:143], v[164:167], v[24:27]
	v_mfma_f32_16x16x32_bf16 v[12:15], v[132:135], v[172:175], v[12:15]
	v_mfma_f32_16x16x32_bf16 v[8:11], v[140:143], v[172:175], v[8:11]
	s_barrier
	s_setprio 0
	s_add_u32 s54, s24, 0x80000
	s_addc_u32 s55, s25, 0
	s_add_i32 s57, s51, s35
	s_mov_b32 m0, s57
	s_nop 0
	global_load_lds_dwordx4 v180, s[54:55]
	s_add_i32 m0, s57, 0x2000
	s_nop 0
	global_load_lds_dwordx4 v176, s[54:55]
	s_add_i32 s54, 0, 0x18000
	v_add_u32_e32 v140, s54, v205
	ds_read_b128 v[128:131], v140
	ds_read_b128 v[132:135], v140 offset:1024
	ds_read_b128 v[136:139], v140 offset:2048
	ds_read_b128 v[140:143], v140 offset:3072
	s_waitcnt vmcnt(6)
	s_setprio 1
	s_barrier
; #define PG8_STAGE(bufoff, gbase, voff) do { _Pragma("unroll") for (int _i = 0; _i < 2; ++_i) \
;     __builtin_amdgcn_global_load_lds((const unsigned*)((const char*)(gbase) + (voff)[_i]), (LAS unsigned*)(lds + (bufoff) + ldsw + _i * 8192), 16, 0, 0); } while (0)
; #define PG8_LDA(dst, b, h) do { _Pragma("unroll") for (int m = 0; m < 4; ++m) _Pragma("unroll") for (int k = 0; k < 2; ++k) dst[m][k] = *(const LAS bf16x8*)(lds + PG8_SA(b, h) + aoff + m * 2048 + k * 1024); } while (0)
; #define PG8_LDB(dst, b, h) do { _Pragma("unroll") for (int n = 0; n < 2; ++n) _Pragma("unroll") for (int k = 0; k < 2; ++k) dst[n][k] = *(const LAS bf16x8*)(lds + PG8_SB(b, h) + boff + n * 2048 + k * 1024); } while (0)
; #define PG8_MMA(ai, bj, At, Bt) do { __builtin_amdgcn_s_setprio(1); _Pragma("unroll") for (int m = 0; m < 4; ++m) _Pragma("unroll") for (int n = 0; n < 2; ++n) _Pragma("unroll") for (int k = 0; k < 2; ++k) \
;     acc[ai][bj][m][n] = __builtin_amdgcn_mfma_f32_16x16x32_bf16(Bt[n][k], At[m][k], acc[ai][bj][m][n], 0, 0, 0); __builtin_amdgcn_s_setprio(0); } while (0)
; #define PG8_WAIT_V(n) asm volatile("s_waitcnt vmcnt(" #n ")" ::: "memory")
; #define PG8_WAIT_L(n) asm volatile("s_waitcnt lgkmcnt(" #n ")" ::: "memory")
; #define PG8_BAR __builtin_amdgcn_s_barrier()
; #define PG8_SCHED __builtin_amdgcn_sched_barrier(0)
; template <class Epi, class Sched = StaticOrder>
; DI void gemm_phase(LAS unsigned char* lds, const Gemm g, const Sched& S, const Epi& E) {
;     ...
;       PG8_BAR; PG8_WAIT_L(0); PG8_MMA(1, 0, At, B0); PG8_BAR; PG8_SCHED;
;       PG8_STAGE(PG8_SB(0, 1), b2 + hstep, voffB);
;       PG8_WAIT_V(6); PG8_BAR; PG8_MMA(1, 1, At, B1); PG8_BAR;
;       PG8_LDB(B0, 1, 0); PG8_SCHED; PG8_LDA(At, 1, 0); PG8_STAGE(PG8_SA(0, 1), a2 + hstep, voffA);
;       PG8_WAIT_L(8); PG8_BAR; PG8_WAIT_L(0); PG8_MMA(0, 0, At, B0); PG8_BAR; PG8_SCHED;
;       PG8_LDB(B1, 1, 1); PG8_STAGE(PG8_SB(1, 0), b3, voffB);
;       PG8_BAR; PG8_WAIT_L(0); PG8_MMA(0, 1, At, B1); PG8_BAR;
;       PG8_LDA(At, 1, 1); PG8_STAGE(PG8_SA(1, 0), a3, voffA);
;       PG8_BAR; PG8_WAIT_L(0); PG8_MMA(1, 0, At, B0); PG8_BAR; PG8_SCHED;
	v_mfma_f32_16x16x32_bf16 v[52:55], v[192:195], v[144:147], v[52:55]
	v_mfma_f32_16x16x32_bf16 v[48:51], v[200:203], v[144:147], v[48:51]
	v_mfma_f32_16x16x32_bf16 v[36:39], v[192:195], v[152:155], v[36:39]
	v_mfma_f32_16x16x32_bf16 v[32:35], v[200:203], v[152:155], v[32:35]
	v_mfma_f32_16x16x32_bf16 v[20:23], v[192:195], v[160:163], v[20:23]
	v_mfma_f32_16x16x32_bf16 v[16:19], v[200:203], v[160:163], v[16:19]
	v_mfma_f32_16x16x32_bf16 v[4:7], v[192:195], v[168:171], v[4:7]
	v_mfma_f32_16x16x32_bf16 v[0:3], v[200:203], v[168:171], v[0:3]
	v_mfma_f32_16x16x32_bf16 v[52:55], v[196:199], v[148:151], v[52:55]
	v_mfma_f32_16x16x32_bf16 v[48:51], v[212:215], v[148:151], v[48:51]
	v_mfma_f32_16x16x32_bf16 v[36:39], v[196:199], v[156:159], v[36:39]
	v_mfma_f32_16x16x32_bf16 v[32:35], v[212:215], v[156:159], v[32:35]
	v_mfma_f32_16x16x32_bf16 v[20:23], v[196:199], v[164:167], v[20:23]
	v_mfma_f32_16x16x32_bf16 v[16:19], v[212:215], v[164:167], v[16:19]
	v_mfma_f32_16x16x32_bf16 v[4:7], v[196:199], v[172:175], v[4:7]
	v_mfma_f32_16x16x32_bf16 v[0:3], v[212:215], v[172:175], v[0:3]
	s_barrier
	s_setprio 0
	s_add_u32 s26, s26, 0x80000
	s_addc_u32 s27, s27, 0
	s_mov_b32 m0, s39
	ds_read_b128 v[144:147], v208 offset:32768
	ds_read_b128 v[148:151], v208 offset:33792
	ds_read_b128 v[152:155], v208 offset:34816
	ds_read_b128 v[156:159], v208 offset:35840
	ds_read_b128 v[160:163], v208 offset:36864
	ds_read_b128 v[164:167], v208 offset:37888
	ds_read_b128 v[168:171], v208 offset:38912
	ds_read_b128 v[172:175], v208 offset:39936
	global_load_lds_dwordx4 v182, s[26:27]
	s_mov_b32 m0, s40
	s_nop 0
	global_load_lds_dwordx4 v178, s[26:27]
	s_waitcnt lgkmcnt(0)
	s_setprio 1
	s_barrier
	v_mfma_f32_16x16x32_bf16 v[124:127], v[128:131], v[144:147], v[124:127]
	v_mfma_f32_16x16x32_bf16 v[120:123], v[136:139], v[144:147], v[120:123]
	v_mfma_f32_16x16x32_bf16 v[108:111], v[128:131], v[152:155], v[108:111]
	v_mfma_f32_16x16x32_bf16 v[104:107], v[136:139], v[152:155], v[104:107]
	v_mfma_f32_16x16x32_bf16 v[92:95], v[128:131], v[160:163], v[92:95]
	v_mfma_f32_16x16x32_bf16 v[88:91], v[136:139], v[160:163], v[88:91]
	v_mfma_f32_16x16x32_bf16 v[76:79], v[128:131], v[168:171], v[76:79]
	v_mfma_f32_16x16x32_bf16 v[72:75], v[136:139], v[168:171], v[72:75]
	v_mfma_f32_16x16x32_bf16 v[124:127], v[132:135], v[148:151], v[124:127]
	v_mfma_f32_16x16x32_bf16 v[120:123], v[140:143], v[148:151], v[120:123]
	v_mfma_f32_16x16x32_bf16 v[108:111], v[132:135], v[156:159], v[108:111]
	v_mfma_f32_16x16x32_bf16 v[104:107], v[140:143], v[156:159], v[104:107]
	v_mfma_f32_16x16x32_bf16 v[92:95], v[132:135], v[164:167], v[92:95]
	v_mfma_f32_16x16x32_bf16 v[88:91], v[140:143], v[164:167], v[88:91]
	v_mfma_f32_16x16x32_bf16 v[76:79], v[132:135], v[172:175], v[76:79]
	v_mfma_f32_16x16x32_bf16 v[72:75], v[140:143], v[172:175], v[72:75]
	s_barrier
	s_setprio 0
	s_add_i32 s26, 0, 0x1c000
	s_add_i32 s27, s54, s35
	v_add_u32_e32 v212, s26, v205
	s_mov_b32 m0, s27
	ds_read_b128 v[192:195], v212
	ds_read_b128 v[196:199], v212 offset:1024
	ds_read_b128 v[200:203], v212 offset:2048
	ds_read_b128 v[212:215], v212 offset:3072
	global_load_lds_dwordx4 v180, s[98:99]
	s_add_i32 m0, s27, 0x2000
	s_nop 0
	global_load_lds_dwordx4 v176, s[98:99]
	s_waitcnt lgkmcnt(0)
	s_setprio 1
	s_barrier
	v_mfma_f32_16x16x32_bf16 v[116:119], v[192:195], v[144:147], v[116:119]
	v_mfma_f32_16x16x32_bf16 v[112:115], v[200:203], v[144:147], v[112:115]
	v_mfma_f32_16x16x32_bf16 v[100:103], v[192:195], v[152:155], v[100:103]
	v_mfma_f32_16x16x32_bf16 v[96:99], v[200:203], v[152:155], v[96:99]
	v_mfma_f32_16x16x32_bf16 v[84:87], v[192:195], v[160:163], v[84:87]
	v_mfma_f32_16x16x32_bf16 v[80:83], v[200:203], v[160:163], v[80:83]
	v_mfma_f32_16x16x32_bf16 v[68:71], v[192:195], v[168:171], v[68:71]
	v_mfma_f32_16x16x32_bf16 v[64:67], v[200:203], v[168:171], v[64:67]
	v_mfma_f32_16x16x32_bf16 v[116:119], v[196:199], v[148:151], v[116:119]
	v_mfma_f32_16x16x32_bf16 v[112:115], v[212:215], v[148:151], v[112:115]
	v_mfma_f32_16x16x32_bf16 v[100:103], v[196:199], v[156:159], v[100:103]
	v_mfma_f32_16x16x32_bf16 v[96:99], v[212:215], v[156:159], v[96:99]
	v_mfma_f32_16x16x32_bf16 v[84:87], v[196:199], v[164:167], v[84:87]
	v_mfma_f32_16x16x32_bf16 v[80:83], v[212:215], v[164:167], v[80:83]
	v_mfma_f32_16x16x32_bf16 v[68:71], v[196:199], v[172:175], v[68:71]
	v_mfma_f32_16x16x32_bf16 v[64:67], v[212:215], v[172:175], v[64:67]
	s_barrier
	s_setprio 0
	s_mov_b32 m0, s46
	ds_read_b128 v[144:147], v208 offset:49152
	ds_read_b128 v[148:151], v208 offset:50176
	ds_read_b128 v[152:155], v208 offset:51200
	ds_read_b128 v[156:159], v208 offset:52224
	ds_read_b128 v[160:163], v208 offset:53248
	ds_read_b128 v[164:167], v208 offset:54272
	ds_read_b128 v[168:171], v208 offset:55296
	ds_read_b128 v[172:175], v208 offset:56320
	global_load_lds_dwordx4 v182, s[100:101]
	s_mov_b32 m0, s47
	s_nop 0
	global_load_lds_dwordx4 v178, s[100:101]
	s_waitcnt vmcnt(10)
	s_waitcnt lgkmcnt(0)
	s_setprio 1
	s_barrier
	v_mfma_f32_16x16x32_bf16 v[60:63], v[128:131], v[144:147], v[60:63]
	v_mfma_f32_16x16x32_bf16 v[56:59], v[136:139], v[144:147], v[56:59]
	v_mfma_f32_16x16x32_bf16 v[44:47], v[128:131], v[152:155], v[44:47]
	v_mfma_f32_16x16x32_bf16 v[40:43], v[136:139], v[152:155], v[40:43]
	v_mfma_f32_16x16x32_bf16 v[28:31], v[128:131], v[160:163], v[28:31]
	v_mfma_f32_16x16x32_bf16 v[24:27], v[136:139], v[160:163], v[24:27]
	v_mfma_f32_16x16x32_bf16 v[12:15], v[128:131], v[168:171], v[12:15]
	v_mfma_f32_16x16x32_bf16 v[8:11], v[136:139], v[168:171], v[8:11]
	v_mfma_f32_16x16x32_bf16 v[60:63], v[132:135], v[148:151], v[60:63]
	v_mfma_f32_16x16x32_bf16 v[56:59], v[140:143], v[148:151], v[56:59]
	v_mfma_f32_16x16x32_bf16 v[44:47], v[132:135], v[156:159], v[44:47]
	v_mfma_f32_16x16x32_bf16 v[40:43], v[140:143], v[156:159], v[40:43]
	v_mfma_f32_16x16x32_bf16 v[28:31], v[132:135], v[164:167], v[28:31]
	v_mfma_f32_16x16x32_bf16 v[24:27], v[140:143], v[164:167], v[24:27]
	v_mfma_f32_16x16x32_bf16 v[12:15], v[132:135], v[172:175], v[12:15]
	v_mfma_f32_16x16x32_bf16 v[8:11], v[140:143], v[172:175], v[8:11]
	s_barrier
; DI unsigned pack2(float lo, float hi) { f32x2 v = {lo, hi}; bf16v2 r = __builtin_convertvector(v, bf16v2); return __builtin_bit_cast(unsigned, r); }
; #define PG8_STAGE(bufoff, gbase, voff) do { _Pragma("unroll") for (int _i = 0; _i < 2; ++_i) \
;     __builtin_amdgcn_global_load_lds((const unsigned*)((const char*)(gbase) + (voff)[_i]), (LAS unsigned*)(lds + (bufoff) + ldsw + _i * 8192), 16, 0, 0); } while (0)
; #define PG8_WAIT_V(n) asm volatile("s_waitcnt vmcnt(" #n ")" ::: "memory")
;   DI void operator()(const f32x4 (&acc)[2][2][4][2], const Unit& u, int wr, int wc, int fr, int fq) const {
;     const int row0 = u.pm * BM + wr * 64 + fr, col0 = u.pn * BM + wc * 32 + 8 * fq;
; #pragma unroll
;     for (int ai = 0; ai < 2; ++ai) {
;       f32x4 bv[4][2][2];
; #pragma unroll
;       for (int m = 0; m < 4; ++m)
; #pragma unroll
;         for (int bj = 0; bj < 2; ++bj) {
;           const float* bp = base + (size_t)(row0 + ai * HALF + m * 16) * 2048 + col0 + bj * HALF;
;           bv[m][bj][0] = *(const f32x4*)bp; bv[m][bj][1] = *(const f32x4*)(bp + 4);
;         }
; #pragma unroll
;       for (int m = 0; m < 4; ++m) {
;         const int row = row0 + ai * HALF + m * 16;
;         const size_t off = (size_t)row * 2048 + col0;
;         float ss = 0.f;
; #pragma unroll
;         for (int bj = 0; bj < 2; ++bj) {
;           const f32x4 v0 = acc[ai][bj][m][0] + bv[m][bj][0], v1 = acc[ai][bj][m][1] + bv[m][bj][1];
;           *(f32x4*)(C + off + bj * HALF) = v0; *(f32x4*)(C + off + bj * HALF + 4) = v1;
;           if (xb) {
;             u32x4 w; w.x = pack2(v0[0], v0[1]); w.y = pack2(v0[2], v0[3]); w.z = pack2(v1[0], v1[1]); w.w = pack2(v1[2], v1[3]);
;             *(u32x4*)(xb + off + bj * HALF) = w;
;             ss += v0[0] * v0[0] + v0[1] * v0[1] + v0[2] * v0[2] + v0[3] * v0[3] + v1[0] * v1[0] + v1[1] * v1[1] + v1[2] * v1[2] + v1[3] * v1[3];
;           }
;         }
;         if (xb) {
;           ss += __shfl_xor(ss, 16); ss += __shfl_xor(ss, 32);
;           if (fq == 0) ssq[(size_t)row * 32 + u.pn * 4 + wc] = ss;
; template <class Epi, class Sched = StaticOrder>
; DI void gemm_phase(LAS unsigned char* lds, const Gemm g, const Sched& S, const Epi& E) {
;     ...
;       PG8_BAR; PG8_WAIT_L(0); PG8_MMA(1, 0, At, B0); PG8_BAR; PG8_SCHED;
;       PG8_STAGE(PG8_SB(1, 1), b3 + hstep, voffB);
;       PG8_WAIT_V(6); PG8_BAR; PG8_MMA(1, 1, At, B1); PG8_BAR;
;     }
	s_setprio 0
	s_add_u32 s24, s24, 0x80080
	s_addc_u32 s25, s25, 0
	s_add_i32 s26, s26, s35
	s_mov_b32 m0, s26
	s_nop 0
	global_load_lds_dwordx4 v180, s[24:25]
	s_add_i32 m0, s26, 0x2000
	s_nop 0
	global_load_lds_dwordx4 v176, s[24:25]
	ds_read_b128 v[128:131], v207
	ds_read_b128 v[132:135], v207 offset:1024
	ds_read_b128 v[136:139], v207 offset:2048
	ds_read_b128 v[140:143], v207 offset:3072
	s_waitcnt vmcnt(6)
	s_setprio 1
	s_barrier
	v_mfma_f32_16x16x32_bf16 v[52:55], v[192:195], v[144:147], v[52:55]
	v_mfma_f32_16x16x32_bf16 v[48:51], v[200:203], v[144:147], v[48:51]
	v_mfma_f32_16x16x32_bf16 v[36:39], v[192:195], v[152:155], v[36:39]
	v_mfma_f32_16x16x32_bf16 v[32:35], v[200:203], v[152:155], v[32:35]
	v_mfma_f32_16x16x32_bf16 v[20:23], v[192:195], v[160:163], v[20:23]
	v_mfma_f32_16x16x32_bf16 v[16:19], v[200:203], v[160:163], v[16:19]
	v_mfma_f32_16x16x32_bf16 v[4:7], v[192:195], v[168:171], v[4:7]
	v_mfma_f32_16x16x32_bf16 v[0:3], v[200:203], v[168:171], v[0:3]
	v_mfma_f32_16x16x32_bf16 v[52:55], v[196:199], v[148:151], v[52:55]
	v_mfma_f32_16x16x32_bf16 v[48:51], v[212:215], v[148:151], v[48:51]
	v_mfma_f32_16x16x32_bf16 v[36:39], v[196:199], v[156:159], v[36:39]
	v_mfma_f32_16x16x32_bf16 v[32:35], v[212:215], v[156:159], v[32:35]
	v_mfma_f32_16x16x32_bf16 v[20:23], v[196:199], v[164:167], v[20:23]
	v_mfma_f32_16x16x32_bf16 v[16:19], v[212:215], v[164:167], v[16:19]
	v_mfma_f32_16x16x32_bf16 v[4:7], v[196:199], v[172:175], v[4:7]
	v_mfma_f32_16x16x32_bf16 v[0:3], v[212:215], v[172:175], v[0:3]
	s_add_i32 s53, s53, 2
	s_add_u32 s22, s22, 0x100
	s_addc_u32 s23, s23, 0
	s_add_u32 s45, s45, 0x100
	s_addc_u32 s52, s52, 0
	s_cmp_gt_u32 s53, 29
	s_barrier
	s_setprio 0
	s_cbranch_scc0 .LBB0_728
	s_waitcnt lgkmcnt(0)
	v_lshl_add_u32 v196, s12, 8, v204
	v_lshl_or_b32 v192, s42, 8, v206
	v_ashrrev_i32_e32 v193, 31, v192
	v_ashrrev_i32_e32 v197, 31, v196
	v_lshl_add_u64 v[194:195], v[192:193], 2, s[60:61]
	v_lshlrev_b64 v[128:129], 13, v[196:197]
	v_lshl_add_u64 v[128:129], v[194:195], 0, v[128:129]
	global_load_dwordx4 v[214:217], v[128:129], off
	global_load_dwordx4 v[218:221], v[128:129], off offset:16
	global_load_dwordx4 v[222:225], v[128:129], off offset:512
	global_load_dwordx4 v[226:229], v[128:129], off offset:528
	v_or_b32_e32 v202, 16, v196
	v_or_b32_e32 v200, 32, v196
	v_or_b32_e32 v198, 48, v196
	v_ashrrev_i32_e32 v203, 31, v202
	v_ashrrev_i32_e32 v201, 31, v200
	v_ashrrev_i32_e32 v199, 31, v198
	v_lshlrev_b64 v[128:129], 13, v[202:203]
	v_lshlrev_b64 v[130:131], 13, v[200:201]
	v_lshlrev_b64 v[132:133], 13, v[198:199]
	v_lshl_add_u64 v[128:129], v[194:195], 0, v[128:129]
	v_lshl_add_u64 v[130:131], v[194:195], 0, v[130:131]
	v_lshl_add_u64 v[132:133], v[194:195], 0, v[132:133]
	global_load_dwordx4 v[168:171], v[128:129], off offset:16
	global_load_dwordx4 v[172:175], v[128:129], off
	global_load_dwordx4 v[160:163], v[128:129], off offset:528
	global_load_dwordx4 v[164:167], v[128:129], off offset:512
	global_load_dwordx4 v[152:155], v[130:131], off offset:16
	global_load_dwordx4 v[156:159], v[130:131], off
	global_load_dwordx4 v[144:147], v[130:131], off offset:528
	global_load_dwordx4 v[148:151], v[130:131], off offset:512
	global_load_dwordx4 v[136:139], v[132:133], off offset:16
	global_load_dwordx4 v[140:143], v[132:133], off
	s_nop 0
	global_load_dwordx4 v[128:131], v[132:133], off offset:528
	s_nop 0
	global_load_dwordx4 v[132:135], v[132:133], off offset:512
	v_and_b32_e32 v212, 64, v211
	v_xor_b32_e32 v230, 16, v211
	v_add_u32_e32 v232, 64, v212
	v_xor_b32_e32 v231, 32, v211
	v_cmp_lt_i32_e32 vcc, v230, v232
	v_lshlrev_b64 v[212:213], 11, v[196:197]
	v_readlane_b32 s64, v243, 3
	v_cndmask_b32_e32 v233, v211, v230, vcc
	v_cmp_lt_i32_e32 vcc, v231, v232
	v_readlane_b32 s78, v243, 17
	v_readlane_b32 s79, v243, 18
	v_cndmask_b32_e32 v234, v211, v231, vcc
	v_lshl_add_u64 v[230:231], v[212:213], 0, v[192:193]
	v_lshlrev_b32_e32 v212, 2, v233
	v_lshl_add_u64 v[232:233], v[230:231], 2, s[78:79]
	v_lshl_add_u64 v[230:231], v[230:231], 1, s[2:3]
	s_lshl_b32 s22, s42, 2
	s_ashr_i32 s23, s22, 31
	v_readlane_b32 s65, v243, 4
	v_readlane_b32 s66, v243, 5
	v_readlane_b32 s67, v243, 6
	v_readlane_b32 s68, v243, 7
	v_readlane_b32 s69, v243, 8
	v_readlane_b32 s70, v243, 9
	v_readlane_b32 s71, v243, 10
	v_readlane_b32 s72, v243, 11
	v_readlane_b32 s73, v243, 12
	v_readlane_b32 s74, v243, 13
	v_readlane_b32 s75, v243, 14
	v_readlane_b32 s76, v243, 15
	v_readlane_b32 s77, v243, 16
	s_waitcnt vmcnt(0)
	v_pk_add_f32 v[126:127], v[126:127], v[216:217]
	v_pk_add_f32 v[124:125], v[124:125], v[214:215]
	v_pk_add_f32 v[116:117], v[116:117], v[222:223]
	v_pk_add_f32 v[122:123], v[122:123], v[220:221]
	v_pk_add_f32 v[120:121], v[120:121], v[218:219]
	v_pk_add_f32 v[214:215], v[112:113], v[226:227]
	global_store_dwordx4 v[232:233], v[124:127], off
	global_store_dwordx4 v[232:233], v[120:123], off offset:16
	v_cvt_pk_bf16_f32 v112, v124, v125
	v_mul_f32_e32 v125, v125, v125
	v_mul_f32_e32 v213, v117, v117
	v_pk_add_f32 v[118:119], v[118:119], v[224:225]
	v_fmac_f32_e32 v125, v124, v124
	v_fmac_f32_e32 v213, v116, v116
	v_fmac_f32_e32 v125, v126, v126
	v_fmac_f32_e32 v213, v118, v118
	v_fmac_f32_e32 v125, v127, v127
	v_fmac_f32_e32 v213, v119, v119
	v_fmac_f32_e32 v125, v120, v120
	v_fmac_f32_e32 v213, v214, v214
	v_pk_add_f32 v[216:217], v[114:115], v[228:229]
	v_fmac_f32_e32 v125, v121, v121
	v_fmac_f32_e32 v213, v215, v215
	v_fmac_f32_e32 v125, v122, v122
	v_fmac_f32_e32 v213, v216, v216
	v_fmac_f32_e32 v125, v123, v123
	v_fmac_f32_e32 v213, v217, v217
	v_cvt_pk_bf16_f32 v114, v120, v121
	v_add_f32_e32 v120, v125, v213
	ds_bpermute_b32 v121, v212, v120
	v_cvt_pk_bf16_f32 v113, v126, v127
	v_cvt_pk_bf16_f32 v115, v122, v123
	global_store_dwordx4 v[230:231], v[112:115], off
	global_store_dwordx4 v[232:233], v[116:119], off offset:512
	global_store_dwordx4 v[232:233], v[214:217], off offset:528
	v_cvt_pk_bf16_f32 v122, v116, v117
	s_waitcnt lgkmcnt(0)
	v_add_f32_e32 v112, v120, v121
	v_lshlrev_b32_e32 v120, 2, v234
	ds_bpermute_b32 v113, v120, v112
	v_cvt_pk_bf16_f32 v123, v118, v119
	v_cvt_pk_bf16_f32 v124, v214, v215
	v_cvt_pk_bf16_f32 v125, v216, v217
	global_store_dwordx4 v[230:231], v[122:125], off offset:256
	s_and_saveexec_b64 s[24:25], s[0:1]
	s_cbranch_execz .LBB0_731
	s_waitcnt lgkmcnt(0)
	v_add_f32_e32 v114, v112, v113
	v_lshlrev_b64 v[112:113], 7, v[196:197]
	v_lshl_add_u64 v[112:113], s[8:9], 0, v[112:113]
	v_lshl_add_u64 v[112:113], s[22:23], 2, v[112:113]
	s_lshl_b32 s12, s41, 2
	v_lshl_add_u64 v[112:113], v[112:113], 0, s[12:13]
	global_store_dword v[112:113], v114, off

; #define PG8_STAGE(bufoff, gbase, voff) do { _Pragma("unroll") for (int _i = 0; _i < 2; ++_i) \
;     __builtin_amdgcn_global_load_lds((const unsigned*)((const char*)(gbase) + (voff)[_i]), (LAS unsigned*)(lds + (bufoff) + ldsw + _i * 8192), 16, 0, 0); } while (0)
; #define PG8_LDA(dst, b, h) do { _Pragma("unroll") for (int m = 0; m < 4; ++m) _Pragma("unroll") for (int k = 0; k < 2; ++k) dst[m][k] = *(const LAS bf16x8*)(lds + PG8_SA(b, h) + aoff + m * 2048 + k * 1024); } while (0)
; #define PG8_LDB(dst, b, h) do { _Pragma("unroll") for (int n = 0; n < 2; ++n) _Pragma("unroll") for (int k = 0; k < 2; ++k) dst[n][k] = *(const LAS bf16x8*)(lds + PG8_SB(b, h) + boff + n * 2048 + k * 1024); } while (0)
; #define PG8_MMA(ai, bj, At, Bt) do { __builtin_amdgcn_s_setprio(1); _Pragma("unroll") for (int m = 0; m < 4; ++m) _Pragma("unroll") for (int n = 0; n < 2; ++n) _Pragma("unroll") for (int k = 0; k < 2; ++k) \
;     acc[ai][bj][m][n] = __builtin_amdgcn_mfma_f32_16x16x32_bf16(Bt[n][k], At[m][k], acc[ai][bj][m][n], 0, 0, 0); __builtin_amdgcn_s_setprio(0); } while (0)
; #define PG8_WAIT_V(n) asm volatile("s_waitcnt vmcnt(" #n ")" ::: "memory")
; template <class Epi, class Sched = StaticOrder>
; DI void gemm_phase(LAS unsigned char* lds, const Gemm g, const Sched& S, const Epi& E) {
;     ...
;     for (int t = 0; t < nt; t += 2) {
;       const bool last = (t == nt - 2);
;       const char* a1 = cA + (size_t)(t + 1) * kstep;
;       const char* a2 = last ? nA : cA + (size_t)(t + 2) * kstep; const char* b2 = last ? nB : cB + (size_t)(t + 2) * kstep;
;       const char* a3 = a2 + kstep; const char* b3 = b2 + kstep;
;       PG8_LDB(B0, 0, 0); PG8_SCHED; PG8_LDA(At, 0, 0); PG8_STAGE(PG8_SA(1, 1), a1 + hstep, voffA);
;       PG8_WAIT_L(8); PG8_BAR; PG8_WAIT_L(0); PG8_MMA(0, 0, At, B0); PG8_BAR; PG8_SCHED;
;       PG8_LDB(B1, 0, 1); PG8_STAGE(PG8_SB(0, 0), b2, voffB);
;       PG8_BAR; PG8_WAIT_L(0); PG8_MMA(0, 1, At, B1); PG8_BAR;
;       PG8_LDA(At, 0, 1); PG8_STAGE(PG8_SA(0, 0), a2, voffA);
;       PG8_BAR; PG8_WAIT_L(0); PG8_MMA(1, 0, At, B0); PG8_BAR; PG8_SCHED;
;       PG8_STAGE(PG8_SB(0, 1), b2 + hstep, voffB);
;       PG8_WAIT_V(6); PG8_BAR; PG8_MMA(1, 1, At, B1); PG8_BAR;
;       PG8_LDB(B0, 1, 0); PG8_SCHED; PG8_LDA(At, 1, 0); PG8_STAGE(PG8_SA(0, 1), a2 + hstep, voffA);
;       PG8_WAIT_L(8); PG8_BAR; PG8_WAIT_L(0); PG8_MMA(0, 0, At, B0); PG8_BAR; PG8_SCHED;
.LBB0_811:
	s_add_i32 m0, s62, 0xc000
	ds_read_b128 v[80:83], v202
	ds_read_b128 v[84:87], v202 offset:1024
	ds_read_b128 v[92:95], v202 offset:2048
	ds_read_b128 v[96:99], v202 offset:3072
	ds_read_b128 v[180:183], v202 offset:4096
	ds_read_b128 v[184:187], v202 offset:5120
	ds_read_b128 v[188:191], v202 offset:6144
	ds_read_b128 v[192:195], v202 offset:7168
	global_load_lds_dwordx4 v170, s[14:15]
	s_add_i32 m0, s62, 0xe000
	s_nop 0
	global_load_lds_dwordx4 v172, s[14:15]
	s_waitcnt lgkmcnt(0)
	s_setprio 1
	s_barrier
	v_mfma_f32_16x16x32_bf16 v[156:159], v[64:67], v[80:83], v[156:159]
	v_mfma_f32_16x16x32_bf16 v[144:147], v[72:75], v[80:83], v[144:147]
	v_mfma_f32_16x16x32_bf16 v[140:143], v[64:67], v[92:95], v[140:143]
	v_mfma_f32_16x16x32_bf16 v[132:135], v[72:75], v[92:95], v[132:135]
	v_mfma_f32_16x16x32_bf16 v[124:127], v[64:67], v[180:183], v[124:127]
	v_mfma_f32_16x16x32_bf16 v[116:119], v[72:75], v[180:183], v[116:119]
	v_mfma_f32_16x16x32_bf16 v[112:115], v[64:67], v[188:191], v[112:115]
	v_mfma_f32_16x16x32_bf16 v[108:111], v[72:75], v[188:191], v[108:111]
	v_mfma_f32_16x16x32_bf16 v[156:159], v[68:71], v[84:87], v[156:159]
	v_mfma_f32_16x16x32_bf16 v[144:147], v[76:79], v[84:87], v[144:147]
	v_mfma_f32_16x16x32_bf16 v[140:143], v[68:71], v[96:99], v[140:143]
	v_mfma_f32_16x16x32_bf16 v[132:135], v[76:79], v[96:99], v[132:135]
	v_mfma_f32_16x16x32_bf16 v[124:127], v[68:71], v[184:187], v[124:127]
	v_mfma_f32_16x16x32_bf16 v[116:119], v[76:79], v[184:187], v[116:119]
	v_mfma_f32_16x16x32_bf16 v[112:115], v[68:71], v[192:195], v[112:115]
	v_mfma_f32_16x16x32_bf16 v[108:111], v[76:79], v[192:195], v[108:111]
	s_barrier
	s_setprio 0
	ds_read_b128 v[206:209], v203
	ds_read_b128 v[212:215], v203 offset:1024
	ds_read_b128 v[216:219], v203 offset:2048
	ds_read_b128 v[220:223], v203 offset:3072
	s_add_u32 s46, s14, 0xfff80080
	s_addc_u32 s47, s15, -1
	s_cmp_eq_u32 s52, 28
	s_cselect_b32 s49, s37, s47
	s_cselect_b32 s48, s42, s46
	s_cselect_b32 s47, s35, s45
	s_cselect_b32 s46, s43, s44
	s_add_i32 s53, s72, s60
	s_add_u32 s98, s46, 0x80
	s_addc_u32 s99, s47, 0
	s_add_u32 s100, s48, 0x80
	s_addc_u32 s101, s49, 0
	s_mov_b32 m0, s53
	s_nop 0
	global_load_lds_dwordx4 v164, s[46:47]
	s_add_i32 m0, s53, 0x2000
	s_nop 0
	global_load_lds_dwordx4 v160, s[46:47]
	s_waitcnt lgkmcnt(0)
	s_setprio 1
	s_barrier
	v_mfma_f32_16x16x32_bf16 v[152:155], v[206:209], v[80:83], v[152:155]
	v_mfma_f32_16x16x32_bf16 v[80:83], v[216:219], v[80:83], v[148:151]
	v_mfma_f32_16x16x32_bf16 v[152:155], v[212:215], v[84:87], v[152:155]
	v_mfma_f32_16x16x32_bf16 v[80:83], v[220:223], v[84:87], v[80:83]
	v_mfma_f32_16x16x32_bf16 v[84:87], v[206:209], v[92:95], v[136:139]
	v_mfma_f32_16x16x32_bf16 v[92:95], v[216:219], v[92:95], v[128:131]
	v_mfma_f32_16x16x32_bf16 v[104:107], v[216:219], v[180:183], v[104:107]
	v_mfma_f32_16x16x32_bf16 v[100:103], v[206:209], v[188:191], v[100:103]
	v_mfma_f32_16x16x32_bf16 v[88:91], v[216:219], v[188:191], v[88:91]
	v_mfma_f32_16x16x32_bf16 v[84:87], v[212:215], v[96:99], v[84:87]
	v_mfma_f32_16x16x32_bf16 v[92:95], v[220:223], v[96:99], v[92:95]
	v_mfma_f32_16x16x32_bf16 v[96:99], v[206:209], v[180:183], v[120:123]
	v_mfma_f32_16x16x32_bf16 v[104:107], v[220:223], v[184:187], v[104:107]
	v_mfma_f32_16x16x32_bf16 v[100:103], v[212:215], v[192:195], v[100:103]
	v_mfma_f32_16x16x32_bf16 v[88:91], v[220:223], v[192:195], v[88:91]
	v_mfma_f32_16x16x32_bf16 v[96:99], v[212:215], v[184:187], v[96:99]
	s_barrier
	s_setprio 0
	s_mov_b32 m0, s62
	ds_read_b128 v[120:123], v202 offset:16384
	ds_read_b128 v[128:131], v202 offset:17408
	ds_read_b128 v[136:139], v202 offset:18432
	ds_read_b128 v[148:151], v202 offset:19456
	ds_read_b128 v[180:183], v202 offset:20480
	ds_read_b128 v[184:187], v202 offset:21504
	ds_read_b128 v[188:191], v202 offset:22528
	ds_read_b128 v[192:195], v202 offset:23552
	global_load_lds_dwordx4 v166, s[48:49]
	s_mov_b32 m0, s63
	s_nop 0
	global_load_lds_dwordx4 v162, s[48:49]
	s_waitcnt vmcnt(10)
	s_waitcnt lgkmcnt(0)
	s_setprio 1
	s_barrier
	v_mfma_f32_16x16x32_bf16 v[60:63], v[64:67], v[120:123], v[60:63]
	v_mfma_f32_16x16x32_bf16 v[48:51], v[72:75], v[120:123], v[48:51]
	v_mfma_f32_16x16x32_bf16 v[44:47], v[64:67], v[136:139], v[44:47]
	v_mfma_f32_16x16x32_bf16 v[36:39], v[72:75], v[136:139], v[36:39]
	v_mfma_f32_16x16x32_bf16 v[28:31], v[64:67], v[180:183], v[28:31]
	v_mfma_f32_16x16x32_bf16 v[20:23], v[72:75], v[180:183], v[20:23]
	v_mfma_f32_16x16x32_bf16 v[16:19], v[64:67], v[188:191], v[16:19]
	v_mfma_f32_16x16x32_bf16 v[12:15], v[72:75], v[188:191], v[12:15]
	v_mfma_f32_16x16x32_bf16 v[60:63], v[68:71], v[128:131], v[60:63]
	v_mfma_f32_16x16x32_bf16 v[48:51], v[76:79], v[128:131], v[48:51]
	v_mfma_f32_16x16x32_bf16 v[44:47], v[68:71], v[148:151], v[44:47]
	v_mfma_f32_16x16x32_bf16 v[36:39], v[76:79], v[148:151], v[36:39]
	v_mfma_f32_16x16x32_bf16 v[28:31], v[68:71], v[184:187], v[28:31]
	v_mfma_f32_16x16x32_bf16 v[20:23], v[76:79], v[184:187], v[20:23]
	v_mfma_f32_16x16x32_bf16 v[16:19], v[68:71], v[192:195], v[16:19]
	v_mfma_f32_16x16x32_bf16 v[12:15], v[76:79], v[192:195], v[12:15]
	s_barrier
	s_setprio 0
	s_add_u32 s54, s46, 0x80000
	s_addc_u32 s55, s47, 0
	s_add_i32 s53, s73, s60
	s_mov_b32 m0, s53
	s_nop 0
	global_load_lds_dwordx4 v164, s[54:55]
	s_add_i32 m0, s53, 0x2000
	s_nop 0
	global_load_lds_dwordx4 v160, s[54:55]
	s_add_i32 s53, 0, 0x18000
	v_add_u32_e32 v76, s53, v198
	ds_read_b128 v[64:67], v76
	ds_read_b128 v[68:71], v76 offset:1024
	ds_read_b128 v[72:75], v76 offset:2048
	ds_read_b128 v[76:79], v76 offset:3072
	s_waitcnt vmcnt(6)
	s_setprio 1
	s_barrier
; #define PG8_STAGE(bufoff, gbase, voff) do { _Pragma("unroll") for (int _i = 0; _i < 2; ++_i) \
;     __builtin_amdgcn_global_load_lds((const unsigned*)((const char*)(gbase) + (voff)[_i]), (LAS unsigned*)(lds + (bufoff) + ldsw + _i * 8192), 16, 0, 0); } while (0)
; #define PG8_LDA(dst, b, h) do { _Pragma("unroll") for (int m = 0; m < 4; ++m) _Pragma("unroll") for (int k = 0; k < 2; ++k) dst[m][k] = *(const LAS bf16x8*)(lds + PG8_SA(b, h) + aoff + m * 2048 + k * 1024); } while (0)
; #define PG8_LDB(dst, b, h) do { _Pragma("unroll") for (int n = 0; n < 2; ++n) _Pragma("unroll") for (int k = 0; k < 2; ++k) dst[n][k] = *(const LAS bf16x8*)(lds + PG8_SB(b, h) + boff + n * 2048 + k * 1024); } while (0)
; #define PG8_MMA(ai, bj, At, Bt) do { __builtin_amdgcn_s_setprio(1); _Pragma("unroll") for (int m = 0; m < 4; ++m) _Pragma("unroll") for (int n = 0; n < 2; ++n) _Pragma("unroll") for (int k = 0; k < 2; ++k) \
;     acc[ai][bj][m][n] = __builtin_amdgcn_mfma_f32_16x16x32_bf16(Bt[n][k], At[m][k], acc[ai][bj][m][n], 0, 0, 0); __builtin_amdgcn_s_setprio(0); } while (0)
; #define PG8_WAIT_V(n) asm volatile("s_waitcnt vmcnt(" #n ")" ::: "memory")
; #define PG8_WAIT_L(n) asm volatile("s_waitcnt lgkmcnt(" #n ")" ::: "memory")
; #define PG8_BAR __builtin_amdgcn_s_barrier()
; #define PG8_SCHED __builtin_amdgcn_sched_barrier(0)
; template <class Epi, class Sched = StaticOrder>
; DI void gemm_phase(LAS unsigned char* lds, const Gemm g, const Sched& S, const Epi& E) {
;     ...
;       PG8_BAR; PG8_WAIT_L(0); PG8_MMA(1, 0, At, B0); PG8_BAR; PG8_SCHED;
;       PG8_STAGE(PG8_SB(0, 1), b2 + hstep, voffB);
;       PG8_WAIT_V(6); PG8_BAR; PG8_MMA(1, 1, At, B1); PG8_BAR;
;       PG8_LDB(B0, 1, 0); PG8_SCHED; PG8_LDA(At, 1, 0); PG8_STAGE(PG8_SA(0, 1), a2 + hstep, voffA);
;       PG8_WAIT_L(8); PG8_BAR; PG8_WAIT_L(0); PG8_MMA(0, 0, At, B0); PG8_BAR; PG8_SCHED;
;       PG8_LDB(B1, 1, 1); PG8_STAGE(PG8_SB(1, 0), b3, voffB);
;       PG8_BAR; PG8_WAIT_L(0); PG8_MMA(0, 1, At, B1); PG8_BAR;
;       PG8_LDA(At, 1, 1); PG8_STAGE(PG8_SA(1, 0), a3, voffA);
;       PG8_BAR; PG8_WAIT_L(0); PG8_MMA(1, 0, At, B0); PG8_BAR; PG8_SCHED;
	v_mfma_f32_16x16x32_bf16 v[56:59], v[206:209], v[120:123], v[56:59]
	v_mfma_f32_16x16x32_bf16 v[52:55], v[216:219], v[120:123], v[52:55]
	v_mfma_f32_16x16x32_bf16 v[40:43], v[206:209], v[136:139], v[40:43]
	v_mfma_f32_16x16x32_bf16 v[32:35], v[216:219], v[136:139], v[32:35]
	v_mfma_f32_16x16x32_bf16 v[24:27], v[206:209], v[180:183], v[24:27]
	v_mfma_f32_16x16x32_bf16 v[8:11], v[216:219], v[180:183], v[8:11]
	v_mfma_f32_16x16x32_bf16 v[4:7], v[206:209], v[188:191], v[4:7]
	v_mfma_f32_16x16x32_bf16 v[0:3], v[216:219], v[188:191], v[0:3]
	v_mfma_f32_16x16x32_bf16 v[56:59], v[212:215], v[128:131], v[56:59]
	v_mfma_f32_16x16x32_bf16 v[52:55], v[220:223], v[128:131], v[52:55]
	v_mfma_f32_16x16x32_bf16 v[40:43], v[212:215], v[148:151], v[40:43]
	v_mfma_f32_16x16x32_bf16 v[32:35], v[220:223], v[148:151], v[32:35]
	v_mfma_f32_16x16x32_bf16 v[24:27], v[212:215], v[184:187], v[24:27]
	v_mfma_f32_16x16x32_bf16 v[8:11], v[220:223], v[184:187], v[8:11]
	v_mfma_f32_16x16x32_bf16 v[4:7], v[212:215], v[192:195], v[4:7]
	v_mfma_f32_16x16x32_bf16 v[0:3], v[220:223], v[192:195], v[0:3]
	s_barrier
	s_setprio 0
	s_add_u32 s48, s48, 0x80000
	s_addc_u32 s49, s49, 0
	s_mov_b32 m0, s64
	ds_read_b128 v[120:123], v202 offset:32768
	ds_read_b128 v[128:131], v202 offset:33792
	ds_read_b128 v[180:183], v202 offset:34816
	ds_read_b128 v[184:187], v202 offset:35840
	ds_read_b128 v[188:191], v202 offset:36864
	ds_read_b128 v[192:195], v202 offset:37888
	ds_read_b128 v[206:209], v202 offset:38912
	ds_read_b128 v[212:215], v202 offset:39936
	global_load_lds_dwordx4 v166, s[48:49]
	s_mov_b32 m0, s65
	s_nop 0
	global_load_lds_dwordx4 v162, s[48:49]
	s_waitcnt lgkmcnt(0)
	s_setprio 1
	s_barrier
	v_mfma_f32_16x16x32_bf16 v[136:139], v[64:67], v[120:123], v[156:159]
	v_mfma_f32_16x16x32_bf16 v[156:159], v[68:71], v[128:131], v[136:139]
	v_mfma_f32_16x16x32_bf16 v[136:139], v[72:75], v[120:123], v[144:147]
	v_mfma_f32_16x16x32_bf16 v[144:147], v[76:79], v[128:131], v[136:139]
	v_mfma_f32_16x16x32_bf16 v[136:139], v[64:67], v[180:183], v[140:143]
	v_mfma_f32_16x16x32_bf16 v[132:135], v[72:75], v[180:183], v[132:135]
	v_mfma_f32_16x16x32_bf16 v[124:127], v[64:67], v[188:191], v[124:127]
	v_mfma_f32_16x16x32_bf16 v[116:119], v[72:75], v[188:191], v[116:119]
	v_mfma_f32_16x16x32_bf16 v[112:115], v[64:67], v[206:209], v[112:115]
	v_mfma_f32_16x16x32_bf16 v[108:111], v[72:75], v[206:209], v[108:111]
	v_mfma_f32_16x16x32_bf16 v[140:143], v[68:71], v[184:187], v[136:139]
	v_mfma_f32_16x16x32_bf16 v[132:135], v[76:79], v[184:187], v[132:135]
	v_mfma_f32_16x16x32_bf16 v[124:127], v[68:71], v[192:195], v[124:127]
	v_mfma_f32_16x16x32_bf16 v[116:119], v[76:79], v[192:195], v[116:119]
	v_mfma_f32_16x16x32_bf16 v[112:115], v[68:71], v[212:215], v[112:115]
	v_mfma_f32_16x16x32_bf16 v[108:111], v[76:79], v[212:215], v[108:111]
	s_barrier
	s_setprio 0
	s_add_i32 s48, 0, 0x1c000
	v_add_u32_e32 v136, s48, v198
	s_add_i32 s49, s53, s60
	ds_read_b128 v[216:219], v136
	ds_read_b128 v[220:223], v136 offset:1024
	ds_read_b128 v[224:227], v136 offset:2048
	ds_read_b128 v[228:231], v136 offset:3072
	s_mov_b32 m0, s49
	s_nop 0
	global_load_lds_dwordx4 v164, s[98:99]
	s_add_i32 m0, s49, 0x2000
	s_nop 0
	global_load_lds_dwordx4 v160, s[98:99]
	s_waitcnt lgkmcnt(0)
	s_setprio 1
	s_barrier
	v_mfma_f32_16x16x32_bf16 v[80:83], v[224:227], v[120:123], v[80:83]
	v_mfma_f32_16x16x32_bf16 v[136:139], v[216:219], v[120:123], v[152:155]
	v_mfma_f32_16x16x32_bf16 v[148:151], v[228:231], v[128:131], v[80:83]
	v_mfma_f32_16x16x32_bf16 v[80:83], v[216:219], v[180:183], v[84:87]
	v_mfma_f32_16x16x32_bf16 v[152:155], v[220:223], v[128:131], v[136:139]
	v_mfma_f32_16x16x32_bf16 v[136:139], v[220:223], v[184:187], v[80:83]
	v_mfma_f32_16x16x32_bf16 v[80:83], v[224:227], v[180:183], v[92:95]
	v_mfma_f32_16x16x32_bf16 v[128:131], v[228:231], v[184:187], v[80:83]
	v_mfma_f32_16x16x32_bf16 v[80:83], v[216:219], v[188:191], v[96:99]
	v_mfma_f32_16x16x32_bf16 v[120:123], v[220:223], v[192:195], v[80:83]
	v_mfma_f32_16x16x32_bf16 v[80:83], v[224:227], v[188:191], v[104:107]
	v_mfma_f32_16x16x32_bf16 v[104:107], v[228:231], v[192:195], v[80:83]
	v_mfma_f32_16x16x32_bf16 v[80:83], v[216:219], v[206:209], v[100:103]
	v_mfma_f32_16x16x32_bf16 v[100:103], v[220:223], v[212:215], v[80:83]
	v_mfma_f32_16x16x32_bf16 v[80:83], v[224:227], v[206:209], v[88:91]
	v_mfma_f32_16x16x32_bf16 v[88:91], v[228:231], v[212:215], v[80:83]
	s_barrier
	s_setprio 0
	s_mov_b32 m0, s67
	s_nop 2
	ds_read_b128 v[80:83], v202 offset:49152
	ds_read_b128 v[84:87], v202 offset:50176
	ds_read_b128 v[92:95], v202 offset:51200
	ds_read_b128 v[96:99], v202 offset:52224
	ds_read_b128 v[180:183], v202 offset:53248
	ds_read_b128 v[184:187], v202 offset:54272
	ds_read_b128 v[188:191], v202 offset:55296
	ds_read_b128 v[192:195], v202 offset:56320
	global_load_lds_dwordx4 v166, s[100:101]
	s_mov_b32 m0, s68
	s_nop 0
	global_load_lds_dwordx4 v162, s[100:101]
	s_waitcnt vmcnt(10)
	s_waitcnt lgkmcnt(0)
	s_setprio 1
	s_barrier
	v_mfma_f32_16x16x32_bf16 v[60:63], v[64:67], v[80:83], v[60:63]
	v_mfma_f32_16x16x32_bf16 v[48:51], v[72:75], v[80:83], v[48:51]
	v_mfma_f32_16x16x32_bf16 v[44:47], v[64:67], v[92:95], v[44:47]
	v_mfma_f32_16x16x32_bf16 v[36:39], v[72:75], v[92:95], v[36:39]
	v_mfma_f32_16x16x32_bf16 v[28:31], v[64:67], v[180:183], v[28:31]
	v_mfma_f32_16x16x32_bf16 v[20:23], v[72:75], v[180:183], v[20:23]
	v_mfma_f32_16x16x32_bf16 v[16:19], v[64:67], v[188:191], v[16:19]
	v_mfma_f32_16x16x32_bf16 v[12:15], v[72:75], v[188:191], v[12:15]
	v_mfma_f32_16x16x32_bf16 v[60:63], v[68:71], v[84:87], v[60:63]
	v_mfma_f32_16x16x32_bf16 v[48:51], v[76:79], v[84:87], v[48:51]
	v_mfma_f32_16x16x32_bf16 v[44:47], v[68:71], v[96:99], v[44:47]
	v_mfma_f32_16x16x32_bf16 v[36:39], v[76:79], v[96:99], v[36:39]
	v_mfma_f32_16x16x32_bf16 v[28:31], v[68:71], v[184:187], v[28:31]
	v_mfma_f32_16x16x32_bf16 v[20:23], v[76:79], v[184:187], v[20:23]
	v_mfma_f32_16x16x32_bf16 v[16:19], v[68:71], v[192:195], v[16:19]
	v_mfma_f32_16x16x32_bf16 v[12:15], v[76:79], v[192:195], v[12:15]
	s_barrier
; #define PG8_STAGE(bufoff, gbase, voff) do { _Pragma("unroll") for (int _i = 0; _i < 2; ++_i) \
;     __builtin_amdgcn_global_load_lds((const unsigned*)((const char*)(gbase) + (voff)[_i]), (LAS unsigned*)(lds + (bufoff) + ldsw + _i * 8192), 16, 0, 0); } while (0)
; #define PG8_MMA(ai, bj, At, Bt) do { __builtin_amdgcn_s_setprio(1); _Pragma("unroll") for (int m = 0; m < 4; ++m) _Pragma("unroll") for (int n = 0; n < 2; ++n) _Pragma("unroll") for (int k = 0; k < 2; ++k) \
;     acc[ai][bj][m][n] = __builtin_amdgcn_mfma_f32_16x16x32_bf16(Bt[n][k], At[m][k], acc[ai][bj][m][n], 0, 0, 0); __builtin_amdgcn_s_setprio(0); } while (0)
; #define PG8_WAIT_V(n) asm volatile("s_waitcnt vmcnt(" #n ")" ::: "memory")
; #define PG8_WAIT_L(n) asm volatile("s_waitcnt lgkmcnt(" #n ")" ::: "memory")
; #define PG8_BAR __builtin_amdgcn_s_barrier()
; #define PG8_SCHED __builtin_amdgcn_sched_barrier(0)
;   DI void operator()(const f32x4 (&acc)[2][2][4][2], const Unit& u, int wr, int wc, int fr, int fq) const {
;     const int col = u.pn * 128 + wc * 32 + 8 * fq;
;     float w0[8], w1[8], w2[8], bb[8];
; #pragma unroll
;     for (int e = 0; e < 8; ++e) { w0[e] = cw[col + e]; w1[e] = cw[5632 + col + e]; w2[e] = cw[2 * 5632 + col + e]; bb[e] = cb[col + e]; }
; #pragma unroll
;     for (int ai = 0; ai < 2; ++ai) {
;       const int row0 = u.pm * BM + ai * HALF + wr * 64, span = row0 >> 6;
;       float rsv[4];
; #pragma unroll
;       for (int m = 0; m < 4; ++m) rsv[m] = row_rstd(ssq, row0 + 16 * m + fr, fq);
; template <class Epi, class Sched = StaticOrder>
; DI void gemm_phase(LAS unsigned char* lds, const Gemm g, const Sched& S, const Epi& E) {
;     ...
;       PG8_BAR; PG8_WAIT_L(0); PG8_MMA(1, 0, At, B0); PG8_BAR; PG8_SCHED;
;       PG8_STAGE(PG8_SB(1, 1), b3 + hstep, voffB);
;       PG8_WAIT_V(6); PG8_BAR; PG8_MMA(1, 1, At, B1); PG8_BAR;
;     }
	s_setprio 0
	s_add_u32 s46, s46, 0x80080
	s_addc_u32 s47, s47, 0
	s_add_i32 s48, s48, s60
	s_mov_b32 m0, s48
	s_nop 0
	global_load_lds_dwordx4 v164, s[46:47]
	s_add_i32 m0, s48, 0x2000
	s_nop 0
	global_load_lds_dwordx4 v160, s[46:47]
	ds_read_b128 v[64:67], v201
	ds_read_b128 v[68:71], v201 offset:1024
	ds_read_b128 v[72:75], v201 offset:2048
	ds_read_b128 v[76:79], v201 offset:3072
	s_waitcnt vmcnt(6)
	s_setprio 1
	s_barrier
	v_mfma_f32_16x16x32_bf16 v[56:59], v[216:219], v[80:83], v[56:59]
	v_mfma_f32_16x16x32_bf16 v[52:55], v[224:227], v[80:83], v[52:55]
	v_mfma_f32_16x16x32_bf16 v[40:43], v[216:219], v[92:95], v[40:43]
	v_mfma_f32_16x16x32_bf16 v[32:35], v[224:227], v[92:95], v[32:35]
	v_mfma_f32_16x16x32_bf16 v[24:27], v[216:219], v[180:183], v[24:27]
	v_mfma_f32_16x16x32_bf16 v[8:11], v[224:227], v[180:183], v[8:11]
	v_mfma_f32_16x16x32_bf16 v[4:7], v[216:219], v[188:191], v[4:7]
	v_mfma_f32_16x16x32_bf16 v[0:3], v[224:227], v[188:191], v[0:3]
	v_mfma_f32_16x16x32_bf16 v[56:59], v[220:223], v[84:87], v[56:59]
	v_mfma_f32_16x16x32_bf16 v[52:55], v[228:231], v[84:87], v[52:55]
	v_mfma_f32_16x16x32_bf16 v[40:43], v[220:223], v[96:99], v[40:43]
	v_mfma_f32_16x16x32_bf16 v[32:35], v[228:231], v[96:99], v[32:35]
	v_mfma_f32_16x16x32_bf16 v[24:27], v[220:223], v[184:187], v[24:27]
	v_mfma_f32_16x16x32_bf16 v[8:11], v[228:231], v[184:187], v[8:11]
	v_mfma_f32_16x16x32_bf16 v[4:7], v[220:223], v[192:195], v[4:7]
	v_mfma_f32_16x16x32_bf16 v[0:3], v[228:231], v[192:195], v[0:3]
	s_add_i32 s52, s52, 2
	s_add_u32 s14, s14, 0x100
	s_addc_u32 s15, s15, 0
	s_add_u32 s44, s44, 0x100
	s_addc_u32 s45, s45, 0
	s_cmp_gt_u32 s52, 29
	s_barrier
	s_setprio 0
	s_cbranch_scc0 .LBB0_811
	s_waitcnt lgkmcnt(0)
	s_lshl_b32 s35, s12, 8
	s_add_i32 s35, s35, s66
	v_or_b32_e32 v190, s35, v179
	v_ashrrev_i32_e32 v191, 31, v190
	v_lshlrev_b64 v[64:65], 7, v[190:191]
	v_or_b32_e32 v188, 16, v190
	v_lshl_add_u64 v[64:65], v[168:169], 0, v[64:65]
	v_ashrrev_i32_e32 v189, 31, v188
	global_load_dwordx4 v[192:195], v[64:65], off
	global_load_dwordx4 v[206:209], v[64:65], off offset:16
	v_lshlrev_b64 v[64:65], 7, v[188:189]
	v_lshl_add_u64 v[64:65], v[168:169], 0, v[64:65]
	global_load_dwordx4 v[212:215], v[64:65], off
	global_load_dwordx4 v[216:219], v[64:65], off offset:16
	v_or_b32_e32 v186, 32, v190
	v_ashrrev_i32_e32 v187, 31, v186
	v_lshlrev_b64 v[64:65], 7, v[186:187]
	v_or_b32_e32 v184, 48, v190
	v_lshl_add_u64 v[64:65], v[168:169], 0, v[64:65]
	v_ashrrev_i32_e32 v185, 31, v184
	global_load_dwordx4 v[220:223], v[64:65], off
	global_load_dwordx4 v[224:227], v[64:65], off offset:16
	v_lshlrev_b64 v[64:65], 7, v[184:185]
	v_lshl_add_u64 v[64:65], v[168:169], 0, v[64:65]
	global_load_dwordx4 v[228:231], v[64:65], off
	global_load_dwordx4 v[232:235], v[64:65], off offset:16
	v_lshl_or_b32 v180, s13, 7, v200
	v_and_b32_e32 v65, 64, v204
	v_xor_b32_e32 v64, 16, v204
	v_ashrrev_i32_e32 v181, 31, v180
	v_add_u32_e32 v65, 64, v65
	v_readlane_b32 s44, v243, 3
	v_xor_b32_e32 v66, 32, v204
	v_lshlrev_b64 v[182:183], 2, v[180:181]
	v_cmp_lt_i32_e32 vcc, v64, v65
	v_readlane_b32 s52, v243, 11
	v_readlane_b32 s53, v243, 12
	v_cndmask_b32_e32 v64, v204, v64, vcc
	v_cmp_lt_i32_e32 vcc, v66, v65
	v_lshl_add_u64 v[92:93], s[52:53], 0, v[182:183]
	v_readlane_b32 s54, v243, 13
	v_cndmask_b32_e32 v65, v204, v66, vcc
	v_add_co_u32_e32 v94, vcc, 0x5000, v92
	v_readlane_b32 s55, v243, 14
	s_nop 0
	v_addc_co_u32_e32 v95, vcc, 0, v93, vcc
	v_add_co_u32_e32 v96, vcc, 0xb000, v92
	v_lshl_add_u64 v[72:73], s[54:55], 0, v[182:183]
	v_lshl_add_u64 v[74:75], v[92:93], 0, s[26:27]
	v_lshl_add_u64 v[76:77], v[92:93], 0, s[28:29]
	v_addc_co_u32_e32 v97, vcc, 0, v93, vcc
	v_lshlrev_b32_e32 v187, 2, v64
	v_lshlrev_b32_e32 v185, 2, v65
	global_load_dwordx4 v[64:67], v[92:93], off offset:16
	global_load_dwordx4 v[80:83], v[92:93], off
	global_load_dwordx4 v[68:71], v[72:73], off offset:16
	global_load_dwordx4 v[84:87], v[72:73], off
	s_nop 0
	global_load_dwordx4 v[72:75], v[74:75], off offset:16
	s_nop 0
	global_load_dwordx4 v[76:79], v[76:77], off offset:16
	s_nop 0
	global_load_dwordx4 v[92:95], v[94:95], off offset:2048
	s_nop 0
	global_load_dwordx4 v[96:99], v[96:97], off
	v_mov_b32_e32 v211, 0
	v_mov_b32_e32 v205, 0
	v_readlane_b32 s45, v243, 4
	v_readlane_b32 s46, v243, 5
	v_readlane_b32 s47, v243, 6
	v_readlane_b32 s48, v243, 7
	v_readlane_b32 s49, v243, 8
	v_readlane_b32 s50, v243, 9
	v_readlane_b32 s51, v243, 10
	v_readlane_b32 s56, v243, 15
	v_readlane_b32 s57, v243, 16
	v_readlane_b32 s58, v243, 17
	v_readlane_b32 s59, v243, 18
	s_waitcnt vmcnt(0)
	v_mov_b32_e32 v196, v192
	v_mov_b32_e32 v197, v206
	v_mov_b32_e32 v206, v193
	v_mov_b32_e32 v192, v194
	v_mov_b32_e32 v193, v208
	v_mov_b32_e32 v208, v195
	v_pk_add_f32 v[194:195], v[196:197], v[206:207]
	v_pk_add_f32 v[192:193], v[192:193], v[208:209]
	v_mov_b32_e32 v196, v212
	v_mov_b32_e32 v197, v216
	v_mov_b32_e32 v216, v213
	v_mov_b32_e32 v206, v214
	v_mov_b32_e32 v207, v218
	v_mov_b32_e32 v218, v215
	v_pk_add_f32 v[192:193], v[194:195], v[192:193]
	v_pk_add_f32 v[194:195], v[196:197], v[216:217]
	v_pk_add_f32 v[196:197], v[206:207], v[218:219]
	v_mov_b32_e32 v208, v220
	v_pk_add_f32 v[194:195], v[194:195], v[196:197]
	v_mov_b32_e32 v197, v192
	v_mov_b32_e32 v196, v194
	v_mov_b32_e32 v192, v195
	v_pk_add_f32 v[192:193], v[196:197], v[192:193]
	ds_bpermute_b32 v195, v187, v193
	ds_bpermute_b32 v194, v187, v192
	v_mov_b32_e32 v209, v224
	v_mov_b32_e32 v224, v221
	v_mov_b32_e32 v212, v222
	v_mov_b32_e32 v213, v226
	s_waitcnt lgkmcnt(0)
; DI unsigned pack2(float lo, float hi) { f32x2 v = {lo, hi}; bf16v2 r = __builtin_convertvector(v, bf16v2); return __builtin_bit_cast(unsigned, r); }
; DI float silu_f(float x) { return x * sigmoid_f(x); }
; DI float dpp_ror1(float v) { return __int_as_float(__builtin_amdgcn_update_dpp(0, __float_as_int(v), 0x121, 0xf, 0xf, false)); }
; DI float dpp_ror2(float v) { return __int_as_float(__builtin_amdgcn_update_dpp(0, __float_as_int(v), 0x122, 0xf, 0xf, false)); }
;   DI void operator()(const f32x4 (&acc)[2][2][4][2], const Unit& u, int wr, int wc, int fr, int fq) const {
;     ...
;       for (int m = 0; m < 4; ++m) rsv[m] = row_rstd(ssq, row0 + 16 * m + fr, fq);
;       float p1[8], p2[8];
; #pragma unroll
;       for (int e = 0; e < 8; ++e) { p1[e] = 0.f; p2[e] = 0.f; }
; #pragma unroll
;       for (int m = 0; m < 4; ++m) {
;         float g[8], uu[8], a[8];
;         const float rs = rsv[m];
; #pragma unroll
;         for (int e = 0; e < 4; ++e) { g[e] = acc[ai][0][m][0][e] * rs; g[4 + e] = acc[ai][0][m][1][e] * rs; uu[e] = acc[ai][1][m][0][e] * rs; uu[4 + e] = acc[ai][1][m][1][e] * rs; }
; #pragma unroll
;         for (int e = 0; e < 8; ++e) {
;           const float x1 = dpp_ror1(g[e]), x2 = dpp_ror2(g[e]);
;           const float pr1 = (fr == 0) ? p1[e] : x1, pr2 = (fr < 2) ? p2[e] : x2;
;           a[e] = w2[e] * g[e] + w1[e] * pr1 + w0[e] * pr2 + bb[e];
;           p1[e] = x1; p2[e] = x2;
;         }
;         if (m == 0 && fr < 2) {
;           float* ha = headA + (size_t)(span * 2 + fr) * 5632 + col; float* hu = headU + (size_t)(span * 2 + fr) * 5632 + col;
;           *(f32x4*)ha = (f32x4){a[0], a[1], a[2], a[3]}; *(f32x4*)(ha + 4) = (f32x4){a[4], a[5], a[6], a[7]};
;           *(f32x4*)hu = (f32x4){uu[0], uu[1], uu[2], uu[3]}; *(f32x4*)(hu + 4) = (f32x4){uu[4], uu[5], uu[6], uu[7]};
;         } else {
;           u32x4 w;
;           w.x = pack2(silu_f(a[0]) * uu[0], silu_f(a[1]) * uu[1]);
;           w.y = pack2(silu_f(a[2]) * uu[2], silu_f(a[3]) * uu[3]);
;           w.z = pack2(silu_f(a[4]) * uu[4], silu_f(a[5]) * uu[5]);
;           w.w = pack2(silu_f(a[6]) * uu[6], silu_f(a[7]) * uu[7]);
;           *(u32x4*)(H + (size_t)(row0 + 16 * m + fr) * 5632 + col) = w;
	v_pk_add_f32 v[192:193], v[192:193], v[194:195]
	ds_bpermute_b32 v195, v185, v193
	ds_bpermute_b32 v194, v185, v192
	v_mov_b32_e32 v226, v223
	v_mov_b32_e32 v196, v228
	v_mov_b32_e32 v197, v232
	v_mov_b32_e32 v232, v229
	s_waitcnt lgkmcnt(0)
	v_pk_add_f32 v[192:193], v[192:193], v[194:195]
	v_mov_b32_e32 v206, v230
	v_pk_fma_f32 v[192:193], v[192:193], s[30:31], v[178:179] op_sel_hi:[1,0,0]
	v_mov_b32_e32 v207, v234
	v_mul_f32_e32 v189, 0x4b800000, v193
	v_cmp_gt_f32_e64 s[12:13], s74, v193
	v_mov_b32_e32 v234, v231
	v_pk_add_f32 v[208:209], v[208:209], v[224:225]
	v_cndmask_b32_e64 v189, v193, v189, s[12:13]
	v_rsq_f32_e32 v189, v189
	v_pk_add_f32 v[212:213], v[212:213], v[226:227]
	v_pk_add_f32 v[196:197], v[196:197], v[232:233]
	v_pk_add_f32 v[194:195], v[206:207], v[234:235]
	v_mul_f32_e32 v191, 0x45800000, v189
	v_cndmask_b32_e64 v220, v189, v191, s[12:13]
	v_pk_add_f32 v[208:209], v[208:209], v[212:213]
	v_pk_add_f32 v[194:195], v[196:197], v[194:195]
	v_pk_mul_f32 v[156:157], v[156:157], v[220:221] op_sel_hi:[1,0]
	v_mov_b32_e32 v216, 0
	v_mov_b32_e32 v218, 0
	v_mov_b32_e32 v196, v194
	v_mov_b32_e32 v197, v208
	v_mov_b32_e32 v208, v195
	v_mov_b32_dpp v216, v156 row_ror:1 row_mask:0xf bank_mask:0xf
	v_mov_b32_dpp v218, v157 row_ror:1 row_mask:0xf bank_mask:0xf
	v_pk_add_f32 v[194:195], v[196:197], v[208:209]
	v_cndmask_b32_e64 v207, v218, 0, s[0:1]
	v_cndmask_b32_e64 v206, v216, 0, s[0:1]
	v_pk_mul_f32 v[158:159], v[158:159], v[220:221] op_sel_hi:[1,0]
	v_mov_b32_e32 v212, 0
	v_mov_b32_e32 v214, 0
	ds_bpermute_b32 v197, v187, v195
	ds_bpermute_b32 v196, v187, v194
	v_mov_b32_e32 v215, 0
	v_mov_b32_e32 v217, 0
	v_pk_mul_f32 v[206:207], v[92:93], v[206:207]
	v_mov_b32_dpp v212, v158 row_ror:1 row_mask:0xf bank_mask:0xf
	v_mov_b32_dpp v214, v159 row_ror:1 row_mask:0xf bank_mask:0xf
	v_mov_b32_dpp v215, v156 row_ror:2 row_mask:0xf bank_mask:0xf
	v_mov_b32_dpp v217, v157 row_ror:2 row_mask:0xf bank_mask:0xf
	v_pk_fma_f32 v[156:157], v[96:97], v[156:157], v[206:207]
	v_mov_b32_e32 v213, 0
	v_cndmask_b32_e64 v207, v214, 0, s[0:1]
	v_cndmask_b32_e64 v206, v212, 0, s[0:1]
	v_cndmask_b32_e64 v209, v217, 0, s[4:5]
	v_cndmask_b32_e64 v208, v215, 0, s[4:5]
	v_mov_b32_dpp v211, v158 row_ror:2 row_mask:0xf bank_mask:0xf
	v_mov_b32_dpp v213, v159 row_ror:2 row_mask:0xf bank_mask:0xf
	v_pk_mul_f32 v[206:207], v[94:95], v[206:207]
	v_pk_fma_f32 v[156:157], v[80:81], v[208:209], v[156:157]
	v_cndmask_b32_e64 v209, v213, 0, s[4:5]
	v_cndmask_b32_e64 v208, v211, 0, s[4:5]
	v_pk_fma_f32 v[158:159], v[98:99], v[158:159], v[206:207]
	v_pk_mul_f32 v[144:145], v[144:145], v[220:221] op_sel_hi:[1,0]
	v_pk_fma_f32 v[158:159], v[82:83], v[208:209], v[158:159]
	v_mov_b32_e32 v207, 0
	v_mov_b32_e32 v209, 0
	v_pk_mul_f32 v[146:147], v[146:147], v[220:221] op_sel_hi:[1,0]
	v_mov_b32_e32 v191, 0
	s_waitcnt lgkmcnt(0)
	v_pk_add_f32 v[194:195], v[194:195], v[196:197]
	v_mov_b32_dpp v207, v144 row_ror:1 row_mask:0xf bank_mask:0xf
	v_mov_b32_dpp v209, v145 row_ror:1 row_mask:0xf bank_mask:0xf
	v_mov_b32_dpp v191, v146 row_ror:1 row_mask:0xf bank_mask:0xf
	v_mov_b32_dpp v205, v147 row_ror:1 row_mask:0xf bank_mask:0xf
	ds_bpermute_b32 v197, v185, v195
	ds_bpermute_b32 v196, v185, v194
	v_pk_mul_f32 v[152:153], v[152:153], v[220:221] op_sel_hi:[1,0]
	v_pk_mul_f32 v[148:149], v[148:149], v[220:221] op_sel_hi:[1,0]
	v_pk_mul_f32 v[154:155], v[154:155], v[220:221] op_sel_hi:[1,0]
	v_pk_mul_f32 v[150:151], v[150:151], v[220:221] op_sel_hi:[1,0]
	v_mov_b32_e32 v206, 0
	v_mov_b32_e32 v208, 0
	v_cndmask_b32_e64 v223, v209, 0, s[0:1]
	v_cndmask_b32_e64 v222, v207, 0, s[0:1]
	v_mov_b32_e32 v189, 0
	v_mov_b32_e32 v193, 0
	v_cndmask_b32_e64 v221, v205, 0, s[0:1]
	v_cndmask_b32_e64 v220, v191, 0, s[0:1]
	v_mov_b32_dpp v206, v144 row_ror:2 row_mask:0xf bank_mask:0xf
	v_mov_b32_dpp v208, v145 row_ror:2 row_mask:0xf bank_mask:0xf
	v_pk_mul_f32 v[222:223], v[72:73], v[222:223]
	v_mov_b32_dpp v189, v146 row_ror:2 row_mask:0xf bank_mask:0xf
	v_mov_b32_dpp v193, v147 row_ror:2 row_mask:0xf bank_mask:0xf
	v_pk_mul_f32 v[220:221], v[74:75], v[220:221]
	v_cndmask_b32_e64 v225, v208, 0, s[4:5]
	v_cndmask_b32_e64 v224, v206, 0, s[4:5]
	v_pk_fma_f32 v[144:145], v[76:77], v[144:145], v[222:223]
	v_cndmask_b32_e64 v223, v193, 0, s[4:5]
	v_cndmask_b32_e64 v222, v189, 0, s[4:5]
	v_pk_fma_f32 v[146:147], v[78:79], v[146:147], v[220:221]
	v_pk_fma_f32 v[144:145], v[64:65], v[224:225], v[144:145]
	v_pk_fma_f32 v[146:147], v[66:67], v[222:223], v[146:147]
	v_cmp_gt_f32_e32 vcc, s74, v192
	v_pk_add_f32 v[156:157], v[84:85], v[156:157]
	v_pk_add_f32 v[158:159], v[86:87], v[158:159]
	v_pk_add_f32 v[144:145], v[68:69], v[144:145]
	v_pk_add_f32 v[146:147], v[70:71], v[146:147]
	s_and_saveexec_b64 s[12:13], s[10:11]
	s_xor_b64 s[12:13], exec, s[12:13]
	s_cbranch_execz .LBB0_814
	v_mul_f32_e32 v219, 0xbfb8aa3b, v156
	v_exp_f32_e32 v219, v219
	v_mul_f32_e32 v220, 0xbfb8aa3b, v157
	v_exp_f32_e32 v220, v220
	v_mul_f32_e32 v222, 0xbfb8aa3b, v159
	v_add_f32_e32 v219, 1.0, v219
	v_exp_f32_e32 v223, v222
	v_add_f32_e32 v221, 1.0, v220
	v_rcp_f32_e32 v220, v219
	v_mul_f32_e32 v219, 0xbfb8aa3b, v158
	v_exp_f32_e32 v219, v219
	v_rcp_f32_e32 v221, v221
	v_add_f32_e32 v219, 1.0, v219
	v_rcp_f32_e32 v222, v219
	v_add_f32_e32 v219, 1.0, v223
	v_rcp_f32_e32 v223, v219
	v_pk_mul_f32 v[156:157], v[156:157], v[220:221]
	s_nop 0
	v_pk_mul_f32 v[152:153], v[152:153], v[156:157]
	v_pk_mul_f32 v[156:157], v[158:159], v[222:223]
	v_cvt_pk_bf16_f32 v152, v152, v153
	v_mul_f32_e32 v153, 0xbfb8aa3b, v144
	v_pk_mul_f32 v[154:155], v[154:155], v[156:157]
	v_exp_f32_e32 v156, v153
	v_mul_f32_e32 v153, 0xbfb8aa3b, v145
	v_exp_f32_e32 v157, v153
	v_cvt_pk_bf16_f32 v153, v154, v155
	v_add_f32_e32 v154, 1.0, v156
	v_mul_f32_e32 v156, 0xbfb8aa3b, v146
	v_add_f32_e32 v155, 1.0, v157
	v_mul_f32_e32 v157, 0xbfb8aa3b, v147
	v_exp_f32_e32 v156, v156
	v_exp_f32_e32 v157, v157
	v_rcp_f32_e32 v154, v154
	v_rcp_f32_e32 v155, v155
	v_add_f32_e32 v156, 1.0, v156
	v_add_f32_e32 v157, 1.0, v157
	v_rcp_f32_e32 v156, v156
	v_rcp_f32_e32 v157, v157
	v_pk_mul_f32 v[144:145], v[144:145], v[154:155]
	s_nop 0
	v_pk_mul_f32 v[144:145], v[148:149], v[144:145]
	s_nop 0
	v_cvt_pk_bf16_f32 v154, v144, v145
	v_pk_mul_f32 v[144:145], v[146:147], v[156:157]
	s_nop 0
	v_pk_mul_f32 v[144:145], v[150:151], v[144:145]
	s_nop 0
	v_cvt_pk_bf16_f32 v155, v144, v145
	v_mov_b64_e32 v[144:145], s[16:17]
	v_mad_i64_i32 v[144:145], s[14:15], v190, s75, v[144:145]
	v_lshl_add_u64 v[144:145], v[180:181], 1, v[144:145]
	global_store_dwordx4 v[144:145], v[152:155], off

; #define PG8_STAGE(bufoff, gbase, voff) do { _Pragma("unroll") for (int _i = 0; _i < 2; ++_i) \
;     __builtin_amdgcn_global_load_lds((const unsigned*)((const char*)(gbase) + (voff)[_i]), (LAS unsigned*)(lds + (bufoff) + ldsw + _i * 8192), 16, 0, 0); } while (0)
; #define PG8_LDA(dst, b, h) do { _Pragma("unroll") for (int m = 0; m < 4; ++m) _Pragma("unroll") for (int k = 0; k < 2; ++k) dst[m][k] = *(const LAS bf16x8*)(lds + PG8_SA(b, h) + aoff + m * 2048 + k * 1024); } while (0)
; #define PG8_LDB(dst, b, h) do { _Pragma("unroll") for (int n = 0; n < 2; ++n) _Pragma("unroll") for (int k = 0; k < 2; ++k) dst[n][k] = *(const LAS bf16x8*)(lds + PG8_SB(b, h) + boff + n * 2048 + k * 1024); } while (0)
; #define PG8_MMA(ai, bj, At, Bt) do { __builtin_amdgcn_s_setprio(1); _Pragma("unroll") for (int m = 0; m < 4; ++m) _Pragma("unroll") for (int n = 0; n < 2; ++n) _Pragma("unroll") for (int k = 0; k < 2; ++k) \
;     acc[ai][bj][m][n] = __builtin_amdgcn_mfma_f32_16x16x32_bf16(Bt[n][k], At[m][k], acc[ai][bj][m][n], 0, 0, 0); __builtin_amdgcn_s_setprio(0); } while (0)
; #define PG8_WAIT_V(n) asm volatile("s_waitcnt vmcnt(" #n ")" ::: "memory")
; template <class Epi, class Sched = StaticOrder>
; DI void gemm_phase(LAS unsigned char* lds, const Gemm g, const Sched& S, const Epi& E) {
;     ...
;     for (int t = 0; t < nt; t += 2) {
;       const bool last = (t == nt - 2);
;       const char* a1 = cA + (size_t)(t + 1) * kstep;
;       const char* a2 = last ? nA : cA + (size_t)(t + 2) * kstep; const char* b2 = last ? nB : cB + (size_t)(t + 2) * kstep;
;       const char* a3 = a2 + kstep; const char* b3 = b2 + kstep;
;       PG8_LDB(B0, 0, 0); PG8_SCHED; PG8_LDA(At, 0, 0); PG8_STAGE(PG8_SA(1, 1), a1 + hstep, voffA);
;       PG8_WAIT_L(8); PG8_BAR; PG8_WAIT_L(0); PG8_MMA(0, 0, At, B0); PG8_BAR; PG8_SCHED;
;       PG8_LDB(B1, 0, 1); PG8_STAGE(PG8_SB(0, 0), b2, voffB);
;       PG8_BAR; PG8_WAIT_L(0); PG8_MMA(0, 1, At, B1); PG8_BAR;
;       PG8_LDA(At, 0, 1); PG8_STAGE(PG8_SA(0, 0), a2, voffA);
;       PG8_BAR; PG8_WAIT_L(0); PG8_MMA(1, 0, At, B0); PG8_BAR; PG8_SCHED;
;       PG8_STAGE(PG8_SB(0, 1), b2 + hstep, voffB);
;       PG8_WAIT_V(6); PG8_BAR; PG8_MMA(1, 1, At, B1); PG8_BAR;
;       PG8_LDB(B0, 1, 0); PG8_SCHED; PG8_LDA(At, 1, 0); PG8_STAGE(PG8_SA(0, 1), a2 + hstep, voffA);
;       PG8_WAIT_L(8); PG8_BAR; PG8_WAIT_L(0); PG8_MMA(0, 0, At, B0); PG8_BAR; PG8_SCHED;
.LBB0_961:
	s_add_i32 m0, s31, 0xc000
	ds_read_b128 v[144:147], v215
	ds_read_b128 v[148:151], v215 offset:1024
	ds_read_b128 v[152:155], v215 offset:2048
	ds_read_b128 v[156:159], v215 offset:3072
	ds_read_b128 v[160:163], v215 offset:4096
	ds_read_b128 v[164:167], v215 offset:5120
	ds_read_b128 v[168:171], v215 offset:6144
	ds_read_b128 v[172:175], v215 offset:7168
	global_load_lds_dwordx4 v184, s[18:19]
	s_add_i32 m0, s31, 0xe000
	s_nop 0
	global_load_lds_dwordx4 v186, s[18:19]
	s_waitcnt lgkmcnt(0)
	s_setprio 1
	s_barrier
	v_mfma_f32_16x16x32_bf16 v[124:127], v[128:131], v[144:147], v[124:127]
	v_mfma_f32_16x16x32_bf16 v[120:123], v[136:139], v[144:147], v[120:123]
	v_mfma_f32_16x16x32_bf16 v[108:111], v[128:131], v[152:155], v[108:111]
	v_mfma_f32_16x16x32_bf16 v[104:107], v[136:139], v[152:155], v[104:107]
	v_mfma_f32_16x16x32_bf16 v[92:95], v[128:131], v[160:163], v[92:95]
	v_mfma_f32_16x16x32_bf16 v[88:91], v[136:139], v[160:163], v[88:91]
	v_mfma_f32_16x16x32_bf16 v[76:79], v[128:131], v[168:171], v[76:79]
	v_mfma_f32_16x16x32_bf16 v[72:75], v[136:139], v[168:171], v[72:75]
	v_mfma_f32_16x16x32_bf16 v[124:127], v[132:135], v[148:151], v[124:127]
	v_mfma_f32_16x16x32_bf16 v[120:123], v[140:143], v[148:151], v[120:123]
	v_mfma_f32_16x16x32_bf16 v[108:111], v[132:135], v[156:159], v[108:111]
	v_mfma_f32_16x16x32_bf16 v[104:107], v[140:143], v[156:159], v[104:107]
	v_mfma_f32_16x16x32_bf16 v[92:95], v[132:135], v[164:167], v[92:95]
	v_mfma_f32_16x16x32_bf16 v[88:91], v[140:143], v[164:167], v[88:91]
	v_mfma_f32_16x16x32_bf16 v[76:79], v[132:135], v[172:175], v[76:79]
	v_mfma_f32_16x16x32_bf16 v[72:75], v[140:143], v[172:175], v[72:75]
	s_barrier
	s_setprio 0
	ds_read_b128 v[192:195], v216
	ds_read_b128 v[196:199], v216 offset:1024
	ds_read_b128 v[200:203], v216 offset:2048
	ds_read_b128 v[204:207], v216 offset:3072
	s_add_u32 s20, s18, 0xffea0080
	s_addc_u32 s21, s19, -1
	s_cmpk_eq_i32 s44, 0x54
	s_cselect_b32 s23, s5, s21
	s_cselect_b32 s22, s4, s20
	s_cselect_b32 s21, s7, s43
	s_cselect_b32 s20, s6, s42
	s_add_i32 s45, s46, s30
	s_add_u32 s98, s20, 0x80
	s_addc_u32 s99, s21, 0
	s_add_u32 s100, s22, 0x80
	s_addc_u32 s101, s23, 0
	s_mov_b32 m0, s45
	s_nop 0
	global_load_lds_dwordx4 v178, s[20:21]
	s_add_i32 m0, s45, 0x2000
	s_nop 0
	global_load_lds_dwordx4 v182, s[20:21]
	s_waitcnt lgkmcnt(0)
	s_setprio 1
	s_barrier
	v_mfma_f32_16x16x32_bf16 v[116:119], v[192:195], v[144:147], v[116:119]
	v_mfma_f32_16x16x32_bf16 v[112:115], v[200:203], v[144:147], v[112:115]
	v_mfma_f32_16x16x32_bf16 v[100:103], v[192:195], v[152:155], v[100:103]
	v_mfma_f32_16x16x32_bf16 v[96:99], v[200:203], v[152:155], v[96:99]
	v_mfma_f32_16x16x32_bf16 v[84:87], v[192:195], v[160:163], v[84:87]
	v_mfma_f32_16x16x32_bf16 v[80:83], v[200:203], v[160:163], v[80:83]
	v_mfma_f32_16x16x32_bf16 v[68:71], v[192:195], v[168:171], v[68:71]
	v_mfma_f32_16x16x32_bf16 v[64:67], v[200:203], v[168:171], v[64:67]
	v_mfma_f32_16x16x32_bf16 v[116:119], v[196:199], v[148:151], v[116:119]
	v_mfma_f32_16x16x32_bf16 v[112:115], v[204:207], v[148:151], v[112:115]
	v_mfma_f32_16x16x32_bf16 v[100:103], v[196:199], v[156:159], v[100:103]
	v_mfma_f32_16x16x32_bf16 v[96:99], v[204:207], v[156:159], v[96:99]
	v_mfma_f32_16x16x32_bf16 v[84:87], v[196:199], v[164:167], v[84:87]
	v_mfma_f32_16x16x32_bf16 v[80:83], v[204:207], v[164:167], v[80:83]
	v_mfma_f32_16x16x32_bf16 v[68:71], v[196:199], v[172:175], v[68:71]
	v_mfma_f32_16x16x32_bf16 v[64:67], v[204:207], v[172:175], v[64:67]
	s_barrier
	s_setprio 0
	s_mov_b32 m0, s31
	ds_read_b128 v[144:147], v215 offset:16384
	ds_read_b128 v[148:151], v215 offset:17408
	ds_read_b128 v[152:155], v215 offset:18432
	ds_read_b128 v[156:159], v215 offset:19456
	ds_read_b128 v[160:163], v215 offset:20480
	ds_read_b128 v[164:167], v215 offset:21504
	ds_read_b128 v[168:171], v215 offset:22528
	ds_read_b128 v[172:175], v215 offset:23552
	global_load_lds_dwordx4 v176, s[22:23]
	s_mov_b32 m0, s33
	s_nop 0
	global_load_lds_dwordx4 v180, s[22:23]
	s_waitcnt vmcnt(10)
	s_waitcnt lgkmcnt(0)
	s_setprio 1
	s_barrier
	v_mfma_f32_16x16x32_bf16 v[60:63], v[128:131], v[144:147], v[60:63]
	v_mfma_f32_16x16x32_bf16 v[56:59], v[136:139], v[144:147], v[56:59]
	v_mfma_f32_16x16x32_bf16 v[44:47], v[128:131], v[152:155], v[44:47]
	v_mfma_f32_16x16x32_bf16 v[40:43], v[136:139], v[152:155], v[40:43]
	v_mfma_f32_16x16x32_bf16 v[28:31], v[128:131], v[160:163], v[28:31]
	v_mfma_f32_16x16x32_bf16 v[24:27], v[136:139], v[160:163], v[24:27]
	v_mfma_f32_16x16x32_bf16 v[12:15], v[128:131], v[168:171], v[12:15]
	v_mfma_f32_16x16x32_bf16 v[8:11], v[136:139], v[168:171], v[8:11]
	v_mfma_f32_16x16x32_bf16 v[60:63], v[132:135], v[148:151], v[60:63]
	v_mfma_f32_16x16x32_bf16 v[56:59], v[140:143], v[148:151], v[56:59]
	v_mfma_f32_16x16x32_bf16 v[44:47], v[132:135], v[156:159], v[44:47]
	v_mfma_f32_16x16x32_bf16 v[40:43], v[140:143], v[156:159], v[40:43]
	v_mfma_f32_16x16x32_bf16 v[28:31], v[132:135], v[164:167], v[28:31]
	v_mfma_f32_16x16x32_bf16 v[24:27], v[140:143], v[164:167], v[24:27]
	v_mfma_f32_16x16x32_bf16 v[12:15], v[132:135], v[172:175], v[12:15]
	v_mfma_f32_16x16x32_bf16 v[8:11], v[140:143], v[172:175], v[8:11]
	s_barrier
	s_setprio 0
	s_add_u32 s52, s20, 0x160000
	s_addc_u32 s53, s21, 0
	s_add_i32 s45, s47, s30
	s_mov_b32 m0, s45
	s_nop 0
	global_load_lds_dwordx4 v178, s[52:53]
	s_add_i32 m0, s45, 0x2000
	s_nop 0
	global_load_lds_dwordx4 v182, s[52:53]
	s_add_i32 s45, 0, 0x18000
	v_add_u32_e32 v140, s45, v212
	ds_read_b128 v[128:131], v140
	ds_read_b128 v[132:135], v140 offset:1024
	ds_read_b128 v[136:139], v140 offset:2048
	ds_read_b128 v[140:143], v140 offset:3072
	s_waitcnt vmcnt(6)
	s_setprio 1
	s_barrier
; #define PG8_STAGE(bufoff, gbase, voff) do { _Pragma("unroll") for (int _i = 0; _i < 2; ++_i) \
;     __builtin_amdgcn_global_load_lds((const unsigned*)((const char*)(gbase) + (voff)[_i]), (LAS unsigned*)(lds + (bufoff) + ldsw + _i * 8192), 16, 0, 0); } while (0)
; #define PG8_LDA(dst, b, h) do { _Pragma("unroll") for (int m = 0; m < 4; ++m) _Pragma("unroll") for (int k = 0; k < 2; ++k) dst[m][k] = *(const LAS bf16x8*)(lds + PG8_SA(b, h) + aoff + m * 2048 + k * 1024); } while (0)
; #define PG8_LDB(dst, b, h) do { _Pragma("unroll") for (int n = 0; n < 2; ++n) _Pragma("unroll") for (int k = 0; k < 2; ++k) dst[n][k] = *(const LAS bf16x8*)(lds + PG8_SB(b, h) + boff + n * 2048 + k * 1024); } while (0)
; #define PG8_MMA(ai, bj, At, Bt) do { __builtin_amdgcn_s_setprio(1); _Pragma("unroll") for (int m = 0; m < 4; ++m) _Pragma("unroll") for (int n = 0; n < 2; ++n) _Pragma("unroll") for (int k = 0; k < 2; ++k) \
;     acc[ai][bj][m][n] = __builtin_amdgcn_mfma_f32_16x16x32_bf16(Bt[n][k], At[m][k], acc[ai][bj][m][n], 0, 0, 0); __builtin_amdgcn_s_setprio(0); } while (0)
; #define PG8_WAIT_V(n) asm volatile("s_waitcnt vmcnt(" #n ")" ::: "memory")
; #define PG8_WAIT_L(n) asm volatile("s_waitcnt lgkmcnt(" #n ")" ::: "memory")
; #define PG8_BAR __builtin_amdgcn_s_barrier()
; #define PG8_SCHED __builtin_amdgcn_sched_barrier(0)
; template <class Epi, class Sched = StaticOrder>
; DI void gemm_phase(LAS unsigned char* lds, const Gemm g, const Sched& S, const Epi& E) {
;     ...
;       PG8_BAR; PG8_WAIT_L(0); PG8_MMA(1, 0, At, B0); PG8_BAR; PG8_SCHED;
;       PG8_STAGE(PG8_SB(0, 1), b2 + hstep, voffB);
;       PG8_WAIT_V(6); PG8_BAR; PG8_MMA(1, 1, At, B1); PG8_BAR;
;       PG8_LDB(B0, 1, 0); PG8_SCHED; PG8_LDA(At, 1, 0); PG8_STAGE(PG8_SA(0, 1), a2 + hstep, voffA);
;       PG8_WAIT_L(8); PG8_BAR; PG8_WAIT_L(0); PG8_MMA(0, 0, At, B0); PG8_BAR; PG8_SCHED;
;       PG8_LDB(B1, 1, 1); PG8_STAGE(PG8_SB(1, 0), b3, voffB);
;       PG8_BAR; PG8_WAIT_L(0); PG8_MMA(0, 1, At, B1); PG8_BAR;
;       PG8_LDA(At, 1, 1); PG8_STAGE(PG8_SA(1, 0), a3, voffA);
;       PG8_BAR; PG8_WAIT_L(0); PG8_MMA(1, 0, At, B0); PG8_BAR; PG8_SCHED;
	v_mfma_f32_16x16x32_bf16 v[52:55], v[192:195], v[144:147], v[52:55]
	v_mfma_f32_16x16x32_bf16 v[48:51], v[200:203], v[144:147], v[48:51]
	v_mfma_f32_16x16x32_bf16 v[36:39], v[192:195], v[152:155], v[36:39]
	v_mfma_f32_16x16x32_bf16 v[32:35], v[200:203], v[152:155], v[32:35]
	v_mfma_f32_16x16x32_bf16 v[20:23], v[192:195], v[160:163], v[20:23]
	v_mfma_f32_16x16x32_bf16 v[16:19], v[200:203], v[160:163], v[16:19]
	v_mfma_f32_16x16x32_bf16 v[4:7], v[192:195], v[168:171], v[4:7]
	v_mfma_f32_16x16x32_bf16 v[0:3], v[200:203], v[168:171], v[0:3]
	v_mfma_f32_16x16x32_bf16 v[52:55], v[196:199], v[148:151], v[52:55]
	v_mfma_f32_16x16x32_bf16 v[48:51], v[204:207], v[148:151], v[48:51]
	v_mfma_f32_16x16x32_bf16 v[36:39], v[196:199], v[156:159], v[36:39]
	v_mfma_f32_16x16x32_bf16 v[32:35], v[204:207], v[156:159], v[32:35]
	v_mfma_f32_16x16x32_bf16 v[20:23], v[196:199], v[164:167], v[20:23]
	v_mfma_f32_16x16x32_bf16 v[16:19], v[204:207], v[164:167], v[16:19]
	v_mfma_f32_16x16x32_bf16 v[4:7], v[196:199], v[172:175], v[4:7]
	v_mfma_f32_16x16x32_bf16 v[0:3], v[204:207], v[172:175], v[0:3]
	s_barrier
	s_setprio 0
	s_add_u32 s22, s22, 0x160000
	s_addc_u32 s23, s23, 0
	s_mov_b32 m0, s34
	ds_read_b128 v[144:147], v215 offset:32768
	ds_read_b128 v[148:151], v215 offset:33792
	ds_read_b128 v[152:155], v215 offset:34816
	ds_read_b128 v[156:159], v215 offset:35840
	ds_read_b128 v[160:163], v215 offset:36864
	ds_read_b128 v[164:167], v215 offset:37888
	ds_read_b128 v[168:171], v215 offset:38912
	ds_read_b128 v[172:175], v215 offset:39936
	global_load_lds_dwordx4 v176, s[22:23]
	s_mov_b32 m0, s35
	s_nop 0
	global_load_lds_dwordx4 v180, s[22:23]
	s_waitcnt lgkmcnt(0)
	s_setprio 1
	s_barrier
	v_mfma_f32_16x16x32_bf16 v[124:127], v[128:131], v[144:147], v[124:127]
	v_mfma_f32_16x16x32_bf16 v[120:123], v[136:139], v[144:147], v[120:123]
	v_mfma_f32_16x16x32_bf16 v[108:111], v[128:131], v[152:155], v[108:111]
	v_mfma_f32_16x16x32_bf16 v[104:107], v[136:139], v[152:155], v[104:107]
	v_mfma_f32_16x16x32_bf16 v[92:95], v[128:131], v[160:163], v[92:95]
	v_mfma_f32_16x16x32_bf16 v[88:91], v[136:139], v[160:163], v[88:91]
	v_mfma_f32_16x16x32_bf16 v[76:79], v[128:131], v[168:171], v[76:79]
	v_mfma_f32_16x16x32_bf16 v[72:75], v[136:139], v[168:171], v[72:75]
	v_mfma_f32_16x16x32_bf16 v[124:127], v[132:135], v[148:151], v[124:127]
	v_mfma_f32_16x16x32_bf16 v[120:123], v[140:143], v[148:151], v[120:123]
	v_mfma_f32_16x16x32_bf16 v[108:111], v[132:135], v[156:159], v[108:111]
	v_mfma_f32_16x16x32_bf16 v[104:107], v[140:143], v[156:159], v[104:107]
	v_mfma_f32_16x16x32_bf16 v[92:95], v[132:135], v[164:167], v[92:95]
	v_mfma_f32_16x16x32_bf16 v[88:91], v[140:143], v[164:167], v[88:91]
	v_mfma_f32_16x16x32_bf16 v[76:79], v[132:135], v[172:175], v[76:79]
	v_mfma_f32_16x16x32_bf16 v[72:75], v[140:143], v[172:175], v[72:75]
	s_barrier
	s_setprio 0
	s_add_i32 s22, 0, 0x1c000
	s_add_i32 s23, s45, s30
	v_add_u32_e32 v204, s22, v212
	s_mov_b32 m0, s23
	ds_read_b128 v[192:195], v204
	ds_read_b128 v[196:199], v204 offset:1024
	ds_read_b128 v[200:203], v204 offset:2048
	ds_read_b128 v[204:207], v204 offset:3072
	global_load_lds_dwordx4 v178, s[98:99]
	s_add_i32 m0, s23, 0x2000
	s_nop 0
	global_load_lds_dwordx4 v182, s[98:99]
	s_waitcnt lgkmcnt(0)
	s_setprio 1
	s_barrier
	v_mfma_f32_16x16x32_bf16 v[116:119], v[192:195], v[144:147], v[116:119]
	v_mfma_f32_16x16x32_bf16 v[112:115], v[200:203], v[144:147], v[112:115]
	v_mfma_f32_16x16x32_bf16 v[100:103], v[192:195], v[152:155], v[100:103]
	v_mfma_f32_16x16x32_bf16 v[96:99], v[200:203], v[152:155], v[96:99]
	v_mfma_f32_16x16x32_bf16 v[84:87], v[192:195], v[160:163], v[84:87]
	v_mfma_f32_16x16x32_bf16 v[80:83], v[200:203], v[160:163], v[80:83]
	v_mfma_f32_16x16x32_bf16 v[68:71], v[192:195], v[168:171], v[68:71]
	v_mfma_f32_16x16x32_bf16 v[64:67], v[200:203], v[168:171], v[64:67]
	v_mfma_f32_16x16x32_bf16 v[116:119], v[196:199], v[148:151], v[116:119]
	v_mfma_f32_16x16x32_bf16 v[112:115], v[204:207], v[148:151], v[112:115]
	v_mfma_f32_16x16x32_bf16 v[100:103], v[196:199], v[156:159], v[100:103]
	v_mfma_f32_16x16x32_bf16 v[96:99], v[204:207], v[156:159], v[96:99]
	v_mfma_f32_16x16x32_bf16 v[84:87], v[196:199], v[164:167], v[84:87]
	v_mfma_f32_16x16x32_bf16 v[80:83], v[204:207], v[164:167], v[80:83]
	v_mfma_f32_16x16x32_bf16 v[68:71], v[196:199], v[172:175], v[68:71]
	v_mfma_f32_16x16x32_bf16 v[64:67], v[204:207], v[172:175], v[64:67]
	s_barrier
	s_setprio 0
	s_mov_b32 m0, s37
	ds_read_b128 v[144:147], v215 offset:49152
	ds_read_b128 v[148:151], v215 offset:50176
	ds_read_b128 v[152:155], v215 offset:51200
	ds_read_b128 v[156:159], v215 offset:52224
	ds_read_b128 v[160:163], v215 offset:53248
	ds_read_b128 v[164:167], v215 offset:54272
	ds_read_b128 v[168:171], v215 offset:55296
	ds_read_b128 v[172:175], v215 offset:56320
	global_load_lds_dwordx4 v176, s[100:101]
	s_mov_b32 m0, s38
	s_nop 0
	global_load_lds_dwordx4 v180, s[100:101]
	s_waitcnt vmcnt(10)
	s_waitcnt lgkmcnt(0)
	s_setprio 1
	s_barrier
	v_mfma_f32_16x16x32_bf16 v[60:63], v[128:131], v[144:147], v[60:63]
	v_mfma_f32_16x16x32_bf16 v[56:59], v[136:139], v[144:147], v[56:59]
	v_mfma_f32_16x16x32_bf16 v[44:47], v[128:131], v[152:155], v[44:47]
	v_mfma_f32_16x16x32_bf16 v[40:43], v[136:139], v[152:155], v[40:43]
	v_mfma_f32_16x16x32_bf16 v[28:31], v[128:131], v[160:163], v[28:31]
	v_mfma_f32_16x16x32_bf16 v[24:27], v[136:139], v[160:163], v[24:27]
	v_mfma_f32_16x16x32_bf16 v[12:15], v[128:131], v[168:171], v[12:15]
	v_mfma_f32_16x16x32_bf16 v[8:11], v[136:139], v[168:171], v[8:11]
	v_mfma_f32_16x16x32_bf16 v[60:63], v[132:135], v[148:151], v[60:63]
	v_mfma_f32_16x16x32_bf16 v[56:59], v[140:143], v[148:151], v[56:59]
	v_mfma_f32_16x16x32_bf16 v[44:47], v[132:135], v[156:159], v[44:47]
	v_mfma_f32_16x16x32_bf16 v[40:43], v[140:143], v[156:159], v[40:43]
	v_mfma_f32_16x16x32_bf16 v[28:31], v[132:135], v[164:167], v[28:31]
	v_mfma_f32_16x16x32_bf16 v[24:27], v[140:143], v[164:167], v[24:27]
	v_mfma_f32_16x16x32_bf16 v[12:15], v[132:135], v[172:175], v[12:15]
	v_mfma_f32_16x16x32_bf16 v[8:11], v[140:143], v[172:175], v[8:11]
	s_barrier
; DI unsigned pack2(float lo, float hi) { f32x2 v = {lo, hi}; bf16v2 r = __builtin_convertvector(v, bf16v2); return __builtin_bit_cast(unsigned, r); }
; #define PG8_STAGE(bufoff, gbase, voff) do { _Pragma("unroll") for (int _i = 0; _i < 2; ++_i) \
;     __builtin_amdgcn_global_load_lds((const unsigned*)((const char*)(gbase) + (voff)[_i]), (LAS unsigned*)(lds + (bufoff) + ldsw + _i * 8192), 16, 0, 0); } while (0)
; #define PG8_WAIT_V(n) asm volatile("s_waitcnt vmcnt(" #n ")" ::: "memory")
;   DI void operator()(const f32x4 (&acc)[2][2][4][2], const Unit& u, int wr, int wc, int fr, int fq) const {
;     const int row0 = u.pm * BM + wr * 64 + fr, col0 = u.pn * BM + wc * 32 + 8 * fq;
; #pragma unroll
;     for (int ai = 0; ai < 2; ++ai) {
;       f32x4 bv[4][2][2];
; #pragma unroll
;       for (int m = 0; m < 4; ++m)
; #pragma unroll
;         for (int bj = 0; bj < 2; ++bj) {
;           const float* bp = base + (size_t)(row0 + ai * HALF + m * 16) * 2048 + col0 + bj * HALF;
;           bv[m][bj][0] = *(const f32x4*)bp; bv[m][bj][1] = *(const f32x4*)(bp + 4);
;         }
; #pragma unroll
;       for (int m = 0; m < 4; ++m) {
;         const int row = row0 + ai * HALF + m * 16;
;         const size_t off = (size_t)row * 2048 + col0;
;         float ss = 0.f;
; #pragma unroll
;         for (int bj = 0; bj < 2; ++bj) {
;           const f32x4 v0 = acc[ai][bj][m][0] + bv[m][bj][0], v1 = acc[ai][bj][m][1] + bv[m][bj][1];
;           *(f32x4*)(C + off + bj * HALF) = v0; *(f32x4*)(C + off + bj * HALF + 4) = v1;
;           if (xb) {
;             u32x4 w; w.x = pack2(v0[0], v0[1]); w.y = pack2(v0[2], v0[3]); w.z = pack2(v1[0], v1[1]); w.w = pack2(v1[2], v1[3]);
;             *(u32x4*)(xb + off + bj * HALF) = w;
;             ss += v0[0] * v0[0] + v0[1] * v0[1] + v0[2] * v0[2] + v0[3] * v0[3] + v1[0] * v1[0] + v1[1] * v1[1] + v1[2] * v1[2] + v1[3] * v1[3];
;           }
;         }
;         if (xb) {
;           ss += __shfl_xor(ss, 16); ss += __shfl_xor(ss, 32);
;           if (fq == 0) ssq[(size_t)row * 32 + u.pn * 4 + wc] = ss;
; template <class Epi, class Sched = StaticOrder>
; DI void gemm_phase(LAS unsigned char* lds, const Gemm g, const Sched& S, const Epi& E) {
;     ...
;       PG8_BAR; PG8_WAIT_L(0); PG8_MMA(1, 0, At, B0); PG8_BAR; PG8_SCHED;
;       PG8_STAGE(PG8_SB(1, 1), b3 + hstep, voffB);
;       PG8_WAIT_V(6); PG8_BAR; PG8_MMA(1, 1, At, B1); PG8_BAR;
;     }
	s_setprio 0
	s_add_u32 s20, s20, 0x160080
	s_addc_u32 s21, s21, 0
	s_add_i32 s22, s22, s30
	s_mov_b32 m0, s22
	s_nop 0
	global_load_lds_dwordx4 v178, s[20:21]
	s_add_i32 m0, s22, 0x2000
	s_nop 0
	global_load_lds_dwordx4 v182, s[20:21]
	ds_read_b128 v[128:131], v214
	ds_read_b128 v[132:135], v214 offset:1024
	ds_read_b128 v[136:139], v214 offset:2048
	ds_read_b128 v[140:143], v214 offset:3072
	s_waitcnt vmcnt(6)
	s_setprio 1
	s_barrier
	v_mfma_f32_16x16x32_bf16 v[52:55], v[192:195], v[144:147], v[52:55]
	v_mfma_f32_16x16x32_bf16 v[48:51], v[200:203], v[144:147], v[48:51]
	v_mfma_f32_16x16x32_bf16 v[36:39], v[192:195], v[152:155], v[36:39]
	v_mfma_f32_16x16x32_bf16 v[32:35], v[200:203], v[152:155], v[32:35]
	v_mfma_f32_16x16x32_bf16 v[20:23], v[192:195], v[160:163], v[20:23]
	v_mfma_f32_16x16x32_bf16 v[16:19], v[200:203], v[160:163], v[16:19]
	v_mfma_f32_16x16x32_bf16 v[4:7], v[192:195], v[168:171], v[4:7]
	v_mfma_f32_16x16x32_bf16 v[0:3], v[200:203], v[168:171], v[0:3]
	v_mfma_f32_16x16x32_bf16 v[52:55], v[196:199], v[148:151], v[52:55]
	v_mfma_f32_16x16x32_bf16 v[48:51], v[204:207], v[148:151], v[48:51]
	v_mfma_f32_16x16x32_bf16 v[36:39], v[196:199], v[156:159], v[36:39]
	v_mfma_f32_16x16x32_bf16 v[32:35], v[204:207], v[156:159], v[32:35]
	v_mfma_f32_16x16x32_bf16 v[20:23], v[196:199], v[164:167], v[20:23]
	v_mfma_f32_16x16x32_bf16 v[16:19], v[204:207], v[164:167], v[16:19]
	v_mfma_f32_16x16x32_bf16 v[4:7], v[196:199], v[172:175], v[4:7]
	v_mfma_f32_16x16x32_bf16 v[0:3], v[204:207], v[172:175], v[0:3]
	s_add_i32 s44, s44, 2
	s_add_u32 s18, s18, 0x100
	s_addc_u32 s19, s19, 0
	s_add_u32 s42, s42, 0x100
	s_addc_u32 s43, s43, 0
	s_cmpk_gt_u32 s44, 0x55
	s_barrier
	s_setprio 0
	s_cbranch_scc0 .LBB0_961
	s_waitcnt lgkmcnt(0)
	v_lshl_add_u32 v194, s51, 8, v211
	v_lshl_or_b32 v192, s2, 8, v213
	v_readlane_b32 s52, v243, 3
	v_ashrrev_i32_e32 v193, 31, v192
	v_readlane_b32 s66, v243, 17
	v_readlane_b32 s67, v243, 18
	v_ashrrev_i32_e32 v195, 31, v194
	v_lshlrev_b64 v[128:129], 13, v[194:195]
	v_lshl_add_u64 v[196:197], v[192:193], 2, s[66:67]
	v_lshl_add_u64 v[236:237], v[196:197], 0, v[128:129]
	global_load_dwordx4 v[220:223], v[236:237], off
	global_load_dwordx4 v[224:227], v[236:237], off offset:16
	global_load_dwordx4 v[228:231], v[236:237], off offset:512
	global_load_dwordx4 v[232:235], v[236:237], off offset:528
	v_or_b32_e32 v206, 16, v194
	v_or_b32_e32 v202, 32, v194
	v_or_b32_e32 v198, 48, v194
	v_ashrrev_i32_e32 v207, 31, v206
	v_ashrrev_i32_e32 v203, 31, v202
	v_ashrrev_i32_e32 v199, 31, v198
	v_lshlrev_b64 v[128:129], 13, v[206:207]
	v_lshlrev_b64 v[130:131], 13, v[202:203]
	v_lshlrev_b64 v[132:133], 13, v[198:199]
	v_lshl_add_u64 v[208:209], v[196:197], 0, v[128:129]
	v_lshl_add_u64 v[204:205], v[196:197], 0, v[130:131]
	v_lshl_add_u64 v[200:201], v[196:197], 0, v[132:133]
	global_load_dwordx4 v[168:171], v[208:209], off offset:16
	global_load_dwordx4 v[172:175], v[208:209], off
	global_load_dwordx4 v[160:163], v[208:209], off offset:528
	global_load_dwordx4 v[164:167], v[208:209], off offset:512
	global_load_dwordx4 v[152:155], v[204:205], off offset:16
	global_load_dwordx4 v[156:159], v[204:205], off
	global_load_dwordx4 v[144:147], v[204:205], off offset:528
	global_load_dwordx4 v[148:151], v[204:205], off offset:512
	global_load_dwordx4 v[136:139], v[200:201], off offset:16
	global_load_dwordx4 v[140:143], v[200:201], off
	global_load_dwordx4 v[128:131], v[200:201], off offset:528
	global_load_dwordx4 v[132:135], v[200:201], off offset:512
	v_and_b32_e32 v218, 64, v217
	v_xor_b32_e32 v238, 16, v217
	v_add_u32_e32 v240, 64, v218
	v_xor_b32_e32 v239, 32, v217
	v_cmp_lt_i32_e32 vcc, v238, v240
	v_lshlrev_b64 v[218:219], 11, v[194:195]
	s_lshl_b32 s18, s2, 2
	v_cndmask_b32_e32 v241, v217, v238, vcc
	v_cmp_lt_i32_e32 vcc, v239, v240
	s_ashr_i32 s19, s18, 31
	v_readlane_b32 s53, v243, 4
	v_cndmask_b32_e32 v240, v217, v239, vcc
	v_lshl_add_u64 v[238:239], v[218:219], 0, v[192:193]
	v_lshlrev_b32_e32 v218, 2, v241
	v_lshl_add_u64 v[238:239], v[238:239], 1, s[12:13]
	v_readlane_b32 s54, v243, 5
	v_readlane_b32 s55, v243, 6
	v_readlane_b32 s56, v243, 7
	v_readlane_b32 s57, v243, 8
	v_readlane_b32 s58, v243, 9
	v_readlane_b32 s59, v243, 10
	v_readlane_b32 s60, v243, 11
	v_readlane_b32 s61, v243, 12
	v_readlane_b32 s62, v243, 13
	v_readlane_b32 s63, v243, 14
	v_readlane_b32 s64, v243, 15
	v_readlane_b32 s65, v243, 16
	s_waitcnt vmcnt(0)
	v_pk_add_f32 v[126:127], v[126:127], v[222:223]
	v_pk_add_f32 v[124:125], v[124:125], v[220:221]
	v_pk_add_f32 v[116:117], v[116:117], v[228:229]
	v_pk_add_f32 v[122:123], v[122:123], v[226:227]
	v_pk_add_f32 v[120:121], v[120:121], v[224:225]
	v_pk_add_f32 v[220:221], v[112:113], v[232:233]
	global_store_dwordx4 v[236:237], v[124:127], off
	global_store_dwordx4 v[236:237], v[120:123], off offset:16
	v_cvt_pk_bf16_f32 v112, v124, v125
	v_mul_f32_e32 v125, v125, v125
	v_mul_f32_e32 v219, v117, v117
	v_pk_add_f32 v[118:119], v[118:119], v[230:231]
	v_fmac_f32_e32 v125, v124, v124
	v_fmac_f32_e32 v219, v116, v116
	v_fmac_f32_e32 v125, v126, v126
	v_fmac_f32_e32 v219, v118, v118
	v_fmac_f32_e32 v125, v127, v127
	v_fmac_f32_e32 v219, v119, v119
	v_fmac_f32_e32 v125, v120, v120
	v_fmac_f32_e32 v219, v220, v220
	v_pk_add_f32 v[222:223], v[114:115], v[234:235]
	v_fmac_f32_e32 v125, v121, v121
	v_fmac_f32_e32 v219, v221, v221
	v_fmac_f32_e32 v125, v122, v122
	v_fmac_f32_e32 v219, v222, v222
	v_fmac_f32_e32 v125, v123, v123
	v_fmac_f32_e32 v219, v223, v223
	v_cvt_pk_bf16_f32 v114, v120, v121
	v_add_f32_e32 v121, v125, v219
	v_cvt_pk_bf16_f32 v115, v122, v123
	ds_bpermute_b32 v122, v218, v121
	v_cvt_pk_bf16_f32 v113, v126, v127
	global_store_dwordx4 v[238:239], v[112:115], off
	global_store_dwordx4 v[236:237], v[116:119], off offset:512
	global_store_dwordx4 v[236:237], v[220:223], off offset:528
	v_lshlrev_b32_e32 v126, 2, v240
	v_cvt_pk_bf16_f32 v120, v116, v117
	s_waitcnt lgkmcnt(0)
	v_add_f32_e32 v112, v121, v122
	ds_bpermute_b32 v113, v126, v112
	v_cvt_pk_bf16_f32 v121, v118, v119
	v_cvt_pk_bf16_f32 v122, v220, v221
	v_cvt_pk_bf16_f32 v123, v222, v223
	global_store_dwordx4 v[238:239], v[120:123], off offset:256
	s_and_saveexec_b64 s[20:21], s[0:1]
	s_cbranch_execz .LBB0_964
	s_waitcnt lgkmcnt(0)
	v_add_f32_e32 v114, v112, v113
	v_lshlrev_b64 v[112:113], 7, v[194:195]
	v_lshl_add_u64 v[112:113], s[14:15], 0, v[112:113]
	v_lshl_add_u64 v[112:113], s[18:19], 2, v[112:113]
	s_lshl_b32 s2, s36, 2
	v_lshl_add_u64 v[112:113], v[112:113], 0, s[2:3]
	global_store_dword v[112:113], v114, off

; #define PG8_STAGE(bufoff, gbase, voff) do { _Pragma("unroll") for (int _i = 0; _i < 2; ++_i) \
;     __builtin_amdgcn_global_load_lds((const unsigned*)((const char*)(gbase) + (voff)[_i]), (LAS unsigned*)(lds + (bufoff) + ldsw + _i * 8192), 16, 0, 0); } while (0)
; #define PG8_LDA(dst, b, h) do { _Pragma("unroll") for (int m = 0; m < 4; ++m) _Pragma("unroll") for (int k = 0; k < 2; ++k) dst[m][k] = *(const LAS bf16x8*)(lds + PG8_SA(b, h) + aoff + m * 2048 + k * 1024); } while (0)
; #define PG8_LDB(dst, b, h) do { _Pragma("unroll") for (int n = 0; n < 2; ++n) _Pragma("unroll") for (int k = 0; k < 2; ++k) dst[n][k] = *(const LAS bf16x8*)(lds + PG8_SB(b, h) + boff + n * 2048 + k * 1024); } while (0)
; #define PG8_MMA(ai, bj, At, Bt) do { __builtin_amdgcn_s_setprio(1); _Pragma("unroll") for (int m = 0; m < 4; ++m) _Pragma("unroll") for (int n = 0; n < 2; ++n) _Pragma("unroll") for (int k = 0; k < 2; ++k) \
;     acc[ai][bj][m][n] = __builtin_amdgcn_mfma_f32_16x16x32_bf16(Bt[n][k], At[m][k], acc[ai][bj][m][n], 0, 0, 0); __builtin_amdgcn_s_setprio(0); } while (0)
; #define PG8_WAIT_V(n) asm volatile("s_waitcnt vmcnt(" #n ")" ::: "memory")
; template <class Epi, class Sched = StaticOrder>
; DI void gemm_phase(LAS unsigned char* lds, const Gemm g, const Sched& S, const Epi& E) {
;     ...
;     for (int t = 0; t < nt; t += 2) {
;       const bool last = (t == nt - 2);
;       const char* a1 = cA + (size_t)(t + 1) * kstep;
;       const char* a2 = last ? nA : cA + (size_t)(t + 2) * kstep; const char* b2 = last ? nB : cB + (size_t)(t + 2) * kstep;
;       const char* a3 = a2 + kstep; const char* b3 = b2 + kstep;
;       PG8_LDB(B0, 0, 0); PG8_SCHED; PG8_LDA(At, 0, 0); PG8_STAGE(PG8_SA(1, 1), a1 + hstep, voffA);
;       PG8_WAIT_L(8); PG8_BAR; PG8_WAIT_L(0); PG8_MMA(0, 0, At, B0); PG8_BAR; PG8_SCHED;
;       PG8_LDB(B1, 0, 1); PG8_STAGE(PG8_SB(0, 0), b2, voffB);
;       PG8_BAR; PG8_WAIT_L(0); PG8_MMA(0, 1, At, B1); PG8_BAR;
;       PG8_LDA(At, 0, 1); PG8_STAGE(PG8_SA(0, 0), a2, voffA);
;       PG8_BAR; PG8_WAIT_L(0); PG8_MMA(1, 0, At, B0); PG8_BAR; PG8_SCHED;
;       PG8_STAGE(PG8_SB(0, 1), b2 + hstep, voffB);
;       PG8_WAIT_V(6); PG8_BAR; PG8_MMA(1, 1, At, B1); PG8_BAR;
;       PG8_LDB(B0, 1, 0); PG8_SCHED; PG8_LDA(At, 1, 0); PG8_STAGE(PG8_SA(0, 1), a2 + hstep, voffA);
;       PG8_WAIT_L(8); PG8_BAR; PG8_WAIT_L(0); PG8_MMA(0, 0, At, B0); PG8_BAR; PG8_SCHED;
.LBB0_1052:
	s_add_i32 m0, s61, 0xc000
	ds_read_b128 v[144:147], v204
	ds_read_b128 v[148:151], v204 offset:1024
	ds_read_b128 v[152:155], v204 offset:2048
	ds_read_b128 v[156:159], v204 offset:3072
	ds_read_b128 v[178:181], v204 offset:4096
	ds_read_b128 v[182:185], v204 offset:5120
	ds_read_b128 v[186:189], v204 offset:6144
	ds_read_b128 v[190:193], v204 offset:7168
	global_load_lds_dwordx4 v172, s[10:11]
	s_add_i32 m0, s61, 0xe000
	s_nop 0
	global_load_lds_dwordx4 v174, s[10:11]
	s_waitcnt lgkmcnt(0)
	s_setprio 1
	s_barrier
	v_mfma_f32_16x16x32_bf16 v[124:127], v[128:131], v[144:147], v[124:127]
	v_mfma_f32_16x16x32_bf16 v[120:123], v[136:139], v[144:147], v[120:123]
	v_mfma_f32_16x16x32_bf16 v[116:119], v[128:131], v[152:155], v[116:119]
	v_mfma_f32_16x16x32_bf16 v[104:107], v[136:139], v[152:155], v[104:107]
	v_mfma_f32_16x16x32_bf16 v[92:95], v[128:131], v[178:181], v[92:95]
	v_mfma_f32_16x16x32_bf16 v[88:91], v[136:139], v[178:181], v[88:91]
	v_mfma_f32_16x16x32_bf16 v[84:87], v[128:131], v[186:189], v[84:87]
	v_mfma_f32_16x16x32_bf16 v[72:75], v[136:139], v[186:189], v[72:75]
	v_mfma_f32_16x16x32_bf16 v[124:127], v[132:135], v[148:151], v[124:127]
	v_mfma_f32_16x16x32_bf16 v[120:123], v[140:143], v[148:151], v[120:123]
	v_mfma_f32_16x16x32_bf16 v[116:119], v[132:135], v[156:159], v[116:119]
	v_mfma_f32_16x16x32_bf16 v[104:107], v[140:143], v[156:159], v[104:107]
	v_mfma_f32_16x16x32_bf16 v[92:95], v[132:135], v[182:185], v[92:95]
	v_mfma_f32_16x16x32_bf16 v[88:91], v[140:143], v[182:185], v[88:91]
	v_mfma_f32_16x16x32_bf16 v[84:87], v[132:135], v[190:193], v[84:87]
	v_mfma_f32_16x16x32_bf16 v[72:75], v[140:143], v[190:193], v[72:75]
	s_barrier
	s_setprio 0
	ds_read_b128 v[194:197], v205
	ds_read_b128 v[212:215], v205 offset:1024
	ds_read_b128 v[216:219], v205 offset:2048
	ds_read_b128 v[220:223], v205 offset:3072
	s_add_u32 s12, s10, 0xfff80080
	s_addc_u32 s13, s11, -1
	s_cmp_eq_u32 s52, 28
	s_cselect_b32 s65, s41, s13
	s_cselect_b32 s64, s42, s12
	s_cselect_b32 s13, s43, s49
	s_cselect_b32 s12, s44, s45
	s_add_i32 s53, s80, s70
	s_add_u32 s98, s12, 0x80
	s_addc_u32 s99, s13, 0
	s_add_u32 s100, s64, 0x80
	s_addc_u32 s101, s65, 0
	s_mov_b32 m0, s53
	s_nop 0
	global_load_lds_dwordx4 v162, s[12:13]
	s_add_i32 m0, s53, 0x2000
	s_nop 0
	global_load_lds_dwordx4 v166, s[12:13]
	s_waitcnt lgkmcnt(0)
	s_setprio 1
	s_barrier
	v_mfma_f32_16x16x32_bf16 v[112:115], v[194:197], v[144:147], v[112:115]
	v_mfma_f32_16x16x32_bf16 v[108:111], v[216:219], v[144:147], v[108:111]
	v_mfma_f32_16x16x32_bf16 v[100:103], v[194:197], v[152:155], v[100:103]
	v_mfma_f32_16x16x32_bf16 v[96:99], v[216:219], v[152:155], v[96:99]
	v_mfma_f32_16x16x32_bf16 v[80:83], v[194:197], v[178:181], v[80:83]
	v_mfma_f32_16x16x32_bf16 v[76:79], v[216:219], v[178:181], v[76:79]
	v_mfma_f32_16x16x32_bf16 v[68:71], v[194:197], v[186:189], v[68:71]
	v_mfma_f32_16x16x32_bf16 v[64:67], v[216:219], v[186:189], v[64:67]
	v_mfma_f32_16x16x32_bf16 v[112:115], v[212:215], v[148:151], v[112:115]
	v_mfma_f32_16x16x32_bf16 v[108:111], v[220:223], v[148:151], v[108:111]
	v_mfma_f32_16x16x32_bf16 v[100:103], v[212:215], v[156:159], v[100:103]
	v_mfma_f32_16x16x32_bf16 v[96:99], v[220:223], v[156:159], v[96:99]
	v_mfma_f32_16x16x32_bf16 v[80:83], v[212:215], v[182:185], v[80:83]
	v_mfma_f32_16x16x32_bf16 v[76:79], v[220:223], v[182:185], v[76:79]
	v_mfma_f32_16x16x32_bf16 v[68:71], v[212:215], v[190:193], v[68:71]
	v_mfma_f32_16x16x32_bf16 v[64:67], v[220:223], v[190:193], v[64:67]
	s_barrier
	s_setprio 0
	s_mov_b32 m0, s61
	ds_read_b128 v[144:147], v204 offset:16384
	ds_read_b128 v[148:151], v204 offset:17408
	ds_read_b128 v[152:155], v204 offset:18432
	ds_read_b128 v[156:159], v204 offset:19456
	ds_read_b128 v[178:181], v204 offset:20480
	ds_read_b128 v[182:185], v204 offset:21504
	ds_read_b128 v[186:189], v204 offset:22528
	ds_read_b128 v[190:193], v204 offset:23552
	global_load_lds_dwordx4 v160, s[64:65]
	s_mov_b32 m0, s63
	s_nop 0
	global_load_lds_dwordx4 v164, s[64:65]
	s_waitcnt vmcnt(10)
	s_waitcnt lgkmcnt(0)
	s_setprio 1
	s_barrier
	v_mfma_f32_16x16x32_bf16 v[60:63], v[128:131], v[144:147], v[60:63]
	v_mfma_f32_16x16x32_bf16 v[56:59], v[136:139], v[144:147], v[56:59]
	v_mfma_f32_16x16x32_bf16 v[48:51], v[128:131], v[152:155], v[48:51]
	v_mfma_f32_16x16x32_bf16 v[40:43], v[136:139], v[152:155], v[40:43]
	v_mfma_f32_16x16x32_bf16 v[28:31], v[128:131], v[178:181], v[28:31]
	v_mfma_f32_16x16x32_bf16 v[24:27], v[136:139], v[178:181], v[24:27]
	v_mfma_f32_16x16x32_bf16 v[12:15], v[128:131], v[186:189], v[12:15]
	v_mfma_f32_16x16x32_bf16 v[8:11], v[136:139], v[186:189], v[8:11]
	v_mfma_f32_16x16x32_bf16 v[60:63], v[132:135], v[148:151], v[60:63]
	v_mfma_f32_16x16x32_bf16 v[56:59], v[140:143], v[148:151], v[56:59]
	v_mfma_f32_16x16x32_bf16 v[48:51], v[132:135], v[156:159], v[48:51]
	v_mfma_f32_16x16x32_bf16 v[40:43], v[140:143], v[156:159], v[40:43]
	v_mfma_f32_16x16x32_bf16 v[28:31], v[132:135], v[182:185], v[28:31]
	v_mfma_f32_16x16x32_bf16 v[24:27], v[140:143], v[182:185], v[24:27]
	v_mfma_f32_16x16x32_bf16 v[12:15], v[132:135], v[190:193], v[12:15]
	v_mfma_f32_16x16x32_bf16 v[8:11], v[140:143], v[190:193], v[8:11]
	s_barrier
	s_setprio 0
	s_add_u32 s54, s12, 0x80000
	s_addc_u32 s55, s13, 0
	s_add_i32 s53, s81, s70
	s_mov_b32 m0, s53
	s_nop 0
	global_load_lds_dwordx4 v162, s[54:55]
	s_add_i32 m0, s53, 0x2000
	s_nop 0
	global_load_lds_dwordx4 v166, s[54:55]
	s_add_i32 s53, 0, 0x18000
	v_add_u32_e32 v140, s53, v199
	ds_read_b128 v[128:131], v140
	ds_read_b128 v[132:135], v140 offset:1024
	ds_read_b128 v[136:139], v140 offset:2048
	ds_read_b128 v[140:143], v140 offset:3072
	s_waitcnt vmcnt(6)
	s_setprio 1
	s_barrier
; #define PG8_STAGE(bufoff, gbase, voff) do { _Pragma("unroll") for (int _i = 0; _i < 2; ++_i) \
;     __builtin_amdgcn_global_load_lds((const unsigned*)((const char*)(gbase) + (voff)[_i]), (LAS unsigned*)(lds + (bufoff) + ldsw + _i * 8192), 16, 0, 0); } while (0)
; #define PG8_LDA(dst, b, h) do { _Pragma("unroll") for (int m = 0; m < 4; ++m) _Pragma("unroll") for (int k = 0; k < 2; ++k) dst[m][k] = *(const LAS bf16x8*)(lds + PG8_SA(b, h) + aoff + m * 2048 + k * 1024); } while (0)
; #define PG8_LDB(dst, b, h) do { _Pragma("unroll") for (int n = 0; n < 2; ++n) _Pragma("unroll") for (int k = 0; k < 2; ++k) dst[n][k] = *(const LAS bf16x8*)(lds + PG8_SB(b, h) + boff + n * 2048 + k * 1024); } while (0)
; #define PG8_MMA(ai, bj, At, Bt) do { __builtin_amdgcn_s_setprio(1); _Pragma("unroll") for (int m = 0; m < 4; ++m) _Pragma("unroll") for (int n = 0; n < 2; ++n) _Pragma("unroll") for (int k = 0; k < 2; ++k) \
;     acc[ai][bj][m][n] = __builtin_amdgcn_mfma_f32_16x16x32_bf16(Bt[n][k], At[m][k], acc[ai][bj][m][n], 0, 0, 0); __builtin_amdgcn_s_setprio(0); } while (0)
; #define PG8_WAIT_V(n) asm volatile("s_waitcnt vmcnt(" #n ")" ::: "memory")
; #define PG8_WAIT_L(n) asm volatile("s_waitcnt lgkmcnt(" #n ")" ::: "memory")
; #define PG8_BAR __builtin_amdgcn_s_barrier()
; #define PG8_SCHED __builtin_amdgcn_sched_barrier(0)
; template <class Epi, class Sched = StaticOrder>
; DI void gemm_phase(LAS unsigned char* lds, const Gemm g, const Sched& S, const Epi& E) {
;     ...
;       PG8_WAIT_V(6); PG8_BAR; PG8_MMA(1, 1, At, B1); PG8_BAR;
;       PG8_LDB(B0, 1, 0); PG8_SCHED; PG8_LDA(At, 1, 0); PG8_STAGE(PG8_SA(0, 1), a2 + hstep, voffA);
;       PG8_WAIT_L(8); PG8_BAR; PG8_WAIT_L(0); PG8_MMA(0, 0, At, B0); PG8_BAR; PG8_SCHED;
;       PG8_LDB(B1, 1, 1); PG8_STAGE(PG8_SB(1, 0), b3, voffB);
;       PG8_BAR; PG8_WAIT_L(0); PG8_MMA(0, 1, At, B1); PG8_BAR;
;       PG8_LDA(At, 1, 1); PG8_STAGE(PG8_SA(1, 0), a3, voffA);
;       PG8_BAR; PG8_WAIT_L(0); PG8_MMA(1, 0, At, B0); PG8_BAR; PG8_SCHED;
;       PG8_STAGE(PG8_SB(1, 1), b3 + hstep, voffB);
;       PG8_WAIT_V(6); PG8_BAR; PG8_MMA(1, 1, At, B1); PG8_BAR;
	v_mfma_f32_16x16x32_bf16 v[52:55], v[194:197], v[144:147], v[52:55]
	v_mfma_f32_16x16x32_bf16 v[44:47], v[216:219], v[144:147], v[44:47]
	v_mfma_f32_16x16x32_bf16 v[36:39], v[194:197], v[152:155], v[36:39]
	v_mfma_f32_16x16x32_bf16 v[32:35], v[216:219], v[152:155], v[32:35]
	v_mfma_f32_16x16x32_bf16 v[20:23], v[194:197], v[178:181], v[20:23]
	v_mfma_f32_16x16x32_bf16 v[16:19], v[216:219], v[178:181], v[16:19]
	v_mfma_f32_16x16x32_bf16 v[4:7], v[194:197], v[186:189], v[4:7]
	v_mfma_f32_16x16x32_bf16 v[0:3], v[216:219], v[186:189], v[0:3]
	v_mfma_f32_16x16x32_bf16 v[52:55], v[212:215], v[148:151], v[52:55]
	v_mfma_f32_16x16x32_bf16 v[44:47], v[220:223], v[148:151], v[44:47]
	v_mfma_f32_16x16x32_bf16 v[36:39], v[212:215], v[156:159], v[36:39]
	v_mfma_f32_16x16x32_bf16 v[32:35], v[220:223], v[156:159], v[32:35]
	v_mfma_f32_16x16x32_bf16 v[20:23], v[212:215], v[182:185], v[20:23]
	v_mfma_f32_16x16x32_bf16 v[16:19], v[220:223], v[182:185], v[16:19]
	v_mfma_f32_16x16x32_bf16 v[4:7], v[212:215], v[190:193], v[4:7]
	v_mfma_f32_16x16x32_bf16 v[0:3], v[220:223], v[190:193], v[0:3]
	s_barrier
	s_setprio 0
	s_add_u32 s54, s64, 0x80000
	s_addc_u32 s55, s65, 0
	s_mov_b32 m0, s71
	ds_read_b128 v[144:147], v204 offset:32768
	ds_read_b128 v[148:151], v204 offset:33792
	ds_read_b128 v[152:155], v204 offset:34816
	ds_read_b128 v[156:159], v204 offset:35840
	ds_read_b128 v[178:181], v204 offset:36864
	ds_read_b128 v[182:185], v204 offset:37888
	ds_read_b128 v[186:189], v204 offset:38912
	ds_read_b128 v[190:193], v204 offset:39936
	global_load_lds_dwordx4 v160, s[54:55]
	s_mov_b32 m0, s72
	s_nop 0
	global_load_lds_dwordx4 v164, s[54:55]
	s_waitcnt lgkmcnt(0)
	s_setprio 1
	s_barrier
	v_mfma_f32_16x16x32_bf16 v[124:127], v[128:131], v[144:147], v[124:127]
	v_mfma_f32_16x16x32_bf16 v[120:123], v[136:139], v[144:147], v[120:123]
	v_mfma_f32_16x16x32_bf16 v[116:119], v[128:131], v[152:155], v[116:119]
	v_mfma_f32_16x16x32_bf16 v[104:107], v[136:139], v[152:155], v[104:107]
	v_mfma_f32_16x16x32_bf16 v[92:95], v[128:131], v[178:181], v[92:95]
	v_mfma_f32_16x16x32_bf16 v[88:91], v[136:139], v[178:181], v[88:91]
	v_mfma_f32_16x16x32_bf16 v[84:87], v[128:131], v[186:189], v[84:87]
	v_mfma_f32_16x16x32_bf16 v[72:75], v[136:139], v[186:189], v[72:75]
	v_mfma_f32_16x16x32_bf16 v[124:127], v[132:135], v[148:151], v[124:127]
	v_mfma_f32_16x16x32_bf16 v[120:123], v[140:143], v[148:151], v[120:123]
	v_mfma_f32_16x16x32_bf16 v[116:119], v[132:135], v[156:159], v[116:119]
	v_mfma_f32_16x16x32_bf16 v[104:107], v[140:143], v[156:159], v[104:107]
	v_mfma_f32_16x16x32_bf16 v[92:95], v[132:135], v[182:185], v[92:95]
	v_mfma_f32_16x16x32_bf16 v[88:91], v[140:143], v[182:185], v[88:91]
	v_mfma_f32_16x16x32_bf16 v[84:87], v[132:135], v[190:193], v[84:87]
	v_mfma_f32_16x16x32_bf16 v[72:75], v[140:143], v[190:193], v[72:75]
	s_barrier
	s_setprio 0
	s_add_i32 s54, 0, 0x1c000
	s_add_i32 s53, s53, s70
	v_add_u32_e32 v168, s54, v199
	s_mov_b32 m0, s53
	ds_read_b128 v[194:197], v168
	ds_read_b128 v[212:215], v168 offset:1024
	ds_read_b128 v[216:219], v168 offset:2048
	ds_read_b128 v[220:223], v168 offset:3072
	global_load_lds_dwordx4 v162, s[98:99]
	s_add_i32 m0, s53, 0x2000
	s_nop 0
	global_load_lds_dwordx4 v166, s[98:99]
	s_waitcnt lgkmcnt(0)
	s_setprio 1
	s_barrier
	v_mfma_f32_16x16x32_bf16 v[112:115], v[194:197], v[144:147], v[112:115]
	v_mfma_f32_16x16x32_bf16 v[108:111], v[216:219], v[144:147], v[108:111]
	v_mfma_f32_16x16x32_bf16 v[100:103], v[194:197], v[152:155], v[100:103]
	v_mfma_f32_16x16x32_bf16 v[96:99], v[216:219], v[152:155], v[96:99]
	v_mfma_f32_16x16x32_bf16 v[80:83], v[194:197], v[178:181], v[80:83]
	v_mfma_f32_16x16x32_bf16 v[76:79], v[216:219], v[178:181], v[76:79]
	v_mfma_f32_16x16x32_bf16 v[68:71], v[194:197], v[186:189], v[68:71]
	v_mfma_f32_16x16x32_bf16 v[64:67], v[216:219], v[186:189], v[64:67]
	v_mfma_f32_16x16x32_bf16 v[112:115], v[212:215], v[148:151], v[112:115]
	v_mfma_f32_16x16x32_bf16 v[108:111], v[220:223], v[148:151], v[108:111]
	v_mfma_f32_16x16x32_bf16 v[100:103], v[212:215], v[156:159], v[100:103]
	v_mfma_f32_16x16x32_bf16 v[96:99], v[220:223], v[156:159], v[96:99]
	v_mfma_f32_16x16x32_bf16 v[80:83], v[212:215], v[182:185], v[80:83]
	v_mfma_f32_16x16x32_bf16 v[76:79], v[220:223], v[182:185], v[76:79]
	v_mfma_f32_16x16x32_bf16 v[68:71], v[212:215], v[190:193], v[68:71]
	v_mfma_f32_16x16x32_bf16 v[64:67], v[220:223], v[190:193], v[64:67]
	s_barrier
	s_setprio 0
	s_mov_b32 m0, s76
	ds_read_b128 v[144:147], v204 offset:49152
	ds_read_b128 v[148:151], v204 offset:50176
	ds_read_b128 v[152:155], v204 offset:51200
	ds_read_b128 v[156:159], v204 offset:52224
	ds_read_b128 v[178:181], v204 offset:53248
	ds_read_b128 v[182:185], v204 offset:54272
	ds_read_b128 v[186:189], v204 offset:55296
	ds_read_b128 v[190:193], v204 offset:56320
	global_load_lds_dwordx4 v160, s[100:101]
	s_mov_b32 m0, s77
	s_nop 0
	global_load_lds_dwordx4 v164, s[100:101]
	s_waitcnt vmcnt(10)
	s_waitcnt lgkmcnt(0)
	s_setprio 1
	s_barrier
	v_mfma_f32_16x16x32_bf16 v[60:63], v[128:131], v[144:147], v[60:63]
	v_mfma_f32_16x16x32_bf16 v[56:59], v[136:139], v[144:147], v[56:59]
	v_mfma_f32_16x16x32_bf16 v[48:51], v[128:131], v[152:155], v[48:51]
	v_mfma_f32_16x16x32_bf16 v[40:43], v[136:139], v[152:155], v[40:43]
	v_mfma_f32_16x16x32_bf16 v[28:31], v[128:131], v[178:181], v[28:31]
	v_mfma_f32_16x16x32_bf16 v[24:27], v[136:139], v[178:181], v[24:27]
	v_mfma_f32_16x16x32_bf16 v[12:15], v[128:131], v[186:189], v[12:15]
	v_mfma_f32_16x16x32_bf16 v[8:11], v[136:139], v[186:189], v[8:11]
	v_mfma_f32_16x16x32_bf16 v[60:63], v[132:135], v[148:151], v[60:63]
	v_mfma_f32_16x16x32_bf16 v[56:59], v[140:143], v[148:151], v[56:59]
	v_mfma_f32_16x16x32_bf16 v[48:51], v[132:135], v[156:159], v[48:51]
	v_mfma_f32_16x16x32_bf16 v[40:43], v[140:143], v[156:159], v[40:43]
	v_mfma_f32_16x16x32_bf16 v[28:31], v[132:135], v[182:185], v[28:31]
	v_mfma_f32_16x16x32_bf16 v[24:27], v[140:143], v[182:185], v[24:27]
	v_mfma_f32_16x16x32_bf16 v[12:15], v[132:135], v[190:193], v[12:15]
	v_mfma_f32_16x16x32_bf16 v[8:11], v[140:143], v[190:193], v[8:11]
	s_barrier
; DI float dpp_ror1(float v) { return __int_as_float(__builtin_amdgcn_update_dpp(0, __float_as_int(v), 0x121, 0xf, 0xf, false)); }
; DI float dpp_ror2(float v) { return __int_as_float(__builtin_amdgcn_update_dpp(0, __float_as_int(v), 0x122, 0xf, 0xf, false)); }
; #define PG8_STAGE(bufoff, gbase, voff) do { _Pragma("unroll") for (int _i = 0; _i < 2; ++_i) \
;     __builtin_amdgcn_global_load_lds((const unsigned*)((const char*)(gbase) + (voff)[_i]), (LAS unsigned*)(lds + (bufoff) + ldsw + _i * 8192), 16, 0, 0); } while (0)
; #define PG8_WAIT_V(n) asm volatile("s_waitcnt vmcnt(" #n ")" ::: "memory")
; #define PG8_BAR __builtin_amdgcn_s_barrier()
;   DI void operator()(const f32x4 (&acc)[2][2][4][2], const Unit& u, int wr, int wc, int fr, int fq) const {
;     ...
;     const int col = u.pn * 128 + wc * 32 + 8 * fq;
;     float w0[8], w1[8], w2[8];
; #pragma unroll
;     for (int e = 0; e < 8; ++e) { w0[e] = cw[col + e]; w1[e] = cw[2048 + col + e]; w2[e] = cw[4096 + col + e]; }
; #pragma unroll
;     for (int ai = 0; ai < 2; ++ai) {
;       const int row0 = u.pm * BM + ai * HALF + wr * 64, span = row0 >> 6;
;       float rsv[4];
; #pragma unroll
;       for (int m = 0; m < 4; ++m) rsv[m] = row_rstd(ssq, row0 + 16 * m + fr, fq);
;       float p1[8], p2[8];
; #pragma unroll
;       for (int e = 0; e < 8; ++e) { p1[e] = 0.f; p2[e] = 0.f; }
; #pragma unroll
;       for (int m = 0; m < 4; ++m) {
;         float g[8], a[8];
;         const float rs1 = rsv[m], rs2 = rs1 * rs1;
; #pragma unroll
;         for (int e = 0; e < 4; ++e) { g[e] = acc[ai][0][m][0][e] * acc[ai][1][m][0][e] * rs2; g[4 + e] = acc[ai][0][m][1][e] * acc[ai][1][m][1][e] * rs2; }
; #pragma unroll
;         for (int e = 0; e < 8; ++e) {
;           const float x1 = dpp_ror1(g[e]), x2 = dpp_ror2(g[e]);
;           const float pr1 = (fr == 0) ? p1[e] : x1, pr2 = (fr < 2) ? p2[e] : x2;
; template <class Epi, class Sched = StaticOrder>
; DI void gemm_phase(LAS unsigned char* lds, const Gemm g, const Sched& S, const Epi& E) {
;     ...
;       PG8_STAGE(PG8_SB(1, 1), b3 + hstep, voffB);
;       PG8_WAIT_V(6); PG8_BAR; PG8_MMA(1, 1, At, B1); PG8_BAR;
;     }
;     E(acc, cur, wr, wc, fr, fq);
	s_setprio 0
	s_add_u32 s12, s12, 0x80080
	s_addc_u32 s13, s13, 0
	s_add_i32 s53, s54, s70
	s_mov_b32 m0, s53
	s_nop 0
	global_load_lds_dwordx4 v162, s[12:13]
	s_add_i32 m0, s53, 0x2000
	s_nop 0
	global_load_lds_dwordx4 v166, s[12:13]
	ds_read_b128 v[128:131], v203
	ds_read_b128 v[132:135], v203 offset:1024
	ds_read_b128 v[136:139], v203 offset:2048
	ds_read_b128 v[140:143], v203 offset:3072
	s_waitcnt vmcnt(6)
	s_setprio 1
	s_barrier
	v_mfma_f32_16x16x32_bf16 v[52:55], v[194:197], v[144:147], v[52:55]
	v_mfma_f32_16x16x32_bf16 v[44:47], v[216:219], v[144:147], v[44:47]
	v_mfma_f32_16x16x32_bf16 v[36:39], v[194:197], v[152:155], v[36:39]
	v_mfma_f32_16x16x32_bf16 v[32:35], v[216:219], v[152:155], v[32:35]
	v_mfma_f32_16x16x32_bf16 v[20:23], v[194:197], v[178:181], v[20:23]
	v_mfma_f32_16x16x32_bf16 v[16:19], v[216:219], v[178:181], v[16:19]
	v_mfma_f32_16x16x32_bf16 v[4:7], v[194:197], v[186:189], v[4:7]
	v_mfma_f32_16x16x32_bf16 v[0:3], v[216:219], v[186:189], v[0:3]
	v_mfma_f32_16x16x32_bf16 v[52:55], v[212:215], v[148:151], v[52:55]
	v_mfma_f32_16x16x32_bf16 v[44:47], v[220:223], v[148:151], v[44:47]
	v_mfma_f32_16x16x32_bf16 v[36:39], v[212:215], v[156:159], v[36:39]
	v_mfma_f32_16x16x32_bf16 v[32:35], v[220:223], v[156:159], v[32:35]
	v_mfma_f32_16x16x32_bf16 v[20:23], v[212:215], v[182:185], v[20:23]
	v_mfma_f32_16x16x32_bf16 v[16:19], v[220:223], v[182:185], v[16:19]
	v_mfma_f32_16x16x32_bf16 v[4:7], v[212:215], v[190:193], v[4:7]
	v_mfma_f32_16x16x32_bf16 v[0:3], v[220:223], v[190:193], v[0:3]
	s_add_i32 s52, s52, 2
	s_add_u32 s10, s10, 0x100
	s_addc_u32 s11, s11, 0
	s_add_u32 s45, s45, 0x100
	s_addc_u32 s49, s49, 0
	s_cmp_gt_u32 s52, 29
	s_barrier
	s_setprio 0
	s_cbranch_scc0 .LBB0_1052
	s_waitcnt lgkmcnt(0)
	s_cmp_lt_i32 s62, 16
	s_mov_b64 s[10:11], -1
	s_cbranch_scc0 .LBB0_1067
	s_lshl_b32 s41, s60, 8
	s_add_i32 s41, s41, s75
	v_or_b32_e32 v186, s41, v177
	v_ashrrev_i32_e32 v187, 31, v186
	v_lshlrev_b64 v[128:129], 7, v[186:187]
	v_or_b32_e32 v180, 16, v186
	v_lshl_add_u64 v[128:129], v[170:171], 0, v[128:129]
	v_ashrrev_i32_e32 v181, 31, v180
	global_load_dwordx4 v[152:155], v[128:129], off
	global_load_dwordx4 v[156:159], v[128:129], off offset:16
	v_lshlrev_b64 v[128:129], 7, v[180:181]
	v_lshl_add_u64 v[128:129], v[170:171], 0, v[128:129]
	global_load_dwordx4 v[188:191], v[128:129], off
	global_load_dwordx4 v[192:195], v[128:129], off offset:16
	v_or_b32_e32 v184, 32, v186
	v_ashrrev_i32_e32 v185, 31, v184
	v_lshlrev_b64 v[128:129], 7, v[184:185]
	v_or_b32_e32 v182, 48, v186
	v_lshl_add_u64 v[128:129], v[170:171], 0, v[128:129]
	v_ashrrev_i32_e32 v183, 31, v182
	global_load_dwordx4 v[212:215], v[128:129], off
	global_load_dwordx4 v[216:219], v[128:129], off offset:16
	v_lshlrev_b64 v[128:129], 7, v[182:183]
	v_lshl_add_u64 v[128:129], v[170:171], 0, v[128:129]
	global_load_dwordx4 v[220:223], v[128:129], off
	global_load_dwordx4 v[224:227], v[128:129], off offset:16
	v_and_b32_e32 v129, 64, v206
	v_lshl_or_b32 v178, s62, 7, v200
	v_xor_b32_e32 v128, 16, v206
	v_add_u32_e32 v129, 64, v129
	v_readlane_b32 s44, v243, 3
	v_xor_b32_e32 v130, 32, v206
	v_ashrrev_i32_e32 v179, 31, v178
	v_readlane_b32 s45, v243, 4
	v_cmp_lt_i32_e32 vcc, v128, v129
	s_movk_i32 s10, 0x2000
	v_lshl_add_u64 v[144:145], v[178:179], 2, s[44:45]
	v_cndmask_b32_e32 v134, v206, v128, vcc
	v_cmp_lt_i32_e32 vcc, v130, v129
	v_lshl_add_u64 v[132:133], v[144:145], 0, s[26:27]
	v_lshl_add_u64 v[136:137], v[144:145], 0, s[28:29]
	v_cndmask_b32_e32 v135, v206, v130, vcc
	v_add_co_u32_e32 v146, vcc, s10, v144
	global_load_dwordx4 v[128:131], v[144:145], off offset:16
	global_load_dwordx4 v[140:143], v[144:145], off
	v_addc_co_u32_e32 v147, vcc, 0, v145, vcc
	v_add_co_u32_e32 v148, vcc, s74, v144
	v_lshlrev_b32_e32 v196, 2, v134
	s_nop 0
	v_addc_co_u32_e32 v149, vcc, 0, v145, vcc
	v_lshlrev_b32_e32 v207, 2, v135
	global_load_dwordx4 v[132:135], v[132:133], off offset:16
	s_nop 0
	global_load_dwordx4 v[136:139], v[136:137], off offset:16
	s_nop 0
	global_load_dwordx4 v[144:147], v[146:147], off
	s_nop 0
	global_load_dwordx4 v[148:151], v[148:149], off
	v_mov_b32_e32 v197, 0
	v_mov_b32_e32 v211, 0
	v_readlane_b32 s46, v243, 5
	v_readlane_b32 s47, v243, 6
	v_readlane_b32 s48, v243, 7
	v_readlane_b32 s49, v243, 8
	v_readlane_b32 s50, v243, 9
	v_readlane_b32 s51, v243, 10
	v_readlane_b32 s52, v243, 11
	v_readlane_b32 s53, v243, 12
	v_readlane_b32 s54, v243, 13
	v_readlane_b32 s55, v243, 14
	v_readlane_b32 s56, v243, 15
	v_readlane_b32 s57, v243, 16
	v_readlane_b32 s58, v243, 17
	v_readlane_b32 s59, v243, 18
	s_waitcnt vmcnt(0)
	v_mov_b32_e32 v208, v152
	v_mov_b32_e32 v209, v156
	v_mov_b32_e32 v156, v153
	v_mov_b32_e32 v152, v154
	v_mov_b32_e32 v153, v158
	v_mov_b32_e32 v158, v155
	v_pk_add_f32 v[154:155], v[208:209], v[156:157]
	v_pk_add_f32 v[152:153], v[152:153], v[158:159]
	v_mov_b32_e32 v156, v188
	v_mov_b32_e32 v157, v192
	v_mov_b32_e32 v192, v189
	v_mov_b32_e32 v158, v190
	v_mov_b32_e32 v159, v194
	v_mov_b32_e32 v194, v191
	v_pk_add_f32 v[152:153], v[154:155], v[152:153]
	v_pk_add_f32 v[154:155], v[156:157], v[192:193]
	v_pk_add_f32 v[156:157], v[158:159], v[194:195]
	v_mov_b32_e32 v188, v212
	v_pk_add_f32 v[154:155], v[154:155], v[156:157]
	v_mov_b32_e32 v157, v152
	v_mov_b32_e32 v156, v154
	v_mov_b32_e32 v152, v155
	v_pk_add_f32 v[152:153], v[156:157], v[152:153]
	ds_bpermute_b32 v155, v196, v153
	ds_bpermute_b32 v154, v196, v152
	v_mov_b32_e32 v189, v216
	v_mov_b32_e32 v216, v213
	v_mov_b32_e32 v190, v214
	v_mov_b32_e32 v191, v218
	s_waitcnt lgkmcnt(0)
; DI unsigned pack2(float lo, float hi) { f32x2 v = {lo, hi}; bf16v2 r = __builtin_convertvector(v, bf16v2); return __builtin_bit_cast(unsigned, r); }
; DI float dpp_ror1(float v) { return __int_as_float(__builtin_amdgcn_update_dpp(0, __float_as_int(v), 0x121, 0xf, 0xf, false)); }
; DI float dpp_ror2(float v) { return __int_as_float(__builtin_amdgcn_update_dpp(0, __float_as_int(v), 0x122, 0xf, 0xf, false)); }
;   DI void operator()(const f32x4 (&acc)[2][2][4][2], const Unit& u, int wr, int wc, int fr, int fq) const {
;     ...
;       for (int m = 0; m < 4; ++m) rsv[m] = row_rstd(ssq, row0 + 16 * m + fr, fq);
;       float p1[8], p2[8];
; #pragma unroll
;       for (int e = 0; e < 8; ++e) { p1[e] = 0.f; p2[e] = 0.f; }
; #pragma unroll
;       for (int m = 0; m < 4; ++m) {
;         float g[8], a[8];
;         const float rs1 = rsv[m], rs2 = rs1 * rs1;
; #pragma unroll
;         for (int e = 0; e < 4; ++e) { g[e] = acc[ai][0][m][0][e] * acc[ai][1][m][0][e] * rs2; g[4 + e] = acc[ai][0][m][1][e] * acc[ai][1][m][1][e] * rs2; }
; #pragma unroll
;         for (int e = 0; e < 8; ++e) {
;           const float x1 = dpp_ror1(g[e]), x2 = dpp_ror2(g[e]);
;           const float pr1 = (fr == 0) ? p1[e] : x1, pr2 = (fr < 2) ? p2[e] : x2;
;           a[e] = w2[e] * g[e] + w1[e] * pr1 + w0[e] * pr2;
;           p1[e] = x1; p2[e] = x2;
;         }
;         if (m == 0 && fr < 2) {
;           float* hc = headC + (size_t)(span * 2 + fr) * 2048 + col;
;           *(f32x4*)hc = (f32x4){a[0], a[1], a[2], a[3]}; *(f32x4*)(hc + 4) = (f32x4){a[4], a[5], a[6], a[7]};
;         } else {
;           u32x4 w; w.x = pack2(a[0] * rs1, a[1] * rs1); w.y = pack2(a[2] * rs1, a[3] * rs1); w.z = pack2(a[4] * rs1, a[5] * rs1); w.w = pack2(a[6] * rs1, a[7] * rs1);
;           *(u32x4*)(C + (size_t)(row0 + 16 * m + fr) * 2048 + col) = w;
	v_pk_add_f32 v[152:153], v[152:153], v[154:155]
	ds_bpermute_b32 v155, v207, v153
	ds_bpermute_b32 v154, v207, v152
	v_mov_b32_e32 v218, v215
	v_mov_b32_e32 v208, v220
	v_mov_b32_e32 v209, v224
	v_mov_b32_e32 v224, v221
	v_mov_b32_e32 v212, v222
	v_mov_b32_e32 v213, v226
	v_mov_b32_e32 v226, v223
	v_pk_add_f32 v[156:157], v[188:189], v[216:217]
	v_pk_add_f32 v[158:159], v[190:191], v[218:219]
	v_pk_add_f32 v[188:189], v[208:209], v[224:225]
	v_pk_add_f32 v[190:191], v[212:213], v[226:227]
	s_waitcnt lgkmcnt(0)
	v_pk_add_f32 v[152:153], v[152:153], v[154:155]
	v_pk_add_f32 v[156:157], v[156:157], v[158:159]
	v_pk_add_f32 v[158:159], v[188:189], v[190:191]
	v_pk_fma_f32 v[188:189], v[152:153], s[30:31], v[176:177] op_sel_hi:[1,0,0]
	v_mov_b32_e32 v153, v156
	v_mul_f32_e32 v152, 0x4b800000, v189
	v_cmp_gt_f32_e64 s[10:11], s84, v189
	v_mov_b32_e32 v156, v159
	v_mov_b32_e32 v194, v123
	v_cndmask_b32_e64 v152, v189, v152, s[10:11]
	v_rsq_f32_e32 v168, v152
	v_mov_b32_e32 v152, v158
	v_pk_add_f32 v[152:153], v[152:153], v[156:157]
	ds_bpermute_b32 v155, v196, v153
	ds_bpermute_b32 v154, v196, v152
	v_mul_f32_e32 v156, 0x45800000, v168
	v_cndmask_b32_e64 v195, v168, v156, s[10:11]
	v_mov_b32_e32 v217, 0
	v_mul_f32_e32 v156, v125, v113
	s_waitcnt lgkmcnt(0)
	v_pk_add_f32 v[190:191], v[152:153], v[154:155]
	v_mov_b32_e32 v152, v111
	v_mov_b32_e32 v153, v195
	v_mul_f32_e32 v154, v124, v112
	v_pk_mul_f32 v[152:153], v[194:195], v[152:153]
	v_mul_f32_e32 v155, v120, v108
	v_mul_f32_e32 v154, v154, v153
	v_pk_mul_f32 v[222:223], v[152:153], v[152:153] op_sel:[0,1] op_sel_hi:[1,0]
	v_mov_b32_e32 v213, 0
	v_mov_b32_dpp v217, v154 row_ror:1 row_mask:0xf bank_mask:0xf
	v_cndmask_b32_e64 v152, v217, 0, s[0:1]
	v_mul_f32_e32 v157, v121, v109
	v_mul_f32_e32 v158, v126, v114
	v_mul_f32_e32 v159, v122, v110
	v_mul_f32_e32 v168, v127, v115
	v_mul_f32_e32 v194, v155, v153
	v_mul_f32_e32 v155, v156, v153
	v_mov_b32_dpp v213, v154 row_ror:2 row_mask:0xf bank_mask:0xf
	v_mov_b32_e32 v221, 0
	v_mul_f32_e32 v152, v144, v152
	v_mul_f32_e32 v208, v157, v153
	v_mul_f32_e32 v156, v158, v153
	v_mul_f32_e32 v159, v159, v153
	v_mul_f32_e32 v157, v168, v153
	v_mov_b32_dpp v221, v155 row_ror:1 row_mask:0xf bank_mask:0xf
	v_cndmask_b32_e64 v153, v213, 0, s[8:9]
	v_fmac_f32_e32 v152, v148, v154
	v_mov_b32_e32 v219, 0
	v_fmac_f32_e32 v152, v140, v153
	v_cndmask_b32_e64 v153, v221, 0, s[0:1]
	v_mov_b32_dpp v219, v155 row_ror:2 row_mask:0xf bank_mask:0xf
	v_mul_f32_e32 v153, v145, v153
	v_mov_b32_e32 v216, 0
	v_cndmask_b32_e64 v154, v219, 0, s[8:9]
	v_fmac_f32_e32 v153, v149, v155
	v_mov_b32_dpp v216, v156 row_ror:1 row_mask:0xf bank_mask:0xf
	v_fmac_f32_e32 v153, v141, v154
	v_mov_b32_e32 v212, 0
	v_cndmask_b32_e64 v154, v216, 0, s[0:1]
	v_mov_b32_e32 v220, 0
	v_mov_b32_dpp v212, v156 row_ror:2 row_mask:0xf bank_mask:0xf
	v_mul_f32_e32 v154, v146, v154
	v_mov_b32_dpp v220, v157 row_ror:1 row_mask:0xf bank_mask:0xf
	v_cndmask_b32_e64 v155, v212, 0, s[8:9]
	v_fmac_f32_e32 v154, v150, v156
	v_mov_b32_e32 v218, 0
	v_fmac_f32_e32 v154, v142, v155
	v_cndmask_b32_e64 v155, v220, 0, s[0:1]
	v_mov_b32_dpp v218, v157 row_ror:2 row_mask:0xf bank_mask:0xf
	v_mul_f32_e32 v155, v147, v155
	v_cndmask_b32_e64 v156, v218, 0, s[8:9]
	v_fmac_f32_e32 v155, v151, v157
	v_mov_b32_dpp v197, v194 row_ror:1 row_mask:0xf bank_mask:0xf
	v_fmac_f32_e32 v155, v143, v156
	v_mov_b32_e32 v189, 0
	v_cndmask_b32_e64 v156, v197, 0, s[0:1]
	v_mov_b32_e32 v214, 0
	v_mov_b32_dpp v189, v194 row_ror:2 row_mask:0xf bank_mask:0xf
	v_mul_f32_e32 v156, v132, v156
	v_mov_b32_dpp v214, v208 row_ror:1 row_mask:0xf bank_mask:0xf
	v_cndmask_b32_e64 v157, v189, 0, s[8:9]
	v_fmac_f32_e32 v156, v136, v194
	v_fmac_f32_e32 v156, v128, v157
	v_cndmask_b32_e64 v157, v214, 0, s[0:1]
	v_mov_b32_e32 v209, 0
	v_mul_f32_e32 v157, v133, v157
	v_fmac_f32_e32 v157, v137, v208
	v_mov_b32_dpp v209, v208 row_ror:2 row_mask:0xf bank_mask:0xf
	v_mov_b32_e32 v208, 0
	v_cndmask_b32_e64 v158, v209, 0, s[8:9]
	v_fmac_f32_e32 v157, v129, v158
	v_mov_b32_dpp v208, v159 row_ror:1 row_mask:0xf bank_mask:0xf
	v_mov_b32_e32 v194, 0
	v_cndmask_b32_e64 v158, v208, 0, s[0:1]
	ds_bpermute_b32 v193, v207, v191
	ds_bpermute_b32 v192, v207, v190
	v_mov_b32_dpp v194, v159 row_ror:2 row_mask:0xf bank_mask:0xf
	v_mov_b32_e32 v215, 0
	v_mul_f32_e32 v158, v134, v158
	v_cndmask_b32_e64 v168, v194, 0, s[8:9]
	v_mov_b32_dpp v215, v222 row_ror:1 row_mask:0xf bank_mask:0xf
	v_fmac_f32_e32 v158, v138, v159
	v_mov_b32_dpp v211, v222 row_ror:2 row_mask:0xf bank_mask:0xf
	v_fmac_f32_e32 v158, v130, v168
	v_cndmask_b32_e64 v168, v215, 0, s[0:1]
	v_mul_f32_e32 v159, v139, v222
	v_cndmask_b32_e64 v223, v211, 0, s[8:9]
	v_fmac_f32_e32 v159, v135, v168
	v_cmp_gt_f32_e32 vcc, s84, v188
	v_fmac_f32_e32 v159, v131, v223
	s_and_saveexec_b64 s[10:11], s[4:5]
	s_xor_b64 s[10:11], exec, s[10:11]
	s_cbranch_execz .LBB0_1056
	v_mul_f32_e32 v152, v195, v152
	v_mul_f32_e32 v153, v195, v153
	v_cvt_pk_bf16_f32 v152, v152, v153
	v_mul_f32_e32 v153, v195, v154
	v_mul_f32_e32 v154, v195, v155
	v_cvt_pk_bf16_f32 v153, v153, v154
	v_mul_f32_e32 v154, v195, v156
	v_mul_f32_e32 v155, v195, v157
	v_cvt_pk_bf16_f32 v154, v154, v155
	v_mul_f32_e32 v155, v195, v158
	v_mul_f32_e32 v156, v195, v159
	v_cvt_pk_bf16_f32 v155, v155, v156
	v_lshlrev_b64 v[156:157], 12, v[186:187]
	v_lshl_add_u64 v[156:157], s[18:19], 0, v[156:157]
	v_lshl_add_u64 v[156:157], v[178:179], 1, v[156:157]
	global_store_dwordx4 v[156:157], v[152:155], off

; #define PG8_STAGE(bufoff, gbase, voff) do { _Pragma("unroll") for (int _i = 0; _i < 2; ++_i) \
;     __builtin_amdgcn_global_load_lds((const unsigned*)((const char*)(gbase) + (voff)[_i]), (LAS unsigned*)(lds + (bufoff) + ldsw + _i * 8192), 16, 0, 0); } while (0)
; #define PG8_LDA(dst, b, h) do { _Pragma("unroll") for (int m = 0; m < 4; ++m) _Pragma("unroll") for (int k = 0; k < 2; ++k) dst[m][k] = *(const LAS bf16x8*)(lds + PG8_SA(b, h) + aoff + m * 2048 + k * 1024); } while (0)
; #define PG8_LDB(dst, b, h) do { _Pragma("unroll") for (int n = 0; n < 2; ++n) _Pragma("unroll") for (int k = 0; k < 2; ++k) dst[n][k] = *(const LAS bf16x8*)(lds + PG8_SB(b, h) + boff + n * 2048 + k * 1024); } while (0)
; #define PG8_MMA(ai, bj, At, Bt) do { __builtin_amdgcn_s_setprio(1); _Pragma("unroll") for (int m = 0; m < 4; ++m) _Pragma("unroll") for (int n = 0; n < 2; ++n) _Pragma("unroll") for (int k = 0; k < 2; ++k) \
;     acc[ai][bj][m][n] = __builtin_amdgcn_mfma_f32_16x16x32_bf16(Bt[n][k], At[m][k], acc[ai][bj][m][n], 0, 0, 0); __builtin_amdgcn_s_setprio(0); } while (0)
; #define PG8_WAIT_V(n) asm volatile("s_waitcnt vmcnt(" #n ")" ::: "memory")
; template <class Epi, class Sched = StaticOrder>
; DI void gemm_phase(LAS unsigned char* lds, const Gemm g, const Sched& S, const Epi& E) {
;     ...
;     for (int t = 0; t < nt; t += 2) {
;       const bool last = (t == nt - 2);
;       const char* a1 = cA + (size_t)(t + 1) * kstep;
;       const char* a2 = last ? nA : cA + (size_t)(t + 2) * kstep; const char* b2 = last ? nB : cB + (size_t)(t + 2) * kstep;
;       const char* a3 = a2 + kstep; const char* b3 = b2 + kstep;
;       PG8_LDB(B0, 0, 0); PG8_SCHED; PG8_LDA(At, 0, 0); PG8_STAGE(PG8_SA(1, 1), a1 + hstep, voffA);
;       PG8_WAIT_L(8); PG8_BAR; PG8_WAIT_L(0); PG8_MMA(0, 0, At, B0); PG8_BAR; PG8_SCHED;
;       PG8_LDB(B1, 0, 1); PG8_STAGE(PG8_SB(0, 0), b2, voffB);
;       PG8_BAR; PG8_WAIT_L(0); PG8_MMA(0, 1, At, B1); PG8_BAR;
;       PG8_LDA(At, 0, 1); PG8_STAGE(PG8_SA(0, 0), a2, voffA);
;       PG8_BAR; PG8_WAIT_L(0); PG8_MMA(1, 0, At, B0); PG8_BAR; PG8_SCHED;
;       PG8_STAGE(PG8_SB(0, 1), b2 + hstep, voffB);
;       PG8_WAIT_V(6); PG8_BAR; PG8_MMA(1, 1, At, B1); PG8_BAR;
;       PG8_LDB(B0, 1, 0); PG8_SCHED; PG8_LDA(At, 1, 0); PG8_STAGE(PG8_SA(0, 1), a2 + hstep, voffA);
;       PG8_WAIT_L(8); PG8_BAR; PG8_WAIT_L(0); PG8_MMA(0, 0, At, B0); PG8_BAR; PG8_SCHED;
.LBB0_1194:
	s_add_i32 m0, s37, 0xc000
	ds_read_b128 v[144:147], v215
	ds_read_b128 v[148:151], v215 offset:1024
	ds_read_b128 v[152:155], v215 offset:2048
	ds_read_b128 v[156:159], v215 offset:3072
	ds_read_b128 v[160:163], v215 offset:4096
	ds_read_b128 v[164:167], v215 offset:5120
	ds_read_b128 v[168:171], v215 offset:6144
	ds_read_b128 v[172:175], v215 offset:7168
	global_load_lds_dwordx4 v184, s[22:23]
	s_add_i32 m0, s37, 0xe000
	s_nop 0
	global_load_lds_dwordx4 v186, s[22:23]
	s_waitcnt lgkmcnt(0)
	s_setprio 1
	s_barrier
	v_mfma_f32_16x16x32_bf16 v[124:127], v[128:131], v[144:147], v[124:127]
	v_mfma_f32_16x16x32_bf16 v[120:123], v[136:139], v[144:147], v[120:123]
	v_mfma_f32_16x16x32_bf16 v[108:111], v[128:131], v[152:155], v[108:111]
	v_mfma_f32_16x16x32_bf16 v[104:107], v[136:139], v[152:155], v[104:107]
	v_mfma_f32_16x16x32_bf16 v[92:95], v[128:131], v[160:163], v[92:95]
	v_mfma_f32_16x16x32_bf16 v[88:91], v[136:139], v[160:163], v[88:91]
	v_mfma_f32_16x16x32_bf16 v[76:79], v[128:131], v[168:171], v[76:79]
	v_mfma_f32_16x16x32_bf16 v[72:75], v[136:139], v[168:171], v[72:75]
	v_mfma_f32_16x16x32_bf16 v[124:127], v[132:135], v[148:151], v[124:127]
	v_mfma_f32_16x16x32_bf16 v[120:123], v[140:143], v[148:151], v[120:123]
	v_mfma_f32_16x16x32_bf16 v[108:111], v[132:135], v[156:159], v[108:111]
	v_mfma_f32_16x16x32_bf16 v[104:107], v[140:143], v[156:159], v[104:107]
	v_mfma_f32_16x16x32_bf16 v[92:95], v[132:135], v[164:167], v[92:95]
	v_mfma_f32_16x16x32_bf16 v[88:91], v[140:143], v[164:167], v[88:91]
	v_mfma_f32_16x16x32_bf16 v[76:79], v[132:135], v[172:175], v[76:79]
	v_mfma_f32_16x16x32_bf16 v[72:75], v[140:143], v[172:175], v[72:75]
	s_barrier
	s_setprio 0
	ds_read_b128 v[192:195], v216
	ds_read_b128 v[196:199], v216 offset:1024
	ds_read_b128 v[200:203], v216 offset:2048
	ds_read_b128 v[204:207], v216 offset:3072
	s_add_u32 s24, s22, 0xfff80080
	s_addc_u32 s25, s23, -1
	s_cmp_eq_u32 s54, 28
	s_cselect_b32 s27, s17, s25
	s_cselect_b32 s26, s43, s24
	s_cselect_b32 s25, s15, s53
	s_cselect_b32 s24, s51, s52
	s_add_i32 s55, s48, s35
	s_add_u32 s98, s24, 0x80
	s_addc_u32 s99, s25, 0
	s_add_u32 s100, s26, 0x80
	s_addc_u32 s101, s27, 0
	s_mov_b32 m0, s55
	s_nop 0
	global_load_lds_dwordx4 v180, s[24:25]
	s_add_i32 m0, s55, 0x2000
	s_nop 0
	global_load_lds_dwordx4 v176, s[24:25]
	s_waitcnt lgkmcnt(0)
	s_setprio 1
	s_barrier
	v_mfma_f32_16x16x32_bf16 v[116:119], v[192:195], v[144:147], v[116:119]
	v_mfma_f32_16x16x32_bf16 v[112:115], v[200:203], v[144:147], v[112:115]
	v_mfma_f32_16x16x32_bf16 v[100:103], v[192:195], v[152:155], v[100:103]
	v_mfma_f32_16x16x32_bf16 v[96:99], v[200:203], v[152:155], v[96:99]
	v_mfma_f32_16x16x32_bf16 v[84:87], v[192:195], v[160:163], v[84:87]
	v_mfma_f32_16x16x32_bf16 v[80:83], v[200:203], v[160:163], v[80:83]
	v_mfma_f32_16x16x32_bf16 v[68:71], v[192:195], v[168:171], v[68:71]
	v_mfma_f32_16x16x32_bf16 v[64:67], v[200:203], v[168:171], v[64:67]
	v_mfma_f32_16x16x32_bf16 v[116:119], v[196:199], v[148:151], v[116:119]
	v_mfma_f32_16x16x32_bf16 v[112:115], v[204:207], v[148:151], v[112:115]
	v_mfma_f32_16x16x32_bf16 v[100:103], v[196:199], v[156:159], v[100:103]
	v_mfma_f32_16x16x32_bf16 v[96:99], v[204:207], v[156:159], v[96:99]
	v_mfma_f32_16x16x32_bf16 v[84:87], v[196:199], v[164:167], v[84:87]
	v_mfma_f32_16x16x32_bf16 v[80:83], v[204:207], v[164:167], v[80:83]
	v_mfma_f32_16x16x32_bf16 v[68:71], v[196:199], v[172:175], v[68:71]
	v_mfma_f32_16x16x32_bf16 v[64:67], v[204:207], v[172:175], v[64:67]
	s_barrier
	s_setprio 0
	s_mov_b32 m0, s37
	ds_read_b128 v[144:147], v215 offset:16384
	ds_read_b128 v[148:151], v215 offset:17408
	ds_read_b128 v[152:155], v215 offset:18432
	ds_read_b128 v[156:159], v215 offset:19456
	ds_read_b128 v[160:163], v215 offset:20480
	ds_read_b128 v[164:167], v215 offset:21504
	ds_read_b128 v[168:171], v215 offset:22528
	ds_read_b128 v[172:175], v215 offset:23552
	global_load_lds_dwordx4 v182, s[26:27]
	s_mov_b32 m0, s38
	s_nop 0
	global_load_lds_dwordx4 v178, s[26:27]
	s_waitcnt vmcnt(10)
	s_waitcnt lgkmcnt(0)
	s_setprio 1
	s_barrier
	v_mfma_f32_16x16x32_bf16 v[60:63], v[128:131], v[144:147], v[60:63]
	v_mfma_f32_16x16x32_bf16 v[56:59], v[136:139], v[144:147], v[56:59]
	v_mfma_f32_16x16x32_bf16 v[44:47], v[128:131], v[152:155], v[44:47]
	v_mfma_f32_16x16x32_bf16 v[40:43], v[136:139], v[152:155], v[40:43]
	v_mfma_f32_16x16x32_bf16 v[28:31], v[128:131], v[160:163], v[28:31]
	v_mfma_f32_16x16x32_bf16 v[24:27], v[136:139], v[160:163], v[24:27]
	v_mfma_f32_16x16x32_bf16 v[12:15], v[128:131], v[168:171], v[12:15]
	v_mfma_f32_16x16x32_bf16 v[8:11], v[136:139], v[168:171], v[8:11]
	v_mfma_f32_16x16x32_bf16 v[60:63], v[132:135], v[148:151], v[60:63]
	v_mfma_f32_16x16x32_bf16 v[56:59], v[140:143], v[148:151], v[56:59]
	v_mfma_f32_16x16x32_bf16 v[44:47], v[132:135], v[156:159], v[44:47]
	v_mfma_f32_16x16x32_bf16 v[40:43], v[140:143], v[156:159], v[40:43]
	v_mfma_f32_16x16x32_bf16 v[28:31], v[132:135], v[164:167], v[28:31]
	v_mfma_f32_16x16x32_bf16 v[24:27], v[140:143], v[164:167], v[24:27]
	v_mfma_f32_16x16x32_bf16 v[12:15], v[132:135], v[172:175], v[12:15]
	v_mfma_f32_16x16x32_bf16 v[8:11], v[140:143], v[172:175], v[8:11]
	s_barrier
	s_setprio 0
	s_add_u32 s56, s24, 0x80000
	s_addc_u32 s57, s25, 0
	s_add_i32 s55, s49, s35
	s_mov_b32 m0, s55
	s_nop 0
	global_load_lds_dwordx4 v180, s[56:57]
	s_add_i32 m0, s55, 0x2000
	s_nop 0
	global_load_lds_dwordx4 v176, s[56:57]
	s_add_i32 s55, 0, 0x18000
	v_add_u32_e32 v140, s55, v212
	ds_read_b128 v[128:131], v140
	ds_read_b128 v[132:135], v140 offset:1024
	ds_read_b128 v[136:139], v140 offset:2048
	ds_read_b128 v[140:143], v140 offset:3072
	s_waitcnt vmcnt(6)
	s_setprio 1
	s_barrier
; #define PG8_STAGE(bufoff, gbase, voff) do { _Pragma("unroll") for (int _i = 0; _i < 2; ++_i) \
;     __builtin_amdgcn_global_load_lds((const unsigned*)((const char*)(gbase) + (voff)[_i]), (LAS unsigned*)(lds + (bufoff) + ldsw + _i * 8192), 16, 0, 0); } while (0)
; #define PG8_LDA(dst, b, h) do { _Pragma("unroll") for (int m = 0; m < 4; ++m) _Pragma("unroll") for (int k = 0; k < 2; ++k) dst[m][k] = *(const LAS bf16x8*)(lds + PG8_SA(b, h) + aoff + m * 2048 + k * 1024); } while (0)
; #define PG8_LDB(dst, b, h) do { _Pragma("unroll") for (int n = 0; n < 2; ++n) _Pragma("unroll") for (int k = 0; k < 2; ++k) dst[n][k] = *(const LAS bf16x8*)(lds + PG8_SB(b, h) + boff + n * 2048 + k * 1024); } while (0)
; #define PG8_MMA(ai, bj, At, Bt) do { __builtin_amdgcn_s_setprio(1); _Pragma("unroll") for (int m = 0; m < 4; ++m) _Pragma("unroll") for (int n = 0; n < 2; ++n) _Pragma("unroll") for (int k = 0; k < 2; ++k) \
;     acc[ai][bj][m][n] = __builtin_amdgcn_mfma_f32_16x16x32_bf16(Bt[n][k], At[m][k], acc[ai][bj][m][n], 0, 0, 0); __builtin_amdgcn_s_setprio(0); } while (0)
; #define PG8_WAIT_V(n) asm volatile("s_waitcnt vmcnt(" #n ")" ::: "memory")
; #define PG8_WAIT_L(n) asm volatile("s_waitcnt lgkmcnt(" #n ")" ::: "memory")
; #define PG8_BAR __builtin_amdgcn_s_barrier()
; #define PG8_SCHED __builtin_amdgcn_sched_barrier(0)
; template <class Epi, class Sched = StaticOrder>
; DI void gemm_phase(LAS unsigned char* lds, const Gemm g, const Sched& S, const Epi& E) {
;     ...
;       PG8_WAIT_V(6); PG8_BAR; PG8_MMA(1, 1, At, B1); PG8_BAR;
;       PG8_LDB(B0, 1, 0); PG8_SCHED; PG8_LDA(At, 1, 0); PG8_STAGE(PG8_SA(0, 1), a2 + hstep, voffA);
;       PG8_WAIT_L(8); PG8_BAR; PG8_WAIT_L(0); PG8_MMA(0, 0, At, B0); PG8_BAR; PG8_SCHED;
;       PG8_LDB(B1, 1, 1); PG8_STAGE(PG8_SB(1, 0), b3, voffB);
;       PG8_BAR; PG8_WAIT_L(0); PG8_MMA(0, 1, At, B1); PG8_BAR;
;       PG8_LDA(At, 1, 1); PG8_STAGE(PG8_SA(1, 0), a3, voffA);
;       PG8_BAR; PG8_WAIT_L(0); PG8_MMA(1, 0, At, B0); PG8_BAR; PG8_SCHED;
;       PG8_STAGE(PG8_SB(1, 1), b3 + hstep, voffB);
;       PG8_WAIT_V(6); PG8_BAR; PG8_MMA(1, 1, At, B1); PG8_BAR;
	v_mfma_f32_16x16x32_bf16 v[52:55], v[192:195], v[144:147], v[52:55]
	v_mfma_f32_16x16x32_bf16 v[48:51], v[200:203], v[144:147], v[48:51]
	v_mfma_f32_16x16x32_bf16 v[36:39], v[192:195], v[152:155], v[36:39]
	v_mfma_f32_16x16x32_bf16 v[32:35], v[200:203], v[152:155], v[32:35]
	v_mfma_f32_16x16x32_bf16 v[20:23], v[192:195], v[160:163], v[20:23]
	v_mfma_f32_16x16x32_bf16 v[16:19], v[200:203], v[160:163], v[16:19]
	v_mfma_f32_16x16x32_bf16 v[4:7], v[192:195], v[168:171], v[4:7]
	v_mfma_f32_16x16x32_bf16 v[0:3], v[200:203], v[168:171], v[0:3]
	v_mfma_f32_16x16x32_bf16 v[52:55], v[196:199], v[148:151], v[52:55]
	v_mfma_f32_16x16x32_bf16 v[48:51], v[204:207], v[148:151], v[48:51]
	v_mfma_f32_16x16x32_bf16 v[36:39], v[196:199], v[156:159], v[36:39]
	v_mfma_f32_16x16x32_bf16 v[32:35], v[204:207], v[156:159], v[32:35]
	v_mfma_f32_16x16x32_bf16 v[20:23], v[196:199], v[164:167], v[20:23]
	v_mfma_f32_16x16x32_bf16 v[16:19], v[204:207], v[164:167], v[16:19]
	v_mfma_f32_16x16x32_bf16 v[4:7], v[196:199], v[172:175], v[4:7]
	v_mfma_f32_16x16x32_bf16 v[0:3], v[204:207], v[172:175], v[0:3]
	s_barrier
	s_setprio 0
	s_add_u32 s26, s26, 0x80000
	s_addc_u32 s27, s27, 0
	s_mov_b32 m0, s39
	ds_read_b128 v[144:147], v215 offset:32768
	ds_read_b128 v[148:151], v215 offset:33792
	ds_read_b128 v[152:155], v215 offset:34816
	ds_read_b128 v[156:159], v215 offset:35840
	ds_read_b128 v[160:163], v215 offset:36864
	ds_read_b128 v[164:167], v215 offset:37888
	ds_read_b128 v[168:171], v215 offset:38912
	ds_read_b128 v[172:175], v215 offset:39936
	global_load_lds_dwordx4 v182, s[26:27]
	s_mov_b32 m0, s40
	s_nop 0
	global_load_lds_dwordx4 v178, s[26:27]
	s_waitcnt lgkmcnt(0)
	s_setprio 1
	s_barrier
	v_mfma_f32_16x16x32_bf16 v[124:127], v[128:131], v[144:147], v[124:127]
	v_mfma_f32_16x16x32_bf16 v[120:123], v[136:139], v[144:147], v[120:123]
	v_mfma_f32_16x16x32_bf16 v[108:111], v[128:131], v[152:155], v[108:111]
	v_mfma_f32_16x16x32_bf16 v[104:107], v[136:139], v[152:155], v[104:107]
	v_mfma_f32_16x16x32_bf16 v[92:95], v[128:131], v[160:163], v[92:95]
	v_mfma_f32_16x16x32_bf16 v[88:91], v[136:139], v[160:163], v[88:91]
	v_mfma_f32_16x16x32_bf16 v[76:79], v[128:131], v[168:171], v[76:79]
	v_mfma_f32_16x16x32_bf16 v[72:75], v[136:139], v[168:171], v[72:75]
	v_mfma_f32_16x16x32_bf16 v[124:127], v[132:135], v[148:151], v[124:127]
	v_mfma_f32_16x16x32_bf16 v[120:123], v[140:143], v[148:151], v[120:123]
	v_mfma_f32_16x16x32_bf16 v[108:111], v[132:135], v[156:159], v[108:111]
	v_mfma_f32_16x16x32_bf16 v[104:107], v[140:143], v[156:159], v[104:107]
	v_mfma_f32_16x16x32_bf16 v[92:95], v[132:135], v[164:167], v[92:95]
	v_mfma_f32_16x16x32_bf16 v[88:91], v[140:143], v[164:167], v[88:91]
	v_mfma_f32_16x16x32_bf16 v[76:79], v[132:135], v[172:175], v[76:79]
	v_mfma_f32_16x16x32_bf16 v[72:75], v[140:143], v[172:175], v[72:75]
	s_barrier
	s_setprio 0
	s_add_i32 s26, 0, 0x1c000
	s_add_i32 s27, s55, s35
	v_add_u32_e32 v204, s26, v212
	s_mov_b32 m0, s27
	ds_read_b128 v[192:195], v204
	ds_read_b128 v[196:199], v204 offset:1024
	ds_read_b128 v[200:203], v204 offset:2048
	ds_read_b128 v[204:207], v204 offset:3072
	global_load_lds_dwordx4 v180, s[98:99]
	s_add_i32 m0, s27, 0x2000
	s_nop 0
	global_load_lds_dwordx4 v176, s[98:99]
	s_waitcnt lgkmcnt(0)
	s_setprio 1
	s_barrier
	v_mfma_f32_16x16x32_bf16 v[116:119], v[192:195], v[144:147], v[116:119]
	v_mfma_f32_16x16x32_bf16 v[112:115], v[200:203], v[144:147], v[112:115]
	v_mfma_f32_16x16x32_bf16 v[100:103], v[192:195], v[152:155], v[100:103]
	v_mfma_f32_16x16x32_bf16 v[96:99], v[200:203], v[152:155], v[96:99]
	v_mfma_f32_16x16x32_bf16 v[84:87], v[192:195], v[160:163], v[84:87]
	v_mfma_f32_16x16x32_bf16 v[80:83], v[200:203], v[160:163], v[80:83]
	v_mfma_f32_16x16x32_bf16 v[68:71], v[192:195], v[168:171], v[68:71]
	v_mfma_f32_16x16x32_bf16 v[64:67], v[200:203], v[168:171], v[64:67]
	v_mfma_f32_16x16x32_bf16 v[116:119], v[196:199], v[148:151], v[116:119]
	v_mfma_f32_16x16x32_bf16 v[112:115], v[204:207], v[148:151], v[112:115]
	v_mfma_f32_16x16x32_bf16 v[100:103], v[196:199], v[156:159], v[100:103]
	v_mfma_f32_16x16x32_bf16 v[96:99], v[204:207], v[156:159], v[96:99]
	v_mfma_f32_16x16x32_bf16 v[84:87], v[196:199], v[164:167], v[84:87]
	v_mfma_f32_16x16x32_bf16 v[80:83], v[204:207], v[164:167], v[80:83]
	v_mfma_f32_16x16x32_bf16 v[68:71], v[196:199], v[172:175], v[68:71]
	v_mfma_f32_16x16x32_bf16 v[64:67], v[204:207], v[172:175], v[64:67]
	s_barrier
	s_setprio 0
	s_mov_b32 m0, s44
	ds_read_b128 v[144:147], v215 offset:49152
	ds_read_b128 v[148:151], v215 offset:50176
	ds_read_b128 v[152:155], v215 offset:51200
	ds_read_b128 v[156:159], v215 offset:52224
	ds_read_b128 v[160:163], v215 offset:53248
	ds_read_b128 v[164:167], v215 offset:54272
	ds_read_b128 v[168:171], v215 offset:55296
	ds_read_b128 v[172:175], v215 offset:56320
	global_load_lds_dwordx4 v182, s[100:101]
	s_mov_b32 m0, s45
	s_nop 0
	global_load_lds_dwordx4 v178, s[100:101]
	s_waitcnt vmcnt(10)
	s_waitcnt lgkmcnt(0)
	s_setprio 1
	s_barrier
	v_mfma_f32_16x16x32_bf16 v[60:63], v[128:131], v[144:147], v[60:63]
	v_mfma_f32_16x16x32_bf16 v[56:59], v[136:139], v[144:147], v[56:59]
	v_mfma_f32_16x16x32_bf16 v[44:47], v[128:131], v[152:155], v[44:47]
	v_mfma_f32_16x16x32_bf16 v[40:43], v[136:139], v[152:155], v[40:43]
	v_mfma_f32_16x16x32_bf16 v[28:31], v[128:131], v[160:163], v[28:31]
	v_mfma_f32_16x16x32_bf16 v[24:27], v[136:139], v[160:163], v[24:27]
	v_mfma_f32_16x16x32_bf16 v[12:15], v[128:131], v[168:171], v[12:15]
	v_mfma_f32_16x16x32_bf16 v[8:11], v[136:139], v[168:171], v[8:11]
	v_mfma_f32_16x16x32_bf16 v[60:63], v[132:135], v[148:151], v[60:63]
	v_mfma_f32_16x16x32_bf16 v[56:59], v[140:143], v[148:151], v[56:59]
	v_mfma_f32_16x16x32_bf16 v[44:47], v[132:135], v[156:159], v[44:47]
	v_mfma_f32_16x16x32_bf16 v[40:43], v[140:143], v[156:159], v[40:43]
	v_mfma_f32_16x16x32_bf16 v[28:31], v[132:135], v[164:167], v[28:31]
	v_mfma_f32_16x16x32_bf16 v[24:27], v[140:143], v[164:167], v[24:27]
	v_mfma_f32_16x16x32_bf16 v[12:15], v[132:135], v[172:175], v[12:15]
	v_mfma_f32_16x16x32_bf16 v[8:11], v[140:143], v[172:175], v[8:11]
	s_barrier
; DI unsigned pack2(float lo, float hi) { f32x2 v = {lo, hi}; bf16v2 r = __builtin_convertvector(v, bf16v2); return __builtin_bit_cast(unsigned, r); }
; #define PG8_STAGE(bufoff, gbase, voff) do { _Pragma("unroll") for (int _i = 0; _i < 2; ++_i) \
;     __builtin_amdgcn_global_load_lds((const unsigned*)((const char*)(gbase) + (voff)[_i]), (LAS unsigned*)(lds + (bufoff) + ldsw + _i * 8192), 16, 0, 0); } while (0)
; #define PG8_WAIT_V(n) asm volatile("s_waitcnt vmcnt(" #n ")" ::: "memory")
;   DI void operator()(const f32x4 (&acc)[2][2][4][2], const Unit& u, int wr, int wc, int fr, int fq) const {
;     const int row0 = u.pm * BM + wr * 64 + fr, col0 = u.pn * BM + wc * 32 + 8 * fq;
; #pragma unroll
;     for (int ai = 0; ai < 2; ++ai) {
;       f32x4 bv[4][2][2];
; #pragma unroll
;       for (int m = 0; m < 4; ++m)
; #pragma unroll
;         for (int bj = 0; bj < 2; ++bj) {
;           const float* bp = base + (size_t)(row0 + ai * HALF + m * 16) * 2048 + col0 + bj * HALF;
;           bv[m][bj][0] = *(const f32x4*)bp; bv[m][bj][1] = *(const f32x4*)(bp + 4);
;         }
; #pragma unroll
;       for (int m = 0; m < 4; ++m) {
;         const int row = row0 + ai * HALF + m * 16;
;         const size_t off = (size_t)row * 2048 + col0;
;         float ss = 0.f;
; #pragma unroll
;         for (int bj = 0; bj < 2; ++bj) {
;           const f32x4 v0 = acc[ai][bj][m][0] + bv[m][bj][0], v1 = acc[ai][bj][m][1] + bv[m][bj][1];
;           *(f32x4*)(C + off + bj * HALF) = v0; *(f32x4*)(C + off + bj * HALF + 4) = v1;
;           if (xb) {
;             u32x4 w; w.x = pack2(v0[0], v0[1]); w.y = pack2(v0[2], v0[3]); w.z = pack2(v1[0], v1[1]); w.w = pack2(v1[2], v1[3]);
;             *(u32x4*)(xb + off + bj * HALF) = w;
;             ss += v0[0] * v0[0] + v0[1] * v0[1] + v0[2] * v0[2] + v0[3] * v0[3] + v1[0] * v1[0] + v1[1] * v1[1] + v1[2] * v1[2] + v1[3] * v1[3];
;           }
;         }
;         if (xb) {
;           ss += __shfl_xor(ss, 16); ss += __shfl_xor(ss, 32);
;           if (fq == 0) ssq[(size_t)row * 32 + u.pn * 4 + wc] = ss;
;         }
; template <class Epi, class Sched = StaticOrder>
; DI void gemm_phase(LAS unsigned char* lds, const Gemm g, const Sched& S, const Epi& E) {
;     ...
;       PG8_STAGE(PG8_SB(1, 1), b3 + hstep, voffB);
;       PG8_WAIT_V(6); PG8_BAR; PG8_MMA(1, 1, At, B1); PG8_BAR;
;     }
;     E(acc, cur, wr, wc, fr, fq);
	s_setprio 0
	s_add_u32 s24, s24, 0x80080
	s_addc_u32 s25, s25, 0
	s_add_i32 s26, s26, s35
	s_mov_b32 m0, s26
	s_nop 0
	global_load_lds_dwordx4 v180, s[24:25]
	s_add_i32 m0, s26, 0x2000
	s_nop 0
	global_load_lds_dwordx4 v176, s[24:25]
	ds_read_b128 v[128:131], v214
	ds_read_b128 v[132:135], v214 offset:1024
	ds_read_b128 v[136:139], v214 offset:2048
	ds_read_b128 v[140:143], v214 offset:3072
	s_waitcnt vmcnt(6)
	s_setprio 1
	s_barrier
	v_mfma_f32_16x16x32_bf16 v[52:55], v[192:195], v[144:147], v[52:55]
	v_mfma_f32_16x16x32_bf16 v[48:51], v[200:203], v[144:147], v[48:51]
	v_mfma_f32_16x16x32_bf16 v[36:39], v[192:195], v[152:155], v[36:39]
	v_mfma_f32_16x16x32_bf16 v[32:35], v[200:203], v[152:155], v[32:35]
	v_mfma_f32_16x16x32_bf16 v[20:23], v[192:195], v[160:163], v[20:23]
	v_mfma_f32_16x16x32_bf16 v[16:19], v[200:203], v[160:163], v[16:19]
	v_mfma_f32_16x16x32_bf16 v[4:7], v[192:195], v[168:171], v[4:7]
	v_mfma_f32_16x16x32_bf16 v[0:3], v[200:203], v[168:171], v[0:3]
	v_mfma_f32_16x16x32_bf16 v[52:55], v[196:199], v[148:151], v[52:55]
	v_mfma_f32_16x16x32_bf16 v[48:51], v[204:207], v[148:151], v[48:51]
	v_mfma_f32_16x16x32_bf16 v[36:39], v[196:199], v[156:159], v[36:39]
	v_mfma_f32_16x16x32_bf16 v[32:35], v[204:207], v[156:159], v[32:35]
	v_mfma_f32_16x16x32_bf16 v[20:23], v[196:199], v[164:167], v[20:23]
	v_mfma_f32_16x16x32_bf16 v[16:19], v[204:207], v[164:167], v[16:19]
	v_mfma_f32_16x16x32_bf16 v[4:7], v[196:199], v[172:175], v[4:7]
	v_mfma_f32_16x16x32_bf16 v[0:3], v[204:207], v[172:175], v[0:3]
	s_add_i32 s54, s54, 2
	s_add_u32 s22, s22, 0x100
	s_addc_u32 s23, s23, 0
	s_add_u32 s52, s52, 0x100
	s_addc_u32 s53, s53, 0
	s_cmp_gt_u32 s54, 29
	s_barrier
	s_setprio 0
	s_cbranch_scc0 .LBB0_1194
	s_waitcnt lgkmcnt(0)
	v_lshl_add_u32 v194, s12, 8, v211
	v_lshl_or_b32 v192, s42, 8, v213
	v_readlane_b32 s52, v243, 3
	v_ashrrev_i32_e32 v193, 31, v192
	v_readlane_b32 s66, v243, 17
	v_readlane_b32 s67, v243, 18
	v_ashrrev_i32_e32 v195, 31, v194
	v_lshlrev_b64 v[128:129], 13, v[194:195]
	v_lshl_add_u64 v[196:197], v[192:193], 2, s[66:67]
	v_lshl_add_u64 v[236:237], v[196:197], 0, v[128:129]
	global_load_dwordx4 v[220:223], v[236:237], off
	global_load_dwordx4 v[224:227], v[236:237], off offset:16
	global_load_dwordx4 v[228:231], v[236:237], off offset:512
	global_load_dwordx4 v[232:235], v[236:237], off offset:528
	v_or_b32_e32 v206, 16, v194
	v_or_b32_e32 v202, 32, v194
	v_or_b32_e32 v198, 48, v194
	v_ashrrev_i32_e32 v207, 31, v206
	v_ashrrev_i32_e32 v203, 31, v202
	v_ashrrev_i32_e32 v199, 31, v198
	v_lshlrev_b64 v[128:129], 13, v[206:207]
	v_lshlrev_b64 v[130:131], 13, v[202:203]
	v_lshlrev_b64 v[132:133], 13, v[198:199]
	v_lshl_add_u64 v[208:209], v[196:197], 0, v[128:129]
	v_lshl_add_u64 v[204:205], v[196:197], 0, v[130:131]
	v_lshl_add_u64 v[200:201], v[196:197], 0, v[132:133]
	global_load_dwordx4 v[168:171], v[208:209], off offset:16
	global_load_dwordx4 v[172:175], v[208:209], off
	global_load_dwordx4 v[160:163], v[208:209], off offset:528
	global_load_dwordx4 v[164:167], v[208:209], off offset:512
	global_load_dwordx4 v[152:155], v[204:205], off offset:16
	global_load_dwordx4 v[156:159], v[204:205], off
	global_load_dwordx4 v[144:147], v[204:205], off offset:528
	global_load_dwordx4 v[148:151], v[204:205], off offset:512
	global_load_dwordx4 v[136:139], v[200:201], off offset:16
	global_load_dwordx4 v[140:143], v[200:201], off
	global_load_dwordx4 v[128:131], v[200:201], off offset:528
	global_load_dwordx4 v[132:135], v[200:201], off offset:512
	v_and_b32_e32 v218, 64, v217
	v_xor_b32_e32 v238, 16, v217
	v_add_u32_e32 v240, 64, v218
	v_xor_b32_e32 v239, 32, v217
	v_cmp_lt_i32_e32 vcc, v238, v240
	v_lshlrev_b64 v[218:219], 11, v[194:195]
	s_lshl_b32 s22, s42, 2
	v_cndmask_b32_e32 v241, v217, v238, vcc
	v_cmp_lt_i32_e32 vcc, v239, v240
	s_ashr_i32 s23, s22, 31
	v_readlane_b32 s53, v243, 4
	v_cndmask_b32_e32 v240, v217, v239, vcc
	v_lshl_add_u64 v[238:239], v[218:219], 0, v[192:193]
	v_lshlrev_b32_e32 v218, 2, v241
	v_lshl_add_u64 v[238:239], v[238:239], 1, s[2:3]
	v_readlane_b32 s54, v243, 5
	v_readlane_b32 s55, v243, 6
	v_readlane_b32 s56, v243, 7
	v_readlane_b32 s57, v243, 8
	v_readlane_b32 s58, v243, 9
	v_readlane_b32 s59, v243, 10
	v_readlane_b32 s60, v243, 11
	v_readlane_b32 s61, v243, 12
	v_readlane_b32 s62, v243, 13
	v_readlane_b32 s63, v243, 14
	v_readlane_b32 s64, v243, 15
	v_readlane_b32 s65, v243, 16
	s_waitcnt vmcnt(0)
	v_pk_add_f32 v[126:127], v[126:127], v[222:223]
	v_pk_add_f32 v[124:125], v[124:125], v[220:221]
	v_pk_add_f32 v[116:117], v[116:117], v[228:229]
	v_pk_add_f32 v[122:123], v[122:123], v[226:227]
	v_pk_add_f32 v[120:121], v[120:121], v[224:225]
	v_pk_add_f32 v[220:221], v[112:113], v[232:233]
	global_store_dwordx4 v[236:237], v[124:127], off
	global_store_dwordx4 v[236:237], v[120:123], off offset:16
	v_cvt_pk_bf16_f32 v112, v124, v125
	v_mul_f32_e32 v125, v125, v125
	v_mul_f32_e32 v219, v117, v117
	v_pk_add_f32 v[118:119], v[118:119], v[230:231]
	v_fmac_f32_e32 v125, v124, v124
	v_fmac_f32_e32 v219, v116, v116
	v_fmac_f32_e32 v125, v126, v126
	v_fmac_f32_e32 v219, v118, v118
	v_fmac_f32_e32 v125, v127, v127
	v_fmac_f32_e32 v219, v119, v119
	v_fmac_f32_e32 v125, v120, v120
	v_fmac_f32_e32 v219, v220, v220
	v_pk_add_f32 v[222:223], v[114:115], v[234:235]
	v_fmac_f32_e32 v125, v121, v121
	v_fmac_f32_e32 v219, v221, v221
	v_fmac_f32_e32 v125, v122, v122
	v_fmac_f32_e32 v219, v222, v222
	v_fmac_f32_e32 v125, v123, v123
	v_fmac_f32_e32 v219, v223, v223
	v_cvt_pk_bf16_f32 v114, v120, v121
	v_add_f32_e32 v121, v125, v219
	v_cvt_pk_bf16_f32 v115, v122, v123
	ds_bpermute_b32 v122, v218, v121
	v_cvt_pk_bf16_f32 v113, v126, v127
	global_store_dwordx4 v[238:239], v[112:115], off
	global_store_dwordx4 v[236:237], v[116:119], off offset:512
	global_store_dwordx4 v[236:237], v[220:223], off offset:528
	v_lshlrev_b32_e32 v126, 2, v240
	v_cvt_pk_bf16_f32 v120, v116, v117
	s_waitcnt lgkmcnt(0)
	v_add_f32_e32 v112, v121, v122
	ds_bpermute_b32 v113, v126, v112
	v_cvt_pk_bf16_f32 v121, v118, v119
	v_cvt_pk_bf16_f32 v122, v220, v221
	v_cvt_pk_bf16_f32 v123, v222, v223
	global_store_dwordx4 v[238:239], v[120:123], off offset:256
	s_and_saveexec_b64 s[24:25], s[0:1]
	s_cbranch_execz .LBB0_1197
	s_waitcnt lgkmcnt(0)
	v_add_f32_e32 v114, v112, v113
	v_lshlrev_b64 v[112:113], 7, v[194:195]
	v_lshl_add_u64 v[112:113], s[8:9], 0, v[112:113]
	v_lshl_add_u64 v[112:113], s[22:23], 2, v[112:113]
	s_lshl_b32 s12, s41, 2
	v_lshl_add_u64 v[112:113], v[112:113], 0, s[12:13]
	global_store_dword v[112:113], v114, off

; #define PG8_STAGE(bufoff, gbase, voff) do { _Pragma("unroll") for (int _i = 0; _i < 2; ++_i) \
;     __builtin_amdgcn_global_load_lds((const unsigned*)((const char*)(gbase) + (voff)[_i]), (LAS unsigned*)(lds + (bufoff) + ldsw + _i * 8192), 16, 0, 0); } while (0)
; #define PG8_LDA(dst, b, h) do { _Pragma("unroll") for (int m = 0; m < 4; ++m) _Pragma("unroll") for (int k = 0; k < 2; ++k) dst[m][k] = *(const LAS bf16x8*)(lds + PG8_SA(b, h) + aoff + m * 2048 + k * 1024); } while (0)
; #define PG8_LDB(dst, b, h) do { _Pragma("unroll") for (int n = 0; n < 2; ++n) _Pragma("unroll") for (int k = 0; k < 2; ++k) dst[n][k] = *(const LAS bf16x8*)(lds + PG8_SB(b, h) + boff + n * 2048 + k * 1024); } while (0)
; #define PG8_MMA(ai, bj, At, Bt) do { __builtin_amdgcn_s_setprio(1); _Pragma("unroll") for (int m = 0; m < 4; ++m) _Pragma("unroll") for (int n = 0; n < 2; ++n) _Pragma("unroll") for (int k = 0; k < 2; ++k) \
;     acc[ai][bj][m][n] = __builtin_amdgcn_mfma_f32_16x16x32_bf16(Bt[n][k], At[m][k], acc[ai][bj][m][n], 0, 0, 0); __builtin_amdgcn_s_setprio(0); } while (0)
; #define PG8_WAIT_V(n) asm volatile("s_waitcnt vmcnt(" #n ")" ::: "memory")
; template <class Epi, class Sched = StaticOrder>
; DI void gemm_phase(LAS unsigned char* lds, const Gemm g, const Sched& S, const Epi& E) {
;     ...
;     for (int t = 0; t < nt; t += 2) {
;       const bool last = (t == nt - 2);
;       const char* a1 = cA + (size_t)(t + 1) * kstep;
;       const char* a2 = last ? nA : cA + (size_t)(t + 2) * kstep; const char* b2 = last ? nB : cB + (size_t)(t + 2) * kstep;
;       const char* a3 = a2 + kstep; const char* b3 = b2 + kstep;
;       PG8_LDB(B0, 0, 0); PG8_SCHED; PG8_LDA(At, 0, 0); PG8_STAGE(PG8_SA(1, 1), a1 + hstep, voffA);
;       PG8_WAIT_L(8); PG8_BAR; PG8_WAIT_L(0); PG8_MMA(0, 0, At, B0); PG8_BAR; PG8_SCHED;
;       PG8_LDB(B1, 0, 1); PG8_STAGE(PG8_SB(0, 0), b2, voffB);
;       PG8_BAR; PG8_WAIT_L(0); PG8_MMA(0, 1, At, B1); PG8_BAR;
;       PG8_LDA(At, 0, 1); PG8_STAGE(PG8_SA(0, 0), a2, voffA);
;       PG8_BAR; PG8_WAIT_L(0); PG8_MMA(1, 0, At, B0); PG8_BAR; PG8_SCHED;
;       PG8_STAGE(PG8_SB(0, 1), b2 + hstep, voffB);
;       PG8_WAIT_V(6); PG8_BAR; PG8_MMA(1, 1, At, B1); PG8_BAR;
;       PG8_LDB(B0, 1, 0); PG8_SCHED; PG8_LDA(At, 1, 0); PG8_STAGE(PG8_SA(0, 1), a2 + hstep, voffA);
;       PG8_WAIT_L(8); PG8_BAR; PG8_WAIT_L(0); PG8_MMA(0, 0, At, B0); PG8_BAR; PG8_SCHED;
.LBB0_1277:
	s_add_i32 m0, s64, 0xc000
	ds_read_b128 v[80:83], v202
	ds_read_b128 v[84:87], v202 offset:1024
	ds_read_b128 v[88:91], v202 offset:2048
	ds_read_b128 v[92:95], v202 offset:3072
	ds_read_b128 v[180:183], v202 offset:4096
	ds_read_b128 v[184:187], v202 offset:5120
	ds_read_b128 v[188:191], v202 offset:6144
	ds_read_b128 v[192:195], v202 offset:7168
	global_load_lds_dwordx4 v170, s[14:15]
	s_add_i32 m0, s64, 0xe000
	s_nop 0
	global_load_lds_dwordx4 v172, s[14:15]
	s_waitcnt lgkmcnt(0)
	s_setprio 1
	s_barrier
	v_mfma_f32_16x16x32_bf16 v[156:159], v[64:67], v[80:83], v[156:159]
	v_mfma_f32_16x16x32_bf16 v[144:147], v[72:75], v[80:83], v[144:147]
	v_mfma_f32_16x16x32_bf16 v[140:143], v[64:67], v[88:91], v[140:143]
	v_mfma_f32_16x16x32_bf16 v[132:135], v[72:75], v[88:91], v[132:135]
	v_mfma_f32_16x16x32_bf16 v[124:127], v[64:67], v[180:183], v[124:127]
	v_mfma_f32_16x16x32_bf16 v[116:119], v[72:75], v[180:183], v[116:119]
	v_mfma_f32_16x16x32_bf16 v[112:115], v[64:67], v[188:191], v[112:115]
	v_mfma_f32_16x16x32_bf16 v[108:111], v[72:75], v[188:191], v[108:111]
	v_mfma_f32_16x16x32_bf16 v[156:159], v[68:71], v[84:87], v[156:159]
	v_mfma_f32_16x16x32_bf16 v[144:147], v[76:79], v[84:87], v[144:147]
	v_mfma_f32_16x16x32_bf16 v[140:143], v[68:71], v[92:95], v[140:143]
	v_mfma_f32_16x16x32_bf16 v[132:135], v[76:79], v[92:95], v[132:135]
	v_mfma_f32_16x16x32_bf16 v[124:127], v[68:71], v[184:187], v[124:127]
	v_mfma_f32_16x16x32_bf16 v[116:119], v[76:79], v[184:187], v[116:119]
	v_mfma_f32_16x16x32_bf16 v[112:115], v[68:71], v[192:195], v[112:115]
	v_mfma_f32_16x16x32_bf16 v[108:111], v[76:79], v[192:195], v[108:111]
	s_barrier
	s_setprio 0
	ds_read_b128 v[206:209], v203
	ds_read_b128 v[212:215], v203 offset:1024
	ds_read_b128 v[216:219], v203 offset:2048
	ds_read_b128 v[220:223], v203 offset:3072
	s_add_u32 s48, s14, 0xfff80080
	s_addc_u32 s49, s15, -1
	s_cmp_eq_u32 s58, 28
	s_cselect_b32 s51, s41, s49
	s_cselect_b32 s50, s42, s48
	s_cselect_b32 s49, s39, s53
	s_cselect_b32 s48, s43, s52
	s_add_i32 s59, s72, s62
	s_add_u32 s98, s48, 0x80
	s_addc_u32 s99, s49, 0
	s_add_u32 s100, s50, 0x80
	s_addc_u32 s101, s51, 0
	s_mov_b32 m0, s59
	s_nop 0
	global_load_lds_dwordx4 v164, s[48:49]
	s_add_i32 m0, s59, 0x2000
	s_nop 0
	global_load_lds_dwordx4 v160, s[48:49]
	s_waitcnt lgkmcnt(0)
	s_setprio 1
	s_barrier
	v_mfma_f32_16x16x32_bf16 v[152:155], v[206:209], v[80:83], v[152:155]
	v_mfma_f32_16x16x32_bf16 v[80:83], v[216:219], v[80:83], v[148:151]
	v_mfma_f32_16x16x32_bf16 v[152:155], v[212:215], v[84:87], v[152:155]
	v_mfma_f32_16x16x32_bf16 v[80:83], v[220:223], v[84:87], v[80:83]
	v_mfma_f32_16x16x32_bf16 v[84:87], v[206:209], v[88:91], v[136:139]
	v_mfma_f32_16x16x32_bf16 v[88:91], v[216:219], v[88:91], v[128:131]
	v_mfma_f32_16x16x32_bf16 v[104:107], v[216:219], v[180:183], v[104:107]
	v_mfma_f32_16x16x32_bf16 v[100:103], v[206:209], v[188:191], v[100:103]
	v_mfma_f32_16x16x32_bf16 v[96:99], v[216:219], v[188:191], v[96:99]
	v_mfma_f32_16x16x32_bf16 v[84:87], v[212:215], v[92:95], v[84:87]
	v_mfma_f32_16x16x32_bf16 v[88:91], v[220:223], v[92:95], v[88:91]
	v_mfma_f32_16x16x32_bf16 v[92:95], v[206:209], v[180:183], v[120:123]
	v_mfma_f32_16x16x32_bf16 v[104:107], v[220:223], v[184:187], v[104:107]
	v_mfma_f32_16x16x32_bf16 v[100:103], v[212:215], v[192:195], v[100:103]
	v_mfma_f32_16x16x32_bf16 v[96:99], v[220:223], v[192:195], v[96:99]
	v_mfma_f32_16x16x32_bf16 v[92:95], v[212:215], v[184:187], v[92:95]
	s_barrier
	s_setprio 0
	s_mov_b32 m0, s64
	ds_read_b128 v[120:123], v202 offset:16384
	ds_read_b128 v[128:131], v202 offset:17408
	ds_read_b128 v[136:139], v202 offset:18432
	ds_read_b128 v[148:151], v202 offset:19456
	ds_read_b128 v[180:183], v202 offset:20480
	ds_read_b128 v[184:187], v202 offset:21504
	ds_read_b128 v[188:191], v202 offset:22528
	ds_read_b128 v[192:195], v202 offset:23552
	global_load_lds_dwordx4 v166, s[50:51]
	s_mov_b32 m0, s65
	s_nop 0
	global_load_lds_dwordx4 v162, s[50:51]
	s_waitcnt vmcnt(10)
	s_waitcnt lgkmcnt(0)
	s_setprio 1
	s_barrier
	v_mfma_f32_16x16x32_bf16 v[60:63], v[64:67], v[120:123], v[60:63]
	v_mfma_f32_16x16x32_bf16 v[48:51], v[72:75], v[120:123], v[48:51]
	v_mfma_f32_16x16x32_bf16 v[44:47], v[64:67], v[136:139], v[44:47]
	v_mfma_f32_16x16x32_bf16 v[36:39], v[72:75], v[136:139], v[36:39]
	v_mfma_f32_16x16x32_bf16 v[28:31], v[64:67], v[180:183], v[28:31]
	v_mfma_f32_16x16x32_bf16 v[20:23], v[72:75], v[180:183], v[20:23]
	v_mfma_f32_16x16x32_bf16 v[16:19], v[64:67], v[188:191], v[16:19]
	v_mfma_f32_16x16x32_bf16 v[12:15], v[72:75], v[188:191], v[12:15]
	v_mfma_f32_16x16x32_bf16 v[60:63], v[68:71], v[128:131], v[60:63]
	v_mfma_f32_16x16x32_bf16 v[48:51], v[76:79], v[128:131], v[48:51]
	v_mfma_f32_16x16x32_bf16 v[44:47], v[68:71], v[148:151], v[44:47]
	v_mfma_f32_16x16x32_bf16 v[36:39], v[76:79], v[148:151], v[36:39]
	v_mfma_f32_16x16x32_bf16 v[28:31], v[68:71], v[184:187], v[28:31]
	v_mfma_f32_16x16x32_bf16 v[20:23], v[76:79], v[184:187], v[20:23]
	v_mfma_f32_16x16x32_bf16 v[16:19], v[68:71], v[192:195], v[16:19]
	v_mfma_f32_16x16x32_bf16 v[12:15], v[76:79], v[192:195], v[12:15]
	s_barrier
	s_setprio 0
	s_add_u32 s78, s48, 0x80000
	s_addc_u32 s79, s49, 0
	s_add_i32 s59, s73, s62
	s_mov_b32 m0, s59
	s_nop 0
	global_load_lds_dwordx4 v164, s[78:79]
	s_add_i32 m0, s59, 0x2000
	s_nop 0
	global_load_lds_dwordx4 v160, s[78:79]
	s_add_i32 s59, 0, 0x18000
	v_add_u32_e32 v76, s59, v198
	ds_read_b128 v[64:67], v76
	ds_read_b128 v[68:71], v76 offset:1024
	ds_read_b128 v[72:75], v76 offset:2048
	ds_read_b128 v[76:79], v76 offset:3072
	s_waitcnt vmcnt(6)
	s_setprio 1
	s_barrier
; #define PG8_STAGE(bufoff, gbase, voff) do { _Pragma("unroll") for (int _i = 0; _i < 2; ++_i) \
;     __builtin_amdgcn_global_load_lds((const unsigned*)((const char*)(gbase) + (voff)[_i]), (LAS unsigned*)(lds + (bufoff) + ldsw + _i * 8192), 16, 0, 0); } while (0)
; #define PG8_LDA(dst, b, h) do { _Pragma("unroll") for (int m = 0; m < 4; ++m) _Pragma("unroll") for (int k = 0; k < 2; ++k) dst[m][k] = *(const LAS bf16x8*)(lds + PG8_SA(b, h) + aoff + m * 2048 + k * 1024); } while (0)
; #define PG8_LDB(dst, b, h) do { _Pragma("unroll") for (int n = 0; n < 2; ++n) _Pragma("unroll") for (int k = 0; k < 2; ++k) dst[n][k] = *(const LAS bf16x8*)(lds + PG8_SB(b, h) + boff + n * 2048 + k * 1024); } while (0)
; #define PG8_MMA(ai, bj, At, Bt) do { __builtin_amdgcn_s_setprio(1); _Pragma("unroll") for (int m = 0; m < 4; ++m) _Pragma("unroll") for (int n = 0; n < 2; ++n) _Pragma("unroll") for (int k = 0; k < 2; ++k) \
;     acc[ai][bj][m][n] = __builtin_amdgcn_mfma_f32_16x16x32_bf16(Bt[n][k], At[m][k], acc[ai][bj][m][n], 0, 0, 0); __builtin_amdgcn_s_setprio(0); } while (0)
; #define PG8_WAIT_V(n) asm volatile("s_waitcnt vmcnt(" #n ")" ::: "memory")
; #define PG8_WAIT_L(n) asm volatile("s_waitcnt lgkmcnt(" #n ")" ::: "memory")
; #define PG8_BAR __builtin_amdgcn_s_barrier()
; #define PG8_SCHED __builtin_amdgcn_sched_barrier(0)
; template <class Epi, class Sched = StaticOrder>
; DI void gemm_phase(LAS unsigned char* lds, const Gemm g, const Sched& S, const Epi& E) {
;     ...
;       PG8_WAIT_V(6); PG8_BAR; PG8_MMA(1, 1, At, B1); PG8_BAR;
;       PG8_LDB(B0, 1, 0); PG8_SCHED; PG8_LDA(At, 1, 0); PG8_STAGE(PG8_SA(0, 1), a2 + hstep, voffA);
;       PG8_WAIT_L(8); PG8_BAR; PG8_WAIT_L(0); PG8_MMA(0, 0, At, B0); PG8_BAR; PG8_SCHED;
;       PG8_LDB(B1, 1, 1); PG8_STAGE(PG8_SB(1, 0), b3, voffB);
;       PG8_BAR; PG8_WAIT_L(0); PG8_MMA(0, 1, At, B1); PG8_BAR;
;       PG8_LDA(At, 1, 1); PG8_STAGE(PG8_SA(1, 0), a3, voffA);
;       PG8_BAR; PG8_WAIT_L(0); PG8_MMA(1, 0, At, B0); PG8_BAR; PG8_SCHED;
;       PG8_STAGE(PG8_SB(1, 1), b3 + hstep, voffB);
;       PG8_WAIT_V(6); PG8_BAR; PG8_MMA(1, 1, At, B1); PG8_BAR;
	v_mfma_f32_16x16x32_bf16 v[56:59], v[206:209], v[120:123], v[56:59]
	v_mfma_f32_16x16x32_bf16 v[52:55], v[216:219], v[120:123], v[52:55]
	v_mfma_f32_16x16x32_bf16 v[40:43], v[206:209], v[136:139], v[40:43]
	v_mfma_f32_16x16x32_bf16 v[32:35], v[216:219], v[136:139], v[32:35]
	v_mfma_f32_16x16x32_bf16 v[24:27], v[206:209], v[180:183], v[24:27]
	v_mfma_f32_16x16x32_bf16 v[8:11], v[216:219], v[180:183], v[8:11]
	v_mfma_f32_16x16x32_bf16 v[4:7], v[206:209], v[188:191], v[4:7]
	v_mfma_f32_16x16x32_bf16 v[0:3], v[216:219], v[188:191], v[0:3]
	v_mfma_f32_16x16x32_bf16 v[56:59], v[212:215], v[128:131], v[56:59]
	v_mfma_f32_16x16x32_bf16 v[52:55], v[220:223], v[128:131], v[52:55]
	v_mfma_f32_16x16x32_bf16 v[40:43], v[212:215], v[148:151], v[40:43]
	v_mfma_f32_16x16x32_bf16 v[32:35], v[220:223], v[148:151], v[32:35]
	v_mfma_f32_16x16x32_bf16 v[24:27], v[212:215], v[184:187], v[24:27]
	v_mfma_f32_16x16x32_bf16 v[8:11], v[220:223], v[184:187], v[8:11]
	v_mfma_f32_16x16x32_bf16 v[4:7], v[212:215], v[192:195], v[4:7]
	v_mfma_f32_16x16x32_bf16 v[0:3], v[220:223], v[192:195], v[0:3]
	s_barrier
	s_setprio 0
	s_add_u32 s50, s50, 0x80000
	s_addc_u32 s51, s51, 0
	s_mov_b32 m0, s66
	ds_read_b128 v[120:123], v202 offset:32768
	ds_read_b128 v[128:131], v202 offset:33792
	ds_read_b128 v[180:183], v202 offset:34816
	ds_read_b128 v[184:187], v202 offset:35840
	ds_read_b128 v[188:191], v202 offset:36864
	ds_read_b128 v[192:195], v202 offset:37888
	ds_read_b128 v[206:209], v202 offset:38912
	ds_read_b128 v[212:215], v202 offset:39936
	global_load_lds_dwordx4 v166, s[50:51]
	s_mov_b32 m0, s67
	s_nop 0
	global_load_lds_dwordx4 v162, s[50:51]
	s_waitcnt lgkmcnt(0)
	s_setprio 1
	s_barrier
	v_mfma_f32_16x16x32_bf16 v[136:139], v[64:67], v[120:123], v[156:159]
	v_mfma_f32_16x16x32_bf16 v[156:159], v[68:71], v[128:131], v[136:139]
	v_mfma_f32_16x16x32_bf16 v[136:139], v[72:75], v[120:123], v[144:147]
	v_mfma_f32_16x16x32_bf16 v[144:147], v[76:79], v[128:131], v[136:139]
	v_mfma_f32_16x16x32_bf16 v[136:139], v[64:67], v[180:183], v[140:143]
	v_mfma_f32_16x16x32_bf16 v[132:135], v[72:75], v[180:183], v[132:135]
	v_mfma_f32_16x16x32_bf16 v[124:127], v[64:67], v[188:191], v[124:127]
	v_mfma_f32_16x16x32_bf16 v[116:119], v[72:75], v[188:191], v[116:119]
	v_mfma_f32_16x16x32_bf16 v[112:115], v[64:67], v[206:209], v[112:115]
	v_mfma_f32_16x16x32_bf16 v[108:111], v[72:75], v[206:209], v[108:111]
	v_mfma_f32_16x16x32_bf16 v[140:143], v[68:71], v[184:187], v[136:139]
	v_mfma_f32_16x16x32_bf16 v[132:135], v[76:79], v[184:187], v[132:135]
	v_mfma_f32_16x16x32_bf16 v[124:127], v[68:71], v[192:195], v[124:127]
	v_mfma_f32_16x16x32_bf16 v[116:119], v[76:79], v[192:195], v[116:119]
	v_mfma_f32_16x16x32_bf16 v[112:115], v[68:71], v[212:215], v[112:115]
	v_mfma_f32_16x16x32_bf16 v[108:111], v[76:79], v[212:215], v[108:111]
	s_barrier
	s_setprio 0
	s_add_i32 s50, 0, 0x1c000
	v_add_u32_e32 v136, s50, v198
	s_add_i32 s51, s59, s62
	ds_read_b128 v[216:219], v136
	ds_read_b128 v[220:223], v136 offset:1024
	ds_read_b128 v[224:227], v136 offset:2048
	ds_read_b128 v[228:231], v136 offset:3072
	s_mov_b32 m0, s51
	s_nop 0
	global_load_lds_dwordx4 v164, s[98:99]
	s_add_i32 m0, s51, 0x2000
	s_nop 0
	global_load_lds_dwordx4 v160, s[98:99]
	s_waitcnt lgkmcnt(0)
	s_setprio 1
	s_barrier
	v_mfma_f32_16x16x32_bf16 v[80:83], v[224:227], v[120:123], v[80:83]
	v_mfma_f32_16x16x32_bf16 v[136:139], v[216:219], v[120:123], v[152:155]
	v_mfma_f32_16x16x32_bf16 v[148:151], v[228:231], v[128:131], v[80:83]
	v_mfma_f32_16x16x32_bf16 v[80:83], v[216:219], v[180:183], v[84:87]
	v_mfma_f32_16x16x32_bf16 v[152:155], v[220:223], v[128:131], v[136:139]
	v_mfma_f32_16x16x32_bf16 v[136:139], v[220:223], v[184:187], v[80:83]
	v_mfma_f32_16x16x32_bf16 v[80:83], v[224:227], v[180:183], v[88:91]
	v_mfma_f32_16x16x32_bf16 v[128:131], v[228:231], v[184:187], v[80:83]
	v_mfma_f32_16x16x32_bf16 v[80:83], v[216:219], v[188:191], v[92:95]
	v_mfma_f32_16x16x32_bf16 v[120:123], v[220:223], v[192:195], v[80:83]
	v_mfma_f32_16x16x32_bf16 v[80:83], v[224:227], v[188:191], v[104:107]
	v_mfma_f32_16x16x32_bf16 v[104:107], v[228:231], v[192:195], v[80:83]
	v_mfma_f32_16x16x32_bf16 v[80:83], v[216:219], v[206:209], v[100:103]
	v_mfma_f32_16x16x32_bf16 v[100:103], v[220:223], v[212:215], v[80:83]
	v_mfma_f32_16x16x32_bf16 v[80:83], v[224:227], v[206:209], v[96:99]
	v_mfma_f32_16x16x32_bf16 v[96:99], v[228:231], v[212:215], v[80:83]
	s_barrier
	s_setprio 0
	s_mov_b32 m0, s55
	s_nop 2
	ds_read_b128 v[80:83], v202 offset:49152
	ds_read_b128 v[84:87], v202 offset:50176
	ds_read_b128 v[88:91], v202 offset:51200
	ds_read_b128 v[92:95], v202 offset:52224
	ds_read_b128 v[180:183], v202 offset:53248
	ds_read_b128 v[184:187], v202 offset:54272
	ds_read_b128 v[188:191], v202 offset:55296
	ds_read_b128 v[192:195], v202 offset:56320
	global_load_lds_dwordx4 v166, s[100:101]
	s_mov_b32 m0, s68
	s_nop 0
	global_load_lds_dwordx4 v162, s[100:101]
	s_waitcnt vmcnt(10)
	s_waitcnt lgkmcnt(0)
	s_setprio 1
	s_barrier
	v_mfma_f32_16x16x32_bf16 v[60:63], v[64:67], v[80:83], v[60:63]
	v_mfma_f32_16x16x32_bf16 v[48:51], v[72:75], v[80:83], v[48:51]
	v_mfma_f32_16x16x32_bf16 v[44:47], v[64:67], v[88:91], v[44:47]
	v_mfma_f32_16x16x32_bf16 v[36:39], v[72:75], v[88:91], v[36:39]
	v_mfma_f32_16x16x32_bf16 v[28:31], v[64:67], v[180:183], v[28:31]
	v_mfma_f32_16x16x32_bf16 v[20:23], v[72:75], v[180:183], v[20:23]
	v_mfma_f32_16x16x32_bf16 v[16:19], v[64:67], v[188:191], v[16:19]
	v_mfma_f32_16x16x32_bf16 v[12:15], v[72:75], v[188:191], v[12:15]
	v_mfma_f32_16x16x32_bf16 v[60:63], v[68:71], v[84:87], v[60:63]
	v_mfma_f32_16x16x32_bf16 v[48:51], v[76:79], v[84:87], v[48:51]
	v_mfma_f32_16x16x32_bf16 v[44:47], v[68:71], v[92:95], v[44:47]
	v_mfma_f32_16x16x32_bf16 v[36:39], v[76:79], v[92:95], v[36:39]
	v_mfma_f32_16x16x32_bf16 v[28:31], v[68:71], v[184:187], v[28:31]
	v_mfma_f32_16x16x32_bf16 v[20:23], v[76:79], v[184:187], v[20:23]
	v_mfma_f32_16x16x32_bf16 v[16:19], v[68:71], v[192:195], v[16:19]
	v_mfma_f32_16x16x32_bf16 v[12:15], v[76:79], v[192:195], v[12:15]
	s_barrier
; DI float dpp_ror1(float v) { return __int_as_float(__builtin_amdgcn_update_dpp(0, __float_as_int(v), 0x121, 0xf, 0xf, false)); }
; DI float dpp_ror2(float v) { return __int_as_float(__builtin_amdgcn_update_dpp(0, __float_as_int(v), 0x122, 0xf, 0xf, false)); }
; #define PG8_STAGE(bufoff, gbase, voff) do { _Pragma("unroll") for (int _i = 0; _i < 2; ++_i) \
;     __builtin_amdgcn_global_load_lds((const unsigned*)((const char*)(gbase) + (voff)[_i]), (LAS unsigned*)(lds + (bufoff) + ldsw + _i * 8192), 16, 0, 0); } while (0)
; #define PG8_WAIT_V(n) asm volatile("s_waitcnt vmcnt(" #n ")" ::: "memory")
; #define PG8_BAR __builtin_amdgcn_s_barrier()
;   DI void operator()(const f32x4 (&acc)[2][2][4][2], const Unit& u, int wr, int wc, int fr, int fq) const {
;     const int col = u.pn * 128 + wc * 32 + 8 * fq;
;     float w0[8], w1[8], w2[8], bb[8];
; #pragma unroll
;     for (int e = 0; e < 8; ++e) { w0[e] = cw[col + e]; w1[e] = cw[5632 + col + e]; w2[e] = cw[2 * 5632 + col + e]; bb[e] = cb[col + e]; }
; #pragma unroll
;     for (int ai = 0; ai < 2; ++ai) {
;       const int row0 = u.pm * BM + ai * HALF + wr * 64, span = row0 >> 6;
;       float rsv[4];
; #pragma unroll
;       for (int m = 0; m < 4; ++m) rsv[m] = row_rstd(ssq, row0 + 16 * m + fr, fq);
;       float p1[8], p2[8];
; #pragma unroll
;       for (int e = 0; e < 8; ++e) { p1[e] = 0.f; p2[e] = 0.f; }
; #pragma unroll
;       for (int m = 0; m < 4; ++m) {
;         float g[8], uu[8], a[8];
;         const float rs = rsv[m];
; #pragma unroll
;         for (int e = 0; e < 4; ++e) { g[e] = acc[ai][0][m][0][e] * rs; g[4 + e] = acc[ai][0][m][1][e] * rs; uu[e] = acc[ai][1][m][0][e] * rs; uu[4 + e] = acc[ai][1][m][1][e] * rs; }
; #pragma unroll
;         for (int e = 0; e < 8; ++e) {
;           const float x1 = dpp_ror1(g[e]), x2 = dpp_ror2(g[e]);
;           const float pr1 = (fr == 0) ? p1[e] : x1, pr2 = (fr < 2) ? p2[e] : x2;
;           a[e] = w2[e] * g[e] + w1[e] * pr1 + w0[e] * pr2 + bb[e];
; template <class Epi, class Sched = StaticOrder>
; DI void gemm_phase(LAS unsigned char* lds, const Gemm g, const Sched& S, const Epi& E) {
;     ...
;       PG8_STAGE(PG8_SB(1, 1), b3 + hstep, voffB);
;       PG8_WAIT_V(6); PG8_BAR; PG8_MMA(1, 1, At, B1); PG8_BAR;
;     }
;     E(acc, cur, wr, wc, fr, fq);
	s_setprio 0
	s_add_u32 s48, s48, 0x80080
	s_addc_u32 s49, s49, 0
	s_add_i32 s50, s50, s62
	s_mov_b32 m0, s50
	s_nop 0
	global_load_lds_dwordx4 v164, s[48:49]
	s_add_i32 m0, s50, 0x2000
	s_nop 0
	global_load_lds_dwordx4 v160, s[48:49]
	ds_read_b128 v[64:67], v201
	ds_read_b128 v[68:71], v201 offset:1024
	ds_read_b128 v[72:75], v201 offset:2048
	ds_read_b128 v[76:79], v201 offset:3072
	s_waitcnt vmcnt(6)
	s_setprio 1
	s_barrier
	v_mfma_f32_16x16x32_bf16 v[56:59], v[216:219], v[80:83], v[56:59]
	v_mfma_f32_16x16x32_bf16 v[52:55], v[224:227], v[80:83], v[52:55]
	v_mfma_f32_16x16x32_bf16 v[40:43], v[216:219], v[88:91], v[40:43]
	v_mfma_f32_16x16x32_bf16 v[32:35], v[224:227], v[88:91], v[32:35]
	v_mfma_f32_16x16x32_bf16 v[24:27], v[216:219], v[180:183], v[24:27]
	v_mfma_f32_16x16x32_bf16 v[8:11], v[224:227], v[180:183], v[8:11]
	v_mfma_f32_16x16x32_bf16 v[4:7], v[216:219], v[188:191], v[4:7]
	v_mfma_f32_16x16x32_bf16 v[0:3], v[224:227], v[188:191], v[0:3]
	v_mfma_f32_16x16x32_bf16 v[56:59], v[220:223], v[84:87], v[56:59]
	v_mfma_f32_16x16x32_bf16 v[52:55], v[228:231], v[84:87], v[52:55]
	v_mfma_f32_16x16x32_bf16 v[40:43], v[220:223], v[92:95], v[40:43]
	v_mfma_f32_16x16x32_bf16 v[32:35], v[228:231], v[92:95], v[32:35]
	v_mfma_f32_16x16x32_bf16 v[24:27], v[220:223], v[184:187], v[24:27]
	v_mfma_f32_16x16x32_bf16 v[8:11], v[228:231], v[184:187], v[8:11]
	v_mfma_f32_16x16x32_bf16 v[4:7], v[220:223], v[192:195], v[4:7]
	v_mfma_f32_16x16x32_bf16 v[0:3], v[228:231], v[192:195], v[0:3]
	s_add_i32 s58, s58, 2
	s_add_u32 s14, s14, 0x100
	s_addc_u32 s15, s15, 0
	s_add_u32 s52, s52, 0x100
	s_addc_u32 s53, s53, 0
	s_cmp_gt_u32 s58, 29
	s_barrier
	s_setprio 0
	s_cbranch_scc0 .LBB0_1277
	s_waitcnt lgkmcnt(0)
	s_lshl_b32 s39, s12, 8
	s_add_i32 s39, s39, s54
	v_or_b32_e32 v190, s39, v179
	v_ashrrev_i32_e32 v191, 31, v190
	v_lshlrev_b64 v[64:65], 7, v[190:191]
	v_or_b32_e32 v188, 16, v190
	v_lshl_add_u64 v[64:65], v[168:169], 0, v[64:65]
	v_ashrrev_i32_e32 v189, 31, v188
	global_load_dwordx4 v[192:195], v[64:65], off
	global_load_dwordx4 v[206:209], v[64:65], off offset:16
	v_lshlrev_b64 v[64:65], 7, v[188:189]
	v_lshl_add_u64 v[64:65], v[168:169], 0, v[64:65]
	global_load_dwordx4 v[212:215], v[64:65], off
	global_load_dwordx4 v[216:219], v[64:65], off offset:16
	v_or_b32_e32 v186, 32, v190
	v_ashrrev_i32_e32 v187, 31, v186
	v_lshlrev_b64 v[64:65], 7, v[186:187]
	v_or_b32_e32 v184, 48, v190
	v_lshl_add_u64 v[64:65], v[168:169], 0, v[64:65]
	v_ashrrev_i32_e32 v185, 31, v184
	global_load_dwordx4 v[220:223], v[64:65], off
	global_load_dwordx4 v[224:227], v[64:65], off offset:16
	v_lshlrev_b64 v[64:65], 7, v[184:185]
	v_lshl_add_u64 v[64:65], v[168:169], 0, v[64:65]
	global_load_dwordx4 v[228:231], v[64:65], off
	global_load_dwordx4 v[232:235], v[64:65], off offset:16
	v_lshl_or_b32 v180, s13, 7, v200
	v_and_b32_e32 v65, 64, v204
	v_xor_b32_e32 v64, 16, v204
	v_ashrrev_i32_e32 v181, 31, v180
	v_add_u32_e32 v65, 64, v65
	v_xor_b32_e32 v66, 32, v204
	v_lshlrev_b64 v[182:183], 2, v[180:181]
	v_cmp_lt_i32_e32 vcc, v64, v65
	v_lshl_add_u64 v[88:89], s[16:17], 0, v[182:183]
	v_lshl_add_u64 v[72:73], s[18:19], 0, v[182:183]
	v_cndmask_b32_e32 v64, v204, v64, vcc
	v_cmp_lt_i32_e32 vcc, v66, v65
	v_lshl_add_u64 v[74:75], v[88:89], 0, s[30:31]
	v_lshl_add_u64 v[76:77], v[88:89], 0, s[34:35]
	v_cndmask_b32_e32 v65, v204, v66, vcc
	v_add_co_u32_e32 v90, vcc, 0x5000, v88
	v_lshlrev_b32_e32 v187, 2, v64
	s_nop 0
	v_addc_co_u32_e32 v91, vcc, 0, v89, vcc
	v_add_co_u32_e32 v92, vcc, 0xb000, v88
	v_lshlrev_b32_e32 v185, 2, v65
	s_nop 0
	v_addc_co_u32_e32 v93, vcc, 0, v89, vcc
	global_load_dwordx4 v[64:67], v[88:89], off offset:16
	global_load_dwordx4 v[80:83], v[88:89], off
	global_load_dwordx4 v[68:71], v[72:73], off offset:16
	global_load_dwordx4 v[84:87], v[72:73], off
	s_nop 0
	global_load_dwordx4 v[72:75], v[74:75], off offset:16
	s_nop 0
	global_load_dwordx4 v[76:79], v[76:77], off offset:16
	s_nop 0
	global_load_dwordx4 v[88:91], v[90:91], off offset:2048
	s_nop 0
	global_load_dwordx4 v[92:95], v[92:93], off
	v_mov_b32_e32 v211, 0
	v_mov_b32_e32 v205, 0
	s_waitcnt vmcnt(0)
	v_mov_b32_e32 v196, v192
	v_mov_b32_e32 v197, v206
	v_mov_b32_e32 v206, v193
	v_mov_b32_e32 v192, v194
	v_mov_b32_e32 v193, v208
	v_mov_b32_e32 v208, v195
	v_pk_add_f32 v[194:195], v[196:197], v[206:207]
	v_pk_add_f32 v[192:193], v[192:193], v[208:209]
	v_mov_b32_e32 v196, v212
	v_mov_b32_e32 v197, v216
	v_mov_b32_e32 v216, v213
	v_mov_b32_e32 v206, v214
	v_mov_b32_e32 v207, v218
	v_mov_b32_e32 v218, v215
	v_pk_add_f32 v[192:193], v[194:195], v[192:193]
	v_pk_add_f32 v[194:195], v[196:197], v[216:217]
	v_pk_add_f32 v[196:197], v[206:207], v[218:219]
	v_mov_b32_e32 v208, v220
	v_pk_add_f32 v[194:195], v[194:195], v[196:197]
	v_mov_b32_e32 v197, v192
	v_mov_b32_e32 v196, v194
	v_mov_b32_e32 v192, v195
	v_pk_add_f32 v[192:193], v[196:197], v[192:193]
	ds_bpermute_b32 v195, v187, v193
	ds_bpermute_b32 v194, v187, v192
	v_mov_b32_e32 v209, v224
	v_mov_b32_e32 v224, v221
	v_mov_b32_e32 v212, v222
	v_mov_b32_e32 v213, v226
	s_waitcnt lgkmcnt(0)
	v_pk_add_f32 v[192:193], v[192:193], v[194:195]
	ds_bpermute_b32 v195, v185, v193
	ds_bpermute_b32 v194, v185, v192
	v_mov_b32_e32 v226, v223
	v_mov_b32_e32 v196, v228
	v_mov_b32_e32 v197, v232
	v_mov_b32_e32 v232, v229
	s_waitcnt lgkmcnt(0)
; DI unsigned pack2(float lo, float hi) { f32x2 v = {lo, hi}; bf16v2 r = __builtin_convertvector(v, bf16v2); return __builtin_bit_cast(unsigned, r); }
; DI float silu_f(float x) { return x * sigmoid_f(x); }
; DI float dpp_ror1(float v) { return __int_as_float(__builtin_amdgcn_update_dpp(0, __float_as_int(v), 0x121, 0xf, 0xf, false)); }
; DI float dpp_ror2(float v) { return __int_as_float(__builtin_amdgcn_update_dpp(0, __float_as_int(v), 0x122, 0xf, 0xf, false)); }
;   DI void operator()(const f32x4 (&acc)[2][2][4][2], const Unit& u, int wr, int wc, int fr, int fq) const {
;     ...
;       for (int m = 0; m < 4; ++m) rsv[m] = row_rstd(ssq, row0 + 16 * m + fr, fq);
;       float p1[8], p2[8];
; #pragma unroll
;       for (int e = 0; e < 8; ++e) { p1[e] = 0.f; p2[e] = 0.f; }
; #pragma unroll
;       for (int m = 0; m < 4; ++m) {
;         float g[8], uu[8], a[8];
;         const float rs = rsv[m];
; #pragma unroll
;         for (int e = 0; e < 4; ++e) { g[e] = acc[ai][0][m][0][e] * rs; g[4 + e] = acc[ai][0][m][1][e] * rs; uu[e] = acc[ai][1][m][0][e] * rs; uu[4 + e] = acc[ai][1][m][1][e] * rs; }
; #pragma unroll
;         for (int e = 0; e < 8; ++e) {
;           const float x1 = dpp_ror1(g[e]), x2 = dpp_ror2(g[e]);
;           const float pr1 = (fr == 0) ? p1[e] : x1, pr2 = (fr < 2) ? p2[e] : x2;
;           a[e] = w2[e] * g[e] + w1[e] * pr1 + w0[e] * pr2 + bb[e];
;           p1[e] = x1; p2[e] = x2;
;         }
;         if (m == 0 && fr < 2) {
;           float* ha = headA + (size_t)(span * 2 + fr) * 5632 + col; float* hu = headU + (size_t)(span * 2 + fr) * 5632 + col;
;           *(f32x4*)ha = (f32x4){a[0], a[1], a[2], a[3]}; *(f32x4*)(ha + 4) = (f32x4){a[4], a[5], a[6], a[7]};
;           *(f32x4*)hu = (f32x4){uu[0], uu[1], uu[2], uu[3]}; *(f32x4*)(hu + 4) = (f32x4){uu[4], uu[5], uu[6], uu[7]};
;         } else {
;           u32x4 w;
;           w.x = pack2(silu_f(a[0]) * uu[0], silu_f(a[1]) * uu[1]);
;           w.y = pack2(silu_f(a[2]) * uu[2], silu_f(a[3]) * uu[3]);
;           w.z = pack2(silu_f(a[4]) * uu[4], silu_f(a[5]) * uu[5]);
;           w.w = pack2(silu_f(a[6]) * uu[6], silu_f(a[7]) * uu[7]);
;           *(u32x4*)(H + (size_t)(row0 + 16 * m + fr) * 5632 + col) = w;
	v_pk_add_f32 v[192:193], v[192:193], v[194:195]
	v_mov_b32_e32 v206, v230
	v_pk_fma_f32 v[192:193], v[192:193], s[36:37], v[178:179] op_sel_hi:[1,0,0]
	v_mov_b32_e32 v207, v234
	v_mul_f32_e32 v189, 0x4b800000, v193
	v_cmp_gt_f32_e64 s[12:13], s74, v193
	v_mov_b32_e32 v234, v231
	v_pk_add_f32 v[208:209], v[208:209], v[224:225]
	v_cndmask_b32_e64 v189, v193, v189, s[12:13]
	v_rsq_f32_e32 v189, v189
	v_pk_add_f32 v[212:213], v[212:213], v[226:227]
	v_pk_add_f32 v[196:197], v[196:197], v[232:233]
	v_pk_add_f32 v[194:195], v[206:207], v[234:235]
	v_mul_f32_e32 v191, 0x45800000, v189
	v_cndmask_b32_e64 v220, v189, v191, s[12:13]
	v_pk_add_f32 v[208:209], v[208:209], v[212:213]
	v_pk_add_f32 v[194:195], v[196:197], v[194:195]
	v_pk_mul_f32 v[156:157], v[156:157], v[220:221] op_sel_hi:[1,0]
	v_mov_b32_e32 v216, 0
	v_mov_b32_e32 v218, 0
	v_mov_b32_e32 v196, v194
	v_mov_b32_e32 v197, v208
	v_mov_b32_e32 v208, v195
	v_mov_b32_dpp v216, v156 row_ror:1 row_mask:0xf bank_mask:0xf
	v_mov_b32_dpp v218, v157 row_ror:1 row_mask:0xf bank_mask:0xf
	v_pk_add_f32 v[194:195], v[196:197], v[208:209]
	v_cndmask_b32_e64 v207, v218, 0, s[0:1]
	v_cndmask_b32_e64 v206, v216, 0, s[0:1]
	v_pk_mul_f32 v[158:159], v[158:159], v[220:221] op_sel_hi:[1,0]
	v_mov_b32_e32 v212, 0
	v_mov_b32_e32 v214, 0
	ds_bpermute_b32 v197, v187, v195
	ds_bpermute_b32 v196, v187, v194
	v_mov_b32_e32 v215, 0
	v_mov_b32_e32 v217, 0
	v_pk_mul_f32 v[206:207], v[88:89], v[206:207]
	v_mov_b32_dpp v212, v158 row_ror:1 row_mask:0xf bank_mask:0xf
	v_mov_b32_dpp v214, v159 row_ror:1 row_mask:0xf bank_mask:0xf
	v_mov_b32_dpp v215, v156 row_ror:2 row_mask:0xf bank_mask:0xf
	v_mov_b32_dpp v217, v157 row_ror:2 row_mask:0xf bank_mask:0xf
	v_pk_fma_f32 v[156:157], v[92:93], v[156:157], v[206:207]
	v_mov_b32_e32 v213, 0
	v_cndmask_b32_e64 v207, v214, 0, s[0:1]
	v_cndmask_b32_e64 v206, v212, 0, s[0:1]
	v_cndmask_b32_e64 v209, v217, 0, s[4:5]
	v_cndmask_b32_e64 v208, v215, 0, s[4:5]
	v_mov_b32_dpp v211, v158 row_ror:2 row_mask:0xf bank_mask:0xf
	v_mov_b32_dpp v213, v159 row_ror:2 row_mask:0xf bank_mask:0xf
	v_pk_mul_f32 v[206:207], v[90:91], v[206:207]
	v_pk_fma_f32 v[156:157], v[80:81], v[208:209], v[156:157]
	v_cndmask_b32_e64 v209, v213, 0, s[4:5]
	v_cndmask_b32_e64 v208, v211, 0, s[4:5]
	v_pk_fma_f32 v[158:159], v[94:95], v[158:159], v[206:207]
	v_pk_mul_f32 v[144:145], v[144:145], v[220:221] op_sel_hi:[1,0]
	v_pk_fma_f32 v[158:159], v[82:83], v[208:209], v[158:159]
	v_mov_b32_e32 v207, 0
	v_mov_b32_e32 v209, 0
	v_pk_mul_f32 v[146:147], v[146:147], v[220:221] op_sel_hi:[1,0]
	v_mov_b32_e32 v191, 0
	s_waitcnt lgkmcnt(0)
	v_pk_add_f32 v[194:195], v[194:195], v[196:197]
	v_mov_b32_dpp v207, v144 row_ror:1 row_mask:0xf bank_mask:0xf
	v_mov_b32_dpp v209, v145 row_ror:1 row_mask:0xf bank_mask:0xf
	v_mov_b32_dpp v191, v146 row_ror:1 row_mask:0xf bank_mask:0xf
	v_mov_b32_dpp v205, v147 row_ror:1 row_mask:0xf bank_mask:0xf
	ds_bpermute_b32 v197, v185, v195
	ds_bpermute_b32 v196, v185, v194
	v_pk_mul_f32 v[152:153], v[152:153], v[220:221] op_sel_hi:[1,0]
	v_pk_mul_f32 v[148:149], v[148:149], v[220:221] op_sel_hi:[1,0]
	v_pk_mul_f32 v[154:155], v[154:155], v[220:221] op_sel_hi:[1,0]
	v_pk_mul_f32 v[150:151], v[150:151], v[220:221] op_sel_hi:[1,0]
	v_mov_b32_e32 v206, 0
	v_mov_b32_e32 v208, 0
	v_cndmask_b32_e64 v223, v209, 0, s[0:1]
	v_cndmask_b32_e64 v222, v207, 0, s[0:1]
	v_mov_b32_e32 v189, 0
	v_mov_b32_e32 v193, 0
	v_cndmask_b32_e64 v221, v205, 0, s[0:1]
	v_cndmask_b32_e64 v220, v191, 0, s[0:1]
	v_mov_b32_dpp v206, v144 row_ror:2 row_mask:0xf bank_mask:0xf
	v_mov_b32_dpp v208, v145 row_ror:2 row_mask:0xf bank_mask:0xf
	v_pk_mul_f32 v[222:223], v[72:73], v[222:223]
	v_mov_b32_dpp v189, v146 row_ror:2 row_mask:0xf bank_mask:0xf
	v_mov_b32_dpp v193, v147 row_ror:2 row_mask:0xf bank_mask:0xf
	v_pk_mul_f32 v[220:221], v[74:75], v[220:221]
	v_cndmask_b32_e64 v225, v208, 0, s[4:5]
	v_cndmask_b32_e64 v224, v206, 0, s[4:5]
	v_pk_fma_f32 v[144:145], v[76:77], v[144:145], v[222:223]
	v_cndmask_b32_e64 v223, v193, 0, s[4:5]
	v_cndmask_b32_e64 v222, v189, 0, s[4:5]
	v_pk_fma_f32 v[146:147], v[78:79], v[146:147], v[220:221]
	v_pk_fma_f32 v[144:145], v[64:65], v[224:225], v[144:145]
	v_pk_fma_f32 v[146:147], v[66:67], v[222:223], v[146:147]
	v_cmp_gt_f32_e32 vcc, s74, v192
	v_pk_add_f32 v[156:157], v[84:85], v[156:157]
	v_pk_add_f32 v[158:159], v[86:87], v[158:159]
	v_pk_add_f32 v[144:145], v[68:69], v[144:145]
	v_pk_add_f32 v[146:147], v[70:71], v[146:147]
	s_and_saveexec_b64 s[12:13], s[10:11]
	s_xor_b64 s[12:13], exec, s[12:13]
	s_cbranch_execz .LBB0_1280
	v_mul_f32_e32 v219, 0xbfb8aa3b, v156
	v_exp_f32_e32 v219, v219
	v_mul_f32_e32 v220, 0xbfb8aa3b, v157
	v_exp_f32_e32 v220, v220
	v_mul_f32_e32 v222, 0xbfb8aa3b, v159
	v_add_f32_e32 v219, 1.0, v219
	v_exp_f32_e32 v223, v222
	v_add_f32_e32 v221, 1.0, v220
	v_rcp_f32_e32 v220, v219
	v_mul_f32_e32 v219, 0xbfb8aa3b, v158
	v_exp_f32_e32 v219, v219
	v_rcp_f32_e32 v221, v221
	v_add_f32_e32 v219, 1.0, v219
	v_rcp_f32_e32 v222, v219
	v_add_f32_e32 v219, 1.0, v223
	v_rcp_f32_e32 v223, v219
	v_pk_mul_f32 v[156:157], v[156:157], v[220:221]
	s_nop 0
	v_pk_mul_f32 v[152:153], v[152:153], v[156:157]
	v_pk_mul_f32 v[156:157], v[158:159], v[222:223]
	v_cvt_pk_bf16_f32 v152, v152, v153
	v_mul_f32_e32 v153, 0xbfb8aa3b, v144
	v_pk_mul_f32 v[154:155], v[154:155], v[156:157]
	v_exp_f32_e32 v156, v153
	v_mul_f32_e32 v153, 0xbfb8aa3b, v145
	v_exp_f32_e32 v157, v153
	v_cvt_pk_bf16_f32 v153, v154, v155
	v_add_f32_e32 v154, 1.0, v156
	v_mul_f32_e32 v156, 0xbfb8aa3b, v146
	v_add_f32_e32 v155, 1.0, v157
	v_mul_f32_e32 v157, 0xbfb8aa3b, v147
	v_exp_f32_e32 v156, v156
	v_exp_f32_e32 v157, v157
	v_rcp_f32_e32 v154, v154
	v_rcp_f32_e32 v155, v155
	v_add_f32_e32 v156, 1.0, v156
	v_add_f32_e32 v157, 1.0, v157
	v_rcp_f32_e32 v156, v156
	v_rcp_f32_e32 v157, v157
	v_pk_mul_f32 v[144:145], v[144:145], v[154:155]
	s_nop 0
	v_pk_mul_f32 v[144:145], v[148:149], v[144:145]
	s_nop 0
	v_cvt_pk_bf16_f32 v154, v144, v145
	v_pk_mul_f32 v[144:145], v[146:147], v[156:157]
	s_nop 0
	v_pk_mul_f32 v[144:145], v[150:151], v[144:145]
	s_nop 0
	v_cvt_pk_bf16_f32 v155, v144, v145
	v_mov_b64_e32 v[144:145], s[20:21]
	v_mad_i64_i32 v[144:145], s[14:15], v190, s75, v[144:145]
	v_lshl_add_u64 v[144:145], v[180:181], 1, v[144:145]
	global_store_dwordx4 v[144:145], v[152:155], off

; #define PG8_STAGE(bufoff, gbase, voff) do { _Pragma("unroll") for (int _i = 0; _i < 2; ++_i) \
;     __builtin_amdgcn_global_load_lds((const unsigned*)((const char*)(gbase) + (voff)[_i]), (LAS unsigned*)(lds + (bufoff) + ldsw + _i * 8192), 16, 0, 0); } while (0)
; #define PG8_LDA(dst, b, h) do { _Pragma("unroll") for (int m = 0; m < 4; ++m) _Pragma("unroll") for (int k = 0; k < 2; ++k) dst[m][k] = *(const LAS bf16x8*)(lds + PG8_SA(b, h) + aoff + m * 2048 + k * 1024); } while (0)
; #define PG8_LDB(dst, b, h) do { _Pragma("unroll") for (int n = 0; n < 2; ++n) _Pragma("unroll") for (int k = 0; k < 2; ++k) dst[n][k] = *(const LAS bf16x8*)(lds + PG8_SB(b, h) + boff + n * 2048 + k * 1024); } while (0)
; #define PG8_MMA(ai, bj, At, Bt) do { __builtin_amdgcn_s_setprio(1); _Pragma("unroll") for (int m = 0; m < 4; ++m) _Pragma("unroll") for (int n = 0; n < 2; ++n) _Pragma("unroll") for (int k = 0; k < 2; ++k) \
;     acc[ai][bj][m][n] = __builtin_amdgcn_mfma_f32_16x16x32_bf16(Bt[n][k], At[m][k], acc[ai][bj][m][n], 0, 0, 0); __builtin_amdgcn_s_setprio(0); } while (0)
; #define PG8_WAIT_V(n) asm volatile("s_waitcnt vmcnt(" #n ")" ::: "memory")
; template <class Epi, class Sched = StaticOrder>
; DI void gemm_phase(LAS unsigned char* lds, const Gemm g, const Sched& S, const Epi& E) {
;     ...
;     for (int t = 0; t < nt; t += 2) {
;       const bool last = (t == nt - 2);
;       const char* a1 = cA + (size_t)(t + 1) * kstep;
;       const char* a2 = last ? nA : cA + (size_t)(t + 2) * kstep; const char* b2 = last ? nB : cB + (size_t)(t + 2) * kstep;
;       const char* a3 = a2 + kstep; const char* b3 = b2 + kstep;
;       PG8_LDB(B0, 0, 0); PG8_SCHED; PG8_LDA(At, 0, 0); PG8_STAGE(PG8_SA(1, 1), a1 + hstep, voffA);
;       PG8_WAIT_L(8); PG8_BAR; PG8_WAIT_L(0); PG8_MMA(0, 0, At, B0); PG8_BAR; PG8_SCHED;
;       PG8_LDB(B1, 0, 1); PG8_STAGE(PG8_SB(0, 0), b2, voffB);
;       PG8_BAR; PG8_WAIT_L(0); PG8_MMA(0, 1, At, B1); PG8_BAR;
;       PG8_LDA(At, 0, 1); PG8_STAGE(PG8_SA(0, 0), a2, voffA);
;       PG8_BAR; PG8_WAIT_L(0); PG8_MMA(1, 0, At, B0); PG8_BAR; PG8_SCHED;
;       PG8_STAGE(PG8_SB(0, 1), b2 + hstep, voffB);
;       PG8_WAIT_V(6); PG8_BAR; PG8_MMA(1, 1, At, B1); PG8_BAR;
;       PG8_LDB(B0, 1, 0); PG8_SCHED; PG8_LDA(At, 1, 0); PG8_STAGE(PG8_SA(0, 1), a2 + hstep, voffA);
;       PG8_WAIT_L(8); PG8_BAR; PG8_WAIT_L(0); PG8_MMA(0, 0, At, B0); PG8_BAR; PG8_SCHED;
.LBB0_1424:
	s_add_i32 m0, s30, 0xc000
	ds_read_b128 v[166:169], v160
	ds_read_b128 v[170:173], v160 offset:1024
	ds_read_b128 v[174:177], v160 offset:2048
	ds_read_b128 v[178:181], v160 offset:3072
	ds_read_b128 v[182:185], v160 offset:4096
	ds_read_b128 v[186:189], v160 offset:5120
	ds_read_b128 v[190:193], v160 offset:6144
	ds_read_b128 v[194:197], v160 offset:7168
	global_load_lds_dwordx4 v136, s[16:17]
	s_add_i32 m0, s30, 0xe000
	s_nop 0
	global_load_lds_dwordx4 v138, s[16:17]
	s_waitcnt lgkmcnt(0)
	s_setprio 1
	s_barrier
	v_mfma_f32_16x16x32_bf16 v[124:127], v[144:147], v[166:169], v[124:127]
	v_mfma_f32_16x16x32_bf16 v[120:123], v[152:155], v[166:169], v[120:123]
	v_mfma_f32_16x16x32_bf16 v[116:119], v[144:147], v[174:177], v[116:119]
	v_mfma_f32_16x16x32_bf16 v[112:115], v[152:155], v[174:177], v[112:115]
	v_mfma_f32_16x16x32_bf16 v[104:107], v[144:147], v[182:185], v[104:107]
	v_mfma_f32_16x16x32_bf16 v[96:99], v[152:155], v[182:185], v[96:99]
	v_mfma_f32_16x16x32_bf16 v[88:91], v[144:147], v[190:193], v[88:91]
	v_mfma_f32_16x16x32_bf16 v[80:83], v[152:155], v[190:193], v[80:83]
	v_mfma_f32_16x16x32_bf16 v[124:127], v[148:151], v[170:173], v[124:127]
	v_mfma_f32_16x16x32_bf16 v[120:123], v[162:165], v[170:173], v[120:123]
	v_mfma_f32_16x16x32_bf16 v[116:119], v[148:151], v[178:181], v[116:119]
	v_mfma_f32_16x16x32_bf16 v[112:115], v[162:165], v[178:181], v[112:115]
	v_mfma_f32_16x16x32_bf16 v[104:107], v[148:151], v[186:189], v[104:107]
	v_mfma_f32_16x16x32_bf16 v[96:99], v[162:165], v[186:189], v[96:99]
	v_mfma_f32_16x16x32_bf16 v[88:91], v[148:151], v[194:197], v[88:91]
	v_mfma_f32_16x16x32_bf16 v[80:83], v[162:165], v[194:197], v[80:83]
	s_barrier
	s_setprio 0
	ds_read_b128 v[198:201], v161
	ds_read_b128 v[202:205], v161 offset:1024
	ds_read_b128 v[206:209], v161 offset:2048
	ds_read_b128 v[210:213], v161 offset:3072
	s_add_u32 s18, s16, 0xffea0080
	s_addc_u32 s19, s17, -1
	s_cmpk_eq_i32 s47, 0x54
	s_cselect_b32 s21, s3, s19
	s_cselect_b32 s20, s2, s18
	s_cselect_b32 s19, s5, s46
	s_cselect_b32 s18, s4, s45
	s_add_i32 s48, s39, s28
	s_add_u32 s98, s18, 0x80
	s_addc_u32 s99, s19, 0
	s_add_u32 s100, s20, 0x80
	s_addc_u32 s101, s21, 0
	s_mov_b32 m0, s48
	s_nop 0
	global_load_lds_dwordx4 v132, s[18:19]
	s_add_i32 m0, s48, 0x2000
	s_nop 0
	global_load_lds_dwordx4 v128, s[18:19]
	s_waitcnt lgkmcnt(0)
	s_setprio 1
	s_barrier
	v_mfma_f32_16x16x32_bf16 v[108:111], v[198:201], v[166:169], v[108:111]
	v_mfma_f32_16x16x32_bf16 v[100:103], v[206:209], v[166:169], v[100:103]
	v_mfma_f32_16x16x32_bf16 v[92:95], v[198:201], v[174:177], v[92:95]
	v_mfma_f32_16x16x32_bf16 v[84:87], v[206:209], v[174:177], v[84:87]
	v_mfma_f32_16x16x32_bf16 v[76:79], v[198:201], v[182:185], v[76:79]
	v_mfma_f32_16x16x32_bf16 v[72:75], v[206:209], v[182:185], v[72:75]
	v_mfma_f32_16x16x32_bf16 v[68:71], v[198:201], v[190:193], v[68:71]
	v_mfma_f32_16x16x32_bf16 v[64:67], v[206:209], v[190:193], v[64:67]
	v_mfma_f32_16x16x32_bf16 v[108:111], v[202:205], v[170:173], v[108:111]
	v_mfma_f32_16x16x32_bf16 v[100:103], v[210:213], v[170:173], v[100:103]
	v_mfma_f32_16x16x32_bf16 v[92:95], v[202:205], v[178:181], v[92:95]
	v_mfma_f32_16x16x32_bf16 v[84:87], v[210:213], v[178:181], v[84:87]
	v_mfma_f32_16x16x32_bf16 v[76:79], v[202:205], v[186:189], v[76:79]
	v_mfma_f32_16x16x32_bf16 v[72:75], v[210:213], v[186:189], v[72:75]
	v_mfma_f32_16x16x32_bf16 v[68:71], v[202:205], v[194:197], v[68:71]
	v_mfma_f32_16x16x32_bf16 v[64:67], v[210:213], v[194:197], v[64:67]
	s_barrier
	s_setprio 0
	s_mov_b32 m0, s30
	ds_read_b128 v[166:169], v160 offset:16384
	ds_read_b128 v[170:173], v160 offset:17408
	ds_read_b128 v[174:177], v160 offset:18432
	ds_read_b128 v[178:181], v160 offset:19456
	ds_read_b128 v[182:185], v160 offset:20480
	ds_read_b128 v[186:189], v160 offset:21504
	ds_read_b128 v[190:193], v160 offset:22528
	ds_read_b128 v[194:197], v160 offset:23552
	global_load_lds_dwordx4 v134, s[20:21]
	s_mov_b32 m0, s31
	s_nop 0
	global_load_lds_dwordx4 v130, s[20:21]
	s_waitcnt vmcnt(10)
	s_waitcnt lgkmcnt(0)
	s_setprio 1
	s_barrier
	v_mfma_f32_16x16x32_bf16 v[60:63], v[144:147], v[166:169], v[60:63]
	v_mfma_f32_16x16x32_bf16 v[56:59], v[152:155], v[166:169], v[56:59]
	v_mfma_f32_16x16x32_bf16 v[52:55], v[144:147], v[174:177], v[52:55]
	v_mfma_f32_16x16x32_bf16 v[44:47], v[152:155], v[174:177], v[44:47]
	v_mfma_f32_16x16x32_bf16 v[36:39], v[144:147], v[182:185], v[36:39]
	v_mfma_f32_16x16x32_bf16 v[28:31], v[152:155], v[182:185], v[28:31]
	v_mfma_f32_16x16x32_bf16 v[20:23], v[144:147], v[190:193], v[20:23]
	v_mfma_f32_16x16x32_bf16 v[12:15], v[152:155], v[190:193], v[12:15]
	v_mfma_f32_16x16x32_bf16 v[60:63], v[148:151], v[170:173], v[60:63]
	v_mfma_f32_16x16x32_bf16 v[56:59], v[162:165], v[170:173], v[56:59]
	v_mfma_f32_16x16x32_bf16 v[52:55], v[148:151], v[178:181], v[52:55]
	v_mfma_f32_16x16x32_bf16 v[44:47], v[162:165], v[178:181], v[44:47]
	v_mfma_f32_16x16x32_bf16 v[36:39], v[148:151], v[186:189], v[36:39]
	v_mfma_f32_16x16x32_bf16 v[28:31], v[162:165], v[186:189], v[28:31]
	v_mfma_f32_16x16x32_bf16 v[20:23], v[148:151], v[194:197], v[20:23]
	v_mfma_f32_16x16x32_bf16 v[12:15], v[162:165], v[194:197], v[12:15]
	s_barrier
	s_setprio 0
	s_add_u32 s48, s18, 0x160000
	s_addc_u32 s49, s19, 0
	s_add_i32 s50, s40, s28
	s_mov_b32 m0, s50
	s_nop 0
	global_load_lds_dwordx4 v132, s[48:49]
	s_add_i32 m0, s50, 0x2000
	s_nop 0
	global_load_lds_dwordx4 v128, s[48:49]
	s_add_i32 s48, 0, 0x18000
	v_add_u32_e32 v162, s48, v157
	ds_read_b128 v[144:147], v162
	ds_read_b128 v[148:151], v162 offset:1024
	ds_read_b128 v[152:155], v162 offset:2048
	ds_read_b128 v[162:165], v162 offset:3072
	s_waitcnt vmcnt(6)
	s_setprio 1
	s_barrier
; #define PG8_STAGE(bufoff, gbase, voff) do { _Pragma("unroll") for (int _i = 0; _i < 2; ++_i) \
;     __builtin_amdgcn_global_load_lds((const unsigned*)((const char*)(gbase) + (voff)[_i]), (LAS unsigned*)(lds + (bufoff) + ldsw + _i * 8192), 16, 0, 0); } while (0)
; #define PG8_LDA(dst, b, h) do { _Pragma("unroll") for (int m = 0; m < 4; ++m) _Pragma("unroll") for (int k = 0; k < 2; ++k) dst[m][k] = *(const LAS bf16x8*)(lds + PG8_SA(b, h) + aoff + m * 2048 + k * 1024); } while (0)
; #define PG8_LDB(dst, b, h) do { _Pragma("unroll") for (int n = 0; n < 2; ++n) _Pragma("unroll") for (int k = 0; k < 2; ++k) dst[n][k] = *(const LAS bf16x8*)(lds + PG8_SB(b, h) + boff + n * 2048 + k * 1024); } while (0)
; #define PG8_MMA(ai, bj, At, Bt) do { __builtin_amdgcn_s_setprio(1); _Pragma("unroll") for (int m = 0; m < 4; ++m) _Pragma("unroll") for (int n = 0; n < 2; ++n) _Pragma("unroll") for (int k = 0; k < 2; ++k) \
;     acc[ai][bj][m][n] = __builtin_amdgcn_mfma_f32_16x16x32_bf16(Bt[n][k], At[m][k], acc[ai][bj][m][n], 0, 0, 0); __builtin_amdgcn_s_setprio(0); } while (0)
; #define PG8_WAIT_V(n) asm volatile("s_waitcnt vmcnt(" #n ")" ::: "memory")
; #define PG8_WAIT_L(n) asm volatile("s_waitcnt lgkmcnt(" #n ")" ::: "memory")
; #define PG8_BAR __builtin_amdgcn_s_barrier()
; #define PG8_SCHED __builtin_amdgcn_sched_barrier(0)
; template <class Epi, class Sched = StaticOrder>
; DI void gemm_phase(LAS unsigned char* lds, const Gemm g, const Sched& S, const Epi& E) {
;     ...
;       PG8_WAIT_V(6); PG8_BAR; PG8_MMA(1, 1, At, B1); PG8_BAR;
;       PG8_LDB(B0, 1, 0); PG8_SCHED; PG8_LDA(At, 1, 0); PG8_STAGE(PG8_SA(0, 1), a2 + hstep, voffA);
;       PG8_WAIT_L(8); PG8_BAR; PG8_WAIT_L(0); PG8_MMA(0, 0, At, B0); PG8_BAR; PG8_SCHED;
;       PG8_LDB(B1, 1, 1); PG8_STAGE(PG8_SB(1, 0), b3, voffB);
;       PG8_BAR; PG8_WAIT_L(0); PG8_MMA(0, 1, At, B1); PG8_BAR;
;       PG8_LDA(At, 1, 1); PG8_STAGE(PG8_SA(1, 0), a3, voffA);
;       PG8_BAR; PG8_WAIT_L(0); PG8_MMA(1, 0, At, B0); PG8_BAR; PG8_SCHED;
;       PG8_STAGE(PG8_SB(1, 1), b3 + hstep, voffB);
;       PG8_WAIT_V(6); PG8_BAR; PG8_MMA(1, 1, At, B1); PG8_BAR;
	v_mfma_f32_16x16x32_bf16 v[48:51], v[198:201], v[166:169], v[48:51]
	v_mfma_f32_16x16x32_bf16 v[40:43], v[206:209], v[166:169], v[40:43]
	v_mfma_f32_16x16x32_bf16 v[32:35], v[198:201], v[174:177], v[32:35]
	v_mfma_f32_16x16x32_bf16 v[24:27], v[206:209], v[174:177], v[24:27]
	v_mfma_f32_16x16x32_bf16 v[16:19], v[198:201], v[182:185], v[16:19]
	v_mfma_f32_16x16x32_bf16 v[8:11], v[206:209], v[182:185], v[8:11]
	v_mfma_f32_16x16x32_bf16 v[4:7], v[198:201], v[190:193], v[4:7]
	v_mfma_f32_16x16x32_bf16 v[0:3], v[206:209], v[190:193], v[0:3]
	v_mfma_f32_16x16x32_bf16 v[48:51], v[202:205], v[170:173], v[48:51]
	v_mfma_f32_16x16x32_bf16 v[40:43], v[210:213], v[170:173], v[40:43]
	v_mfma_f32_16x16x32_bf16 v[32:35], v[202:205], v[178:181], v[32:35]
	v_mfma_f32_16x16x32_bf16 v[24:27], v[210:213], v[178:181], v[24:27]
	v_mfma_f32_16x16x32_bf16 v[16:19], v[202:205], v[186:189], v[16:19]
	v_mfma_f32_16x16x32_bf16 v[8:11], v[210:213], v[186:189], v[8:11]
	v_mfma_f32_16x16x32_bf16 v[4:7], v[202:205], v[194:197], v[4:7]
	v_mfma_f32_16x16x32_bf16 v[0:3], v[210:213], v[194:197], v[0:3]
	s_barrier
	s_setprio 0
	s_add_u32 s20, s20, 0x160000
	s_addc_u32 s21, s21, 0
	s_mov_b32 m0, s33
	ds_read_b128 v[166:169], v160 offset:32768
	ds_read_b128 v[170:173], v160 offset:33792
	ds_read_b128 v[174:177], v160 offset:34816
	ds_read_b128 v[178:181], v160 offset:35840
	ds_read_b128 v[182:185], v160 offset:36864
	ds_read_b128 v[186:189], v160 offset:37888
	ds_read_b128 v[190:193], v160 offset:38912
	ds_read_b128 v[194:197], v160 offset:39936
	global_load_lds_dwordx4 v134, s[20:21]
	s_mov_b32 m0, s34
	s_nop 0
	global_load_lds_dwordx4 v130, s[20:21]
	s_waitcnt lgkmcnt(0)
	s_setprio 1
	s_barrier
	v_mfma_f32_16x16x32_bf16 v[124:127], v[144:147], v[166:169], v[124:127]
	v_mfma_f32_16x16x32_bf16 v[120:123], v[152:155], v[166:169], v[120:123]
	v_mfma_f32_16x16x32_bf16 v[116:119], v[144:147], v[174:177], v[116:119]
	v_mfma_f32_16x16x32_bf16 v[112:115], v[152:155], v[174:177], v[112:115]
	v_mfma_f32_16x16x32_bf16 v[104:107], v[144:147], v[182:185], v[104:107]
	v_mfma_f32_16x16x32_bf16 v[96:99], v[152:155], v[182:185], v[96:99]
	v_mfma_f32_16x16x32_bf16 v[88:91], v[144:147], v[190:193], v[88:91]
	v_mfma_f32_16x16x32_bf16 v[80:83], v[152:155], v[190:193], v[80:83]
	v_mfma_f32_16x16x32_bf16 v[124:127], v[148:151], v[170:173], v[124:127]
	v_mfma_f32_16x16x32_bf16 v[120:123], v[162:165], v[170:173], v[120:123]
	v_mfma_f32_16x16x32_bf16 v[116:119], v[148:151], v[178:181], v[116:119]
	v_mfma_f32_16x16x32_bf16 v[112:115], v[162:165], v[178:181], v[112:115]
	v_mfma_f32_16x16x32_bf16 v[104:107], v[148:151], v[186:189], v[104:107]
	v_mfma_f32_16x16x32_bf16 v[96:99], v[162:165], v[186:189], v[96:99]
	v_mfma_f32_16x16x32_bf16 v[88:91], v[148:151], v[194:197], v[88:91]
	v_mfma_f32_16x16x32_bf16 v[80:83], v[162:165], v[194:197], v[80:83]
	s_barrier
	s_setprio 0
	s_add_i32 s20, 0, 0x1c000
	s_add_i32 s21, s48, s28
	v_add_u32_e32 v210, s20, v157
	s_mov_b32 m0, s21
	ds_read_b128 v[198:201], v210
	ds_read_b128 v[202:205], v210 offset:1024
	ds_read_b128 v[206:209], v210 offset:2048
	ds_read_b128 v[210:213], v210 offset:3072
	global_load_lds_dwordx4 v132, s[98:99]
	s_add_i32 m0, s21, 0x2000
	s_nop 0
	global_load_lds_dwordx4 v128, s[98:99]
	s_waitcnt lgkmcnt(0)
	s_setprio 1
	s_barrier
	v_mfma_f32_16x16x32_bf16 v[108:111], v[198:201], v[166:169], v[108:111]
	v_mfma_f32_16x16x32_bf16 v[100:103], v[206:209], v[166:169], v[100:103]
	v_mfma_f32_16x16x32_bf16 v[92:95], v[198:201], v[174:177], v[92:95]
	v_mfma_f32_16x16x32_bf16 v[84:87], v[206:209], v[174:177], v[84:87]
	v_mfma_f32_16x16x32_bf16 v[76:79], v[198:201], v[182:185], v[76:79]
	v_mfma_f32_16x16x32_bf16 v[72:75], v[206:209], v[182:185], v[72:75]
	v_mfma_f32_16x16x32_bf16 v[68:71], v[198:201], v[190:193], v[68:71]
	v_mfma_f32_16x16x32_bf16 v[64:67], v[206:209], v[190:193], v[64:67]
	v_mfma_f32_16x16x32_bf16 v[108:111], v[202:205], v[170:173], v[108:111]
	v_mfma_f32_16x16x32_bf16 v[100:103], v[210:213], v[170:173], v[100:103]
	v_mfma_f32_16x16x32_bf16 v[92:95], v[202:205], v[178:181], v[92:95]
	v_mfma_f32_16x16x32_bf16 v[84:87], v[210:213], v[178:181], v[84:87]
	v_mfma_f32_16x16x32_bf16 v[76:79], v[202:205], v[186:189], v[76:79]
	v_mfma_f32_16x16x32_bf16 v[72:75], v[210:213], v[186:189], v[72:75]
	v_mfma_f32_16x16x32_bf16 v[68:71], v[202:205], v[194:197], v[68:71]
	v_mfma_f32_16x16x32_bf16 v[64:67], v[210:213], v[194:197], v[64:67]
	s_barrier
	s_setprio 0
	s_mov_b32 m0, s35
	ds_read_b128 v[166:169], v160 offset:49152
	ds_read_b128 v[170:173], v160 offset:50176
	ds_read_b128 v[174:177], v160 offset:51200
	ds_read_b128 v[178:181], v160 offset:52224
	ds_read_b128 v[182:185], v160 offset:53248
	ds_read_b128 v[186:189], v160 offset:54272
	ds_read_b128 v[190:193], v160 offset:55296
	ds_read_b128 v[194:197], v160 offset:56320
	global_load_lds_dwordx4 v134, s[100:101]
	s_mov_b32 m0, s36
	s_nop 0
	global_load_lds_dwordx4 v130, s[100:101]
	s_waitcnt vmcnt(10)
	s_waitcnt lgkmcnt(0)
	s_setprio 1
	s_barrier
	v_mfma_f32_16x16x32_bf16 v[60:63], v[144:147], v[166:169], v[60:63]
	v_mfma_f32_16x16x32_bf16 v[56:59], v[152:155], v[166:169], v[56:59]
	v_mfma_f32_16x16x32_bf16 v[52:55], v[144:147], v[174:177], v[52:55]
	v_mfma_f32_16x16x32_bf16 v[44:47], v[152:155], v[174:177], v[44:47]
	v_mfma_f32_16x16x32_bf16 v[36:39], v[144:147], v[182:185], v[36:39]
	v_mfma_f32_16x16x32_bf16 v[28:31], v[152:155], v[182:185], v[28:31]
	v_mfma_f32_16x16x32_bf16 v[20:23], v[144:147], v[190:193], v[20:23]
	v_mfma_f32_16x16x32_bf16 v[12:15], v[152:155], v[190:193], v[12:15]
	v_mfma_f32_16x16x32_bf16 v[60:63], v[148:151], v[170:173], v[60:63]
	v_mfma_f32_16x16x32_bf16 v[56:59], v[162:165], v[170:173], v[56:59]
	v_mfma_f32_16x16x32_bf16 v[52:55], v[148:151], v[178:181], v[52:55]
	v_mfma_f32_16x16x32_bf16 v[44:47], v[162:165], v[178:181], v[44:47]
	v_mfma_f32_16x16x32_bf16 v[36:39], v[148:151], v[186:189], v[36:39]
	v_mfma_f32_16x16x32_bf16 v[28:31], v[162:165], v[186:189], v[28:31]
	v_mfma_f32_16x16x32_bf16 v[20:23], v[148:151], v[194:197], v[20:23]
	v_mfma_f32_16x16x32_bf16 v[12:15], v[162:165], v[194:197], v[12:15]
	s_barrier
; #define PG8_STAGE(bufoff, gbase, voff) do { _Pragma("unroll") for (int _i = 0; _i < 2; ++_i) \
;     __builtin_amdgcn_global_load_lds((const unsigned*)((const char*)(gbase) + (voff)[_i]), (LAS unsigned*)(lds + (bufoff) + ldsw + _i * 8192), 16, 0, 0); } while (0)
; #define PG8_MMA(ai, bj, At, Bt) do { __builtin_amdgcn_s_setprio(1); _Pragma("unroll") for (int m = 0; m < 4; ++m) _Pragma("unroll") for (int n = 0; n < 2; ++n) _Pragma("unroll") for (int k = 0; k < 2; ++k) \
;     acc[ai][bj][m][n] = __builtin_amdgcn_mfma_f32_16x16x32_bf16(Bt[n][k], At[m][k], acc[ai][bj][m][n], 0, 0, 0); __builtin_amdgcn_s_setprio(0); } while (0)
; #define PG8_WAIT_V(n) asm volatile("s_waitcnt vmcnt(" #n ")" ::: "memory")
; #define PG8_BAR __builtin_amdgcn_s_barrier()
;   DI void operator()(const f32x4 (&acc)[2][2][4][2], const Unit& u, int wr, int wc, int fr, int fq) const {
;     const int row0 = u.pm * BM + wr * 64 + fr, col0 = u.pn * BM + wc * 32 + 8 * fq;
; #pragma unroll
;     for (int ai = 0; ai < 2; ++ai) {
;       f32x4 bv[4][2][2];
; #pragma unroll
;       for (int m = 0; m < 4; ++m)
; #pragma unroll
;         for (int bj = 0; bj < 2; ++bj) {
;           const float* bp = base + (size_t)(row0 + ai * HALF + m * 16) * 2048 + col0 + bj * HALF;
;           bv[m][bj][0] = *(const f32x4*)bp; bv[m][bj][1] = *(const f32x4*)(bp + 4);
;         }
; template <class Epi, class Sched = StaticOrder>
; DI void gemm_phase(LAS unsigned char* lds, const Gemm g, const Sched& S, const Epi& E) {
;     ...
;       PG8_STAGE(PG8_SB(1, 1), b3 + hstep, voffB);
;       PG8_WAIT_V(6); PG8_BAR; PG8_MMA(1, 1, At, B1); PG8_BAR;
;     }
;     E(acc, cur, wr, wc, fr, fq);
	s_setprio 0
	s_add_u32 s18, s18, 0x160080
	s_addc_u32 s19, s19, 0
	s_add_i32 s20, s20, s28
	s_mov_b32 m0, s20
	s_nop 0
	global_load_lds_dwordx4 v132, s[18:19]
	s_add_i32 m0, s20, 0x2000
	s_nop 0
	global_load_lds_dwordx4 v128, s[18:19]
	ds_read_b128 v[144:147], v159
	ds_read_b128 v[148:151], v159 offset:1024
	ds_read_b128 v[152:155], v159 offset:2048
	ds_read_b128 v[162:165], v159 offset:3072
	s_waitcnt vmcnt(6)
	s_setprio 1
	s_barrier
	v_mfma_f32_16x16x32_bf16 v[48:51], v[198:201], v[166:169], v[48:51]
	v_mfma_f32_16x16x32_bf16 v[40:43], v[206:209], v[166:169], v[40:43]
	v_mfma_f32_16x16x32_bf16 v[32:35], v[198:201], v[174:177], v[32:35]
	v_mfma_f32_16x16x32_bf16 v[24:27], v[206:209], v[174:177], v[24:27]
	v_mfma_f32_16x16x32_bf16 v[16:19], v[198:201], v[182:185], v[16:19]
	v_mfma_f32_16x16x32_bf16 v[8:11], v[206:209], v[182:185], v[8:11]
	v_mfma_f32_16x16x32_bf16 v[4:7], v[198:201], v[190:193], v[4:7]
	v_mfma_f32_16x16x32_bf16 v[0:3], v[206:209], v[190:193], v[0:3]
	v_mfma_f32_16x16x32_bf16 v[48:51], v[202:205], v[170:173], v[48:51]
	v_mfma_f32_16x16x32_bf16 v[40:43], v[210:213], v[170:173], v[40:43]
	v_mfma_f32_16x16x32_bf16 v[32:35], v[202:205], v[178:181], v[32:35]
	v_mfma_f32_16x16x32_bf16 v[24:27], v[210:213], v[178:181], v[24:27]
	v_mfma_f32_16x16x32_bf16 v[16:19], v[202:205], v[186:189], v[16:19]
	v_mfma_f32_16x16x32_bf16 v[8:11], v[210:213], v[186:189], v[8:11]
	v_mfma_f32_16x16x32_bf16 v[4:7], v[202:205], v[194:197], v[4:7]
	v_mfma_f32_16x16x32_bf16 v[0:3], v[210:213], v[194:197], v[0:3]
	s_add_i32 s47, s47, 2
	s_add_u32 s16, s16, 0x100
	s_addc_u32 s17, s17, 0
	s_add_u32 s45, s45, 0x100
	s_addc_u32 s46, s46, 0
	s_cmpk_gt_u32 s47, 0x55
	s_barrier
	s_setprio 0
	s_cbranch_scc0 .LBB0_1424
	s_waitcnt lgkmcnt(0)
	v_lshl_or_b32 v144, s44, 8, v158
	v_lshl_add_u32 v154, s43, 8, v156
	v_ashrrev_i32_e32 v145, 31, v144
	v_lshlrev_b64 v[144:145], 2, v[144:145]
	v_ashrrev_i32_e32 v155, 31, v154
	v_lshl_add_u64 v[146:147], s[54:55], 0, v[144:145]
	v_lshlrev_b64 v[148:149], 13, v[154:155]
	v_or_b32_e32 v174, 16, v154
	v_lshl_add_u64 v[170:171], v[146:147], 0, v[148:149]
	v_ashrrev_i32_e32 v175, 31, v174
	global_load_dwordx4 v[150:153], v[170:171], off offset:16
	global_load_dwordx4 v[162:165], v[170:171], off
	global_load_dwordx4 v[166:169], v[170:171], off offset:528
	s_nop 0
	global_load_dwordx4 v[170:173], v[170:171], off offset:512
	v_lshlrev_b64 v[222:223], 13, v[174:175]
	v_or_b32_e32 v190, 32, v154
	v_lshl_add_u64 v[186:187], v[146:147], 0, v[222:223]
	v_ashrrev_i32_e32 v191, 31, v190
	global_load_dwordx4 v[174:177], v[186:187], off offset:16
	global_load_dwordx4 v[178:181], v[186:187], off
	global_load_dwordx4 v[182:185], v[186:187], off offset:528
	s_nop 0
	global_load_dwordx4 v[186:189], v[186:187], off offset:512
	v_lshlrev_b64 v[224:225], 13, v[190:191]
	v_or_b32_e32 v154, 48, v154
	v_lshl_add_u64 v[202:203], v[146:147], 0, v[224:225]
	v_ashrrev_i32_e32 v155, 31, v154
	global_load_dwordx4 v[190:193], v[202:203], off offset:16
	global_load_dwordx4 v[194:197], v[202:203], off
	global_load_dwordx4 v[198:201], v[202:203], off offset:528
	s_nop 0
	global_load_dwordx4 v[202:205], v[202:203], off offset:512
	v_lshlrev_b64 v[154:155], 13, v[154:155]
	v_lshl_add_u64 v[218:219], v[146:147], 0, v[154:155]
	global_load_dwordx4 v[206:209], v[218:219], off offset:16
	global_load_dwordx4 v[210:213], v[218:219], off
	global_load_dwordx4 v[214:217], v[218:219], off offset:528
	s_nop 0
	global_load_dwordx4 v[218:221], v[218:219], off offset:512
	s_and_b64 vcc, exec, s[0:1]
	s_mov_b32 s44, s41
	s_mov_b32 s43, s42
	s_mov_b64 s[18:19], s[4:5]
	s_mov_b64 s[16:17], s[2:3]
	s_waitcnt vmcnt(0)
; #define PG8_WAIT_V(n) asm volatile("s_waitcnt vmcnt(" #n ")" ::: "memory")
; #define PG8_BAR __builtin_amdgcn_s_barrier()
;   DI void operator()(const f32x4 (&acc)[2][2][4][2], const Unit& u, int wr, int wc, int fr, int fq) const {
;     ...
;       for (int m = 0; m < 4; ++m) {
;         const int row = row0 + ai * HALF + m * 16;
;         const size_t off = (size_t)row * 2048 + col0;
;         float ss = 0.f;
; #pragma unroll
;         for (int bj = 0; bj < 2; ++bj) {
;           const f32x4 v0 = acc[ai][bj][m][0] + bv[m][bj][0], v1 = acc[ai][bj][m][1] + bv[m][bj][1];
;           *(f32x4*)(C + off + bj * HALF) = v0; *(f32x4*)(C + off + bj * HALF + 4) = v1;
; template <class Epi, class Sched = StaticOrder>
; DI void gemm_phase(LAS unsigned char* lds, const Gemm g, const Sched& S, const Epi& E) {
;     ...
;     E(acc, cur, wr, wc, fr, fq);
;     if (!has_next) break;
; #pragma unroll
;     for (int a = 0; a < 2; ++a)
; #pragma unroll
;       for (int b = 0; b < 2; ++b)
; #pragma unroll
;         for (int m = 0; m < 4; ++m)
; #pragma unroll
;           for (int n = 0; n < 2; ++n) acc[a][b][m][n] = (f32x4){0.f, 0.f, 0.f, 0.f};
;     cur = nxt; cA = nA; cB = nB; ++ui;
;   }
;   PG8_WAIT_V(0);
;   if (wr == 0) PG8_BAR;
;   PG8_BAR;
	v_pk_add_f32 v[120:121], v[120:121], v[150:151]
	v_lshl_add_u64 v[150:151], s[54:55], 0, v[148:149]
	v_pk_add_f32 v[126:127], v[126:127], v[164:165]
	v_pk_add_f32 v[124:125], v[124:125], v[162:163]
	v_lshl_add_u64 v[150:151], v[150:151], 0, v[144:145]
	v_pk_add_f32 v[110:111], v[110:111], v[172:173]
	v_pk_add_f32 v[108:109], v[108:109], v[170:171]
	v_pk_add_f32 v[122:123], v[122:123], v[152:153]
	global_store_dwordx4 v[150:151], v[124:127], off
	global_store_dwordx4 v[150:151], v[120:123], off offset:16
	v_pk_add_f32 v[102:103], v[102:103], v[168:169]
	v_pk_add_f32 v[100:101], v[100:101], v[166:167]
	global_store_dwordx4 v[150:151], v[108:111], off offset:512
	global_store_dwordx4 v[150:151], v[100:103], off offset:528
	v_pk_add_f32 v[94:95], v[94:95], v[188:189]
	v_pk_add_f32 v[108:109], v[112:113], v[174:175]
	v_lshl_add_u64 v[112:113], s[54:55], 0, v[222:223]
	v_pk_add_f32 v[102:103], v[118:119], v[180:181]
	v_pk_add_f32 v[100:101], v[116:117], v[178:179]
	v_lshl_add_u64 v[112:113], v[112:113], 0, v[144:145]
	v_pk_add_f32 v[92:93], v[92:93], v[186:187]
	v_pk_add_f32 v[110:111], v[114:115], v[176:177]
	global_store_dwordx4 v[112:113], v[100:103], off
	global_store_dwordx4 v[112:113], v[108:111], off offset:16
	v_pk_add_f32 v[86:87], v[86:87], v[184:185]
	v_pk_add_f32 v[84:85], v[84:85], v[182:183]
	global_store_dwordx4 v[112:113], v[92:95], off offset:512
	global_store_dwordx4 v[112:113], v[84:87], off offset:528
	v_pk_add_f32 v[78:79], v[78:79], v[204:205]
	v_pk_add_f32 v[92:93], v[96:97], v[190:191]
	v_lshl_add_u64 v[96:97], s[54:55], 0, v[224:225]
	v_pk_add_f32 v[86:87], v[106:107], v[196:197]
	v_pk_add_f32 v[84:85], v[104:105], v[194:195]
	v_lshl_add_u64 v[96:97], v[96:97], 0, v[144:145]
	v_pk_add_f32 v[76:77], v[76:77], v[202:203]
	v_pk_add_f32 v[94:95], v[98:99], v[192:193]
	global_store_dwordx4 v[96:97], v[84:87], off
	global_store_dwordx4 v[96:97], v[92:95], off offset:16
	v_pk_add_f32 v[74:75], v[74:75], v[200:201]
	v_pk_add_f32 v[72:73], v[72:73], v[198:199]
	global_store_dwordx4 v[96:97], v[76:79], off offset:512
	global_store_dwordx4 v[96:97], v[72:75], off offset:528
	v_pk_add_f32 v[70:71], v[70:71], v[220:221]
	v_pk_add_f32 v[76:77], v[80:81], v[206:207]
	v_lshl_add_u64 v[80:81], s[54:55], 0, v[154:155]
	v_pk_add_f32 v[74:75], v[90:91], v[212:213]
	v_pk_add_f32 v[72:73], v[88:89], v[210:211]
	v_lshl_add_u64 v[80:81], v[80:81], 0, v[144:145]
	v_pk_add_f32 v[68:69], v[68:69], v[218:219]
	v_pk_add_f32 v[64:65], v[64:65], v[214:215]
	v_lshl_add_u64 v[154:155], v[148:149], 0, s[10:11]
	v_pk_add_f32 v[78:79], v[82:83], v[208:209]
	global_store_dwordx4 v[80:81], v[72:75], off
	global_store_dwordx4 v[80:81], v[76:79], off offset:16
	v_pk_add_f32 v[66:67], v[66:67], v[216:217]
	global_store_dwordx4 v[80:81], v[68:71], off offset:512
	global_store_dwordx4 v[80:81], v[64:67], off offset:528
	v_lshl_add_u64 v[152:153], v[148:149], 0, s[12:13]
	v_lshl_add_u64 v[150:151], v[148:149], 0, s[14:15]
	v_lshl_add_u64 v[64:65], v[146:147], 0, v[154:155]
	global_load_dwordx4 v[108:111], v[64:65], off offset:16
	global_load_dwordx4 v[120:123], v[64:65], off
	global_load_dwordx4 v[92:95], v[64:65], off offset:528
	global_load_dwordx4 v[100:103], v[64:65], off offset:512
	v_lshl_add_u64 v[64:65], v[146:147], 0, v[152:153]
	global_load_dwordx4 v[88:91], v[64:65], off offset:16
	global_load_dwordx4 v[96:99], v[64:65], off
	global_load_dwordx4 v[76:79], v[64:65], off offset:528
	global_load_dwordx4 v[84:87], v[64:65], off offset:512
	v_lshl_add_u64 v[68:69], v[146:147], 0, v[150:151]
	global_load_dwordx4 v[72:75], v[68:69], off offset:16
	global_load_dwordx4 v[80:83], v[68:69], off
	global_load_dwordx4 v[64:67], v[68:69], off offset:528
	s_nop 0
	global_load_dwordx4 v[68:71], v[68:69], off offset:512
	v_lshl_add_u64 v[148:149], v[148:149], 0, s[6:7]
	v_lshl_add_u64 v[112:113], v[146:147], 0, v[148:149]
	global_load_dwordx4 v[116:119], v[112:113], off offset:16
	global_load_dwordx4 v[124:127], v[112:113], off
	global_load_dwordx4 v[104:107], v[112:113], off offset:528
	s_nop 0
	global_load_dwordx4 v[112:115], v[112:113], off offset:512
	s_waitcnt vmcnt(0)
	v_pk_add_f32 v[56:57], v[56:57], v[108:109]
	v_lshl_add_u64 v[108:109], s[54:55], 0, v[154:155]
	v_pk_add_f32 v[62:63], v[62:63], v[122:123]
	v_pk_add_f32 v[60:61], v[60:61], v[120:121]
	v_lshl_add_u64 v[108:109], v[108:109], 0, v[144:145]
	v_pk_add_f32 v[50:51], v[50:51], v[102:103]
	v_pk_add_f32 v[48:49], v[48:49], v[100:101]
	v_pk_add_f32 v[58:59], v[58:59], v[110:111]
	global_store_dwordx4 v[108:109], v[60:63], off
	global_store_dwordx4 v[108:109], v[56:59], off offset:16
	v_pk_add_f32 v[42:43], v[42:43], v[94:95]
	v_pk_add_f32 v[40:41], v[40:41], v[92:93]
	global_store_dwordx4 v[108:109], v[48:51], off offset:512
	global_store_dwordx4 v[108:109], v[40:43], off offset:528
	v_pk_add_f32 v[34:35], v[34:35], v[86:87]
	v_lshl_add_u64 v[48:49], s[54:55], 0, v[152:153]
	v_pk_add_f32 v[42:43], v[54:55], v[98:99]
	v_pk_add_f32 v[40:41], v[52:53], v[96:97]
	v_lshl_add_u64 v[48:49], v[48:49], 0, v[144:145]
	v_pk_add_f32 v[32:33], v[32:33], v[84:85]
	v_pk_add_f32 v[46:47], v[46:47], v[90:91]
	v_pk_add_f32 v[44:45], v[44:45], v[88:89]
	global_store_dwordx4 v[48:49], v[40:43], off
	global_store_dwordx4 v[48:49], v[44:47], off offset:16
	v_pk_add_f32 v[26:27], v[26:27], v[78:79]
	v_pk_add_f32 v[24:25], v[24:25], v[76:77]
	global_store_dwordx4 v[48:49], v[32:35], off offset:512
	global_store_dwordx4 v[48:49], v[24:27], off offset:528
	v_pk_add_f32 v[18:19], v[18:19], v[70:71]
	v_lshl_add_u64 v[32:33], s[54:55], 0, v[150:151]
	v_pk_add_f32 v[26:27], v[38:39], v[82:83]
	v_pk_add_f32 v[24:25], v[36:37], v[80:81]
	v_lshl_add_u64 v[32:33], v[32:33], 0, v[144:145]
	v_pk_add_f32 v[16:17], v[16:17], v[68:69]
	v_pk_add_f32 v[30:31], v[30:31], v[74:75]
	v_pk_add_f32 v[28:29], v[28:29], v[72:73]
	global_store_dwordx4 v[32:33], v[24:27], off
	global_store_dwordx4 v[32:33], v[28:31], off offset:16
	v_pk_add_f32 v[10:11], v[10:11], v[66:67]
	v_pk_add_f32 v[8:9], v[8:9], v[64:65]
	global_store_dwordx4 v[32:33], v[16:19], off offset:512
	global_store_dwordx4 v[32:33], v[8:11], off offset:528
	v_pk_add_f32 v[6:7], v[6:7], v[114:115]
	v_lshl_add_u64 v[16:17], s[54:55], 0, v[148:149]
	v_pk_add_f32 v[10:11], v[22:23], v[126:127]
	v_pk_add_f32 v[8:9], v[20:21], v[124:125]
	v_lshl_add_u64 v[16:17], v[16:17], 0, v[144:145]
	v_pk_add_f32 v[4:5], v[4:5], v[112:113]
	v_pk_add_f32 v[14:15], v[14:15], v[118:119]
	v_pk_add_f32 v[12:13], v[12:13], v[116:117]
	global_store_dwordx4 v[16:17], v[8:11], off
	global_store_dwordx4 v[16:17], v[12:15], off offset:16
	v_pk_add_f32 v[2:3], v[2:3], v[106:107]
	v_pk_add_f32 v[0:1], v[0:1], v[104:105]
	global_store_dwordx4 v[16:17], v[4:7], off offset:512
	global_store_dwordx4 v[16:17], v[0:3], off offset:528
	s_cbranch_vccz .LBB0_1417
	s_waitcnt vmcnt(0)
	s_cmpk_gt_u32 s23, 0xff
	s_cbranch_scc1 .LBB0_1428
	s_barrier
